# GEMM: one static s_setprio 1 for waves 4-7 at phase entry, all per-segment setprio flips in the K-loops deleted, setprio 0 at phase exit
# speedup vs baseline: 1.0014x; 1.0014x over previous
; #define PG8_WAIT_V(n) asm volatile("s_waitcnt vmcnt(" #n ")" ::: "memory")
; #define PG8_BAR __builtin_amdgcn_s_barrier()
; template <class Epi, class Sched, bool HM = false>
; __device__ __forceinline__ void gemm_phase(PG8_LAS unsigned char* lds, const Gemm g, const Sched& S, const Epi& E) {
;     ...
;     PG8_WAIT_V(0);
;     PG8_BAR;
.LBB0_235:
	s_waitcnt vmcnt(0)
	s_setprio 0
	v_readlane_b32 s30, v252, 46
	v_readlane_b32 s28, v252, 50
	v_readlane_b32 s36, v255, 21
	v_readlane_b32 s88, v255, 23
	v_readlane_b32 s58, v255, 25
	v_readlane_b32 s31, v252, 47
	v_readlane_b32 s51, v252, 48
	v_readlane_b32 s52, v252, 49
	v_readlane_b32 s57, v255, 8
	v_readlane_b32 s29, v252, 51
	v_readlane_b32 s83, v255, 7
	v_readlane_b32 s37, v255, 22
	v_readlane_b32 s89, v255, 24
	v_readlane_b32 s59, v255, 26
	s_barrier

; #define PG8_STAGE(bufoff, gbase, voff) do { _Pragma("unroll") for (int _i = 0; _i < 2; ++_i) glds16_s((voff)[_i], (const void*)(gbase), ldsbase + (unsigned)((bufoff) + _i * 8192) + ldsw); } while (0)
; template <class Epi, class Sched, bool HM = false>
; __device__ __forceinline__ void gemm_phase(PG8_LAS unsigned char* lds, const Gemm g, const Sched& S, const Epi& E) {
;     ...
;     const int tid = tid_, wid = __builtin_amdgcn_readfirstlane(tid >> 6), lane = tid & 63, wr = wid >> 2, wc = wid & 3, fr = lane & 15, fq = lane >> 4;
;     const int K = g.K, nt = K / BK;
;     unsigned voffA[2], voffB[2];
; #pragma unroll
;     for (int i = 0; i < 2; ++i) { int R, C; stage_rc(tid * 16 + i * 8192, R, C); const int Rb = Epi::PERM ? ((R & ~31) + perm32(R & 31)) : R;
;         voffA[i] = (unsigned)(R * g.lda + C) * 2u; voffB[i] = (unsigned)(Rb * g.ldb + C) * 2u; }
;     const unsigned voffX = (unsigned)((4 * (wid & 3) + (lane >> 4)) * g.lda + 8 * (lane & 15)) * 2u;
;     const size_t kstep = (size_t)(BK * 2);
;     const size_t hstepA = (size_t)HALF * g.lda * 2, hstepB = (size_t)HALF * g.ldb * 2;
;     const size_t tstepA = (size_t)(HM ? HALF : g.pms) * g.lda * 2, tstepB = 2 * hstepB, xstep = 2 * hstepA; const bool hasx = g.pms != BM;
;     const unsigned ldsw = (unsigned)wid * 1024u, ldsx = (unsigned)(wid & 3) * 1024u;
;     const unsigned ldsbase = (unsigned)__builtin_amdgcn_readfirstlane((int)(unsigned)(__UINTPTR_TYPE__)lds);
;     const int aoff = lds_byte(wr * 64 + fr, fq * 8), boff = lds_byte(wc * 32 + fr, fq * 8);
;     const int xoff = XOFF + fr * 256 + fq * 16;
;     ...
;     Unit cur, nxt; int ui = 0;
;     if (!S.next(0, cur)) return;
;     f32x4 acc[2][2][4][2]; f32x4 accx[2];
; #pragma unroll
;     for (int a = 0; a < 2; ++a)
; #pragma unroll
;         for (int b = 0; b < 2; ++b)
; #pragma unroll
;             for (int m = 0; m < 4; ++m)
; #pragma unroll
;                 for (int n = 0; n < 2; ++n) acc[a][b][m][n] = (f32x4){0.f, 0.f, 0.f, 0.f};
;     accx[0] = (f32x4){0.f, 0.f, 0.f, 0.f}; accx[1] = accx[0];
;     bf16x8 At[4][2], B0[2][2], B1[2][2], Ax[2];
;     const char* cA = PG8_APTR(cur); const char* cB = PG8_BPTR(cur);
;     S.a_ready(cur);
;     PG8_STAGE(PG8_SB(0, 0), cB, voffB); PG8_STAGE(PG8_SB(0, 1), cB + hstepB, voffB); PG8_STAGE(PG8_SA(0, 0), cA, voffA); PG8_STAGEX(0, cA + xstep); PG8_STAGE(PG8_SA(0, 1), cA + hstepA, voffA);
;     if (wr == 1) PG8_BAR;
.LBB0_237:
	s_mov_b64 s[0:1], s[30:31]
	s_mov_b64 s[4:5], s[30:31]
	s_mov_b64 s[8:9], s[30:31]
	s_waitcnt vmcnt(0)
	v_mov_b32_e32 v4, v0
	s_andn2_b64 vcc, exec, s[96:97]
	v_readfirstlane_b32 s20, v4
	s_cbranch_vccnz .LBB0_236
	v_bfe_i32 v7, v4, 27, 1
	v_lshlrev_b32_e32 v5, 4, v4
	v_lshrrev_b32_e32 v7, 22, v7
	v_add_u32_e32 v7, v5, v7
	v_and_b32_e32 v7, 0xfffffc00, v7
	v_sub_u32_e32 v7, v5, v7
	v_ashrrev_i32_e32 v6, 31, v4
	v_lshrrev_b32_e32 v8, 4, v7
	v_lshrrev_b32_e32 v6, 26, v6
	v_bitop3_b32 v7, v8, v7, 32 bitop3:0x6c
	v_add_u32_e32 v6, v4, v6
	v_ashrrev_i32_e32 v9, 31, v7
	v_ashrrev_i32_e32 v6, 6, v6
	v_lshrrev_b32_e32 v9, 26, v9
	v_lshlrev_b32_e32 v8, 3, v6
	v_add_u32_e32 v9, v7, v9
	v_and_b32_e32 v8, -16, v8
	v_ashrrev_i32_e32 v10, 6, v9
	v_and_b32_e32 v9, 0xc0, v9
	s_add_u32 s13, s0, 0x1a1e4000
	v_add_u32_e32 v8, v10, v8
	v_sub_u32_e32 v7, v7, v9
	s_addc_u32 s14, s1, 0
	v_lshlrev_b32_e32 v6, 5, v6
	v_ashrrev_i16_sdwa v7, v1, sext(v7) dst_sel:DWORD dst_unused:UNUSED_PAD src0_sel:DWORD src1_sel:BYTE_0
	v_lshlrev_b32_e32 v9, 1, v8
	v_lshrrev_b32_e32 v11, 2, v8
	v_and_b32_e32 v10, 3, v10
	s_mov_b32 s1, 0x3fffe0
	v_and_b32_e32 v6, 32, v6
	v_bfe_i32 v7, v7, 0, 16
	v_and_b32_e32 v9, 24, v9
	v_and_b32_e32 v11, 4, v11
	v_and_or_b32 v10, v8, s1, v10
	v_or3_b32 v9, v10, v11, v9
	v_add_lshl_u32 v6, v6, v7, 1
	v_add_u32_e32 v5, 0x2000, v5
	v_lshl_add_u32 v225, v8, 12, v6
	v_lshl_add_u32 v226, v9, 10, v6
	v_ashrrev_i32_e32 v6, 31, v5
	v_lshrrev_b32_e32 v6, 22, v6
	v_add_u32_e32 v6, v5, v6
	v_ashrrev_i32_e32 v6, 10, v6
	v_mul_i32_i24_e32 v7, 0x400, v6
	v_sub_u32_e32 v5, v5, v7
	v_lshrrev_b32_e32 v7, 4, v5
	v_bitop3_b32 v5, v7, v5, 32 bitop3:0x6c
	v_ashrrev_i32_e32 v8, 31, v5
	v_lshrrev_b32_e32 v8, 26, v8
	s_add_u32 s15, s4, 0x15aa0000
	v_lshlrev_b32_e32 v7, 3, v6
	v_add_u32_e32 v8, v5, v8
	s_addc_u32 s16, s5, 0
	s_ashr_i32 s0, s20, 6
	v_and_b32_e32 v7, -16, v7
	v_ashrrev_i32_e32 v9, 6, v8
	v_and_b32_e32 v8, 0xc0, v8
	s_and_b32 s21, s0, 3
	v_add_u32_e32 v7, v9, v7
	v_sub_u32_e32 v5, v5, v8
	v_and_b32_e32 v9, 3, v9
	v_lshlrev_b32_e32 v6, 5, v6
	v_ashrrev_i16_sdwa v5, v1, sext(v5) dst_sel:DWORD dst_unused:UNUSED_PAD src0_sel:DWORD src1_sel:BYTE_0
	v_lshlrev_b32_e32 v8, 1, v7
	v_lshrrev_b32_e32 v10, 2, v7
	v_and_or_b32 v9, v7, s1, v9
	s_ashr_i32 s22, s20, 8
	s_lshl_b32 s1, s21, 14
	s_lshl_b32 s0, s0, 10
	s_lshl_b32 s23, s21, 10
	v_readlane_b32 s4, v254, 34
	v_and_b32_e32 v6, 32, v6
	v_bfe_i32 v5, v5, 0, 16
	v_and_b32_e32 v8, 24, v8
	v_and_b32_e32 v10, 4, v10
	v_readlane_b32 s5, v254, 35
	s_add_u32 s4, s15, s4
	v_bfe_u32 v2, v4, 4, 2
	v_or3_b32 v8, v9, v10, v8
	v_add_lshl_u32 v5, v6, v5, 1
	v_and_b32_e32 v4, 15, v4
	s_addc_u32 s5, s16, s5
	s_add_i32 s17, s0, 0
	v_lshl_add_u32 v227, v7, 12, v5
	v_lshl_add_u32 v228, v8, 10, v5
	v_lshlrev_b32_e32 v5, 4, v4
	v_lshlrev_b32_e32 v6, 12, v2
	s_add_i32 s18, s17, 0x10000
	s_mov_b32 s0, m0
	s_mov_b32 m0, s18
	s_nop 0
	global_load_lds_dwordx4 v226, s[4:5]
	s_mov_b32 m0, s0
	v_or3_b32 v229, s1, v6, v5
	v_lshrrev_b32_e32 v232, 8, v229
	v_and_b32_e32 v232, 0xf0, v232
	v_xor_b32_e32 v229, v229, v232
	s_add_i32 s19, s17, 0x12000
	s_mov_b32 s0, m0
	s_mov_b32 m0, s19
	s_nop 0
	global_load_lds_dwordx4 v228, s[4:5]
	s_mov_b32 m0, s0
	v_readlane_b32 s1, v254, 23
	s_mul_i32 s0, s1, s10
	s_add_u32 s6, s13, s0
	s_mul_hi_i32 s0, s1, s10
	s_addc_u32 s7, s14, s0
	s_add_u32 s0, s4, 0x20000
	s_addc_u32 s1, s5, 0
	s_add_i32 s24, s17, 0x14000
	s_mov_b32 s25, m0
	s_mov_b32 m0, s24
	s_nop 0
	global_load_lds_dwordx4 v226, s[0:1]
	s_mov_b32 m0, s25
	s_add_i32 s25, s17, 0x16000
	s_mov_b32 s27, m0
	s_mov_b32 m0, s25
	s_nop 0
	global_load_lds_dwordx4 v228, s[0:1]
	s_mov_b32 m0, s27
	v_readlane_b32 s0, v254, 32
	v_readlane_b32 s1, v254, 33
	s_add_u32 s6, s6, s0
	s_addc_u32 s7, s7, s1
	s_mov_b32 s0, m0
	s_mov_b32 m0, s17
	s_nop 0
	global_load_lds_dwordx4 v225, s[6:7]
	s_mov_b32 m0, s0
	s_add_i32 s28, s17, 0x2000
	s_mov_b32 s0, m0
	s_mov_b32 m0, s28
	s_nop 0
	global_load_lds_dwordx4 v227, s[6:7]
	s_mov_b32 m0, s0
	s_add_u32 s0, s6, 0x100000
	s_addc_u32 s1, s7, 0
	s_add_i32 s29, s23, 0
	s_add_i32 s23, s29, 0x20400
	s_mov_b32 s27, m0
	s_mov_b32 m0, s23
	s_nop 0
	global_load_lds_dwordx4 v229, s[0:1]
	s_mov_b32 m0, s27
	s_add_u32 s0, s6, 0x80000
	s_addc_u32 s1, s7, 0
	s_add_i32 s30, s17, 0x4000
	s_mov_b32 s23, m0
	s_mov_b32 m0, s30
	s_nop 0
	global_load_lds_dwordx4 v225, s[0:1]
	s_mov_b32 m0, s23
	s_add_i32 s31, s17, 0x6000
	s_mov_b32 s23, m0
	s_mov_b32 m0, s31
	s_nop 0
	global_load_lds_dwordx4 v227, s[0:1]
	s_mov_b32 m0, s23
	s_cmp_eq_u32 s22, 1
	s_cselect_b64 s[0:1], -1, 0
	s_cmp_lg_u32 s22, 1
	s_cbranch_scc1 .LBB0_240
	s_setprio 1
	s_barrier

; #define PG8_STAGE(bufoff, gbase, voff) do { _Pragma("unroll") for (int _i = 0; _i < 2; ++_i) glds16_s((voff)[_i], (const void*)(gbase), ldsbase + (unsigned)((bufoff) + _i * 8192) + ldsw); } while (0)
; #define PG8_LDA(dst, b, h) do { _Pragma("unroll") for (int m = 0; m < 4; ++m) _Pragma("unroll") for (int k = 0; k < 2; ++k) dst[m][k] = *(const PG8_LAS bf16x8*)(lds + PG8_SA(b, h) + aoff + m * 2048 + k * 1024); } while (0)
; #define PG8_MMA(ai, bj, At, Bt) do { __builtin_amdgcn_s_setprio(1); _Pragma("unroll") for (int m = 0; m < 4; ++m) _Pragma("unroll") for (int n = 0; n < 2; ++n) _Pragma("unroll") for (int k = 0; k < 2; ++k) \
;         acc[ai][bj][m][n] = __builtin_amdgcn_mfma_f32_16x16x32_bf16(Bt[n][k], At[m][k], acc[ai][bj][m][n], 0, 0, 0); __builtin_amdgcn_s_setprio(0); } while (0)
; #define PG8_WAIT_V(n) asm volatile("s_waitcnt vmcnt(" #n ")" ::: "memory")
; #define PG8_WAIT_L(n) asm volatile("s_waitcnt lgkmcnt(" #n ")" ::: "memory")
; #define PG8_BAR __builtin_amdgcn_s_barrier()
; #define PG8_SCHED __builtin_amdgcn_sched_barrier(0)
; template <class Epi, class Sched, bool HM = false>
; __device__ __forceinline__ void gemm_phase(PG8_LAS unsigned char* lds, const Gemm g, const Sched& S, const Epi& E) {
;     ...
;             if (!HM) PG8_LDA(At, 1, 1); PG8_STAGE(PG8_SB(1, 0), b3, voffB); PG8_STAGE(PG8_SB(1, 1), b3 + hstepB, voffB); PG8_STAGE(PG8_SA(1, 0), a3, voffA);
;             PG8_WAIT_V(8); PG8_WAIT_L(0); PG8_BAR; if (!HM) { PG8_MMA(1, 0, At, B0); PG8_MMA(1, 1, At, B1); } PG8_BAR; PG8_SCHED;
;         }
.LBB0_254:
.LBB0_255:
	s_barrier
	ds_read_b128 v[182:185], v235 offset:49152
	ds_read_b128 v[186:189], v235 offset:50176
	ds_read_b128 v[190:193], v235 offset:51200
	ds_read_b128 v[194:197], v235 offset:52224
	ds_read_b128 v[198:201], v235 offset:53248
	ds_read_b128 v[202:205], v235 offset:54272
	ds_read_b128 v[206:209], v235 offset:55296
	ds_read_b128 v[210:213], v235 offset:56320
	s_mov_b32 s8, m0
	s_mov_b32 m0, s36
	s_nop 0
	global_load_lds_dwordx4 v226, s[6:7]
	s_mov_b32 m0, s8
	s_nop 0
	s_mov_b32 s8, m0
	s_mov_b32 m0, s37
	s_nop 0
	global_load_lds_dwordx4 v228, s[6:7]
	s_mov_b32 m0, s8
	s_add_u32 s6, s6, 0x20000
	s_addc_u32 s7, s7, 0
	s_mov_b32 s8, m0
	s_mov_b32 m0, s57
	s_nop 0
	global_load_lds_dwordx4 v226, s[6:7]
	s_mov_b32 m0, s8
	s_nop 0
	s_mov_b32 s8, m0
	s_mov_b32 m0, s58
	s_nop 0
	global_load_lds_dwordx4 v228, s[6:7]
	s_mov_b32 m0, s8
	s_mov_b32 s6, m0
	s_mov_b32 m0, s51
	s_nop 0
	global_load_lds_dwordx4 v225, s[4:5]
	s_mov_b32 m0, s6
	s_nop 0
	s_mov_b32 s6, m0
	s_mov_b32 m0, s52
	s_nop 0
	global_load_lds_dwordx4 v227, s[4:5]
	s_mov_b32 m0, s6
	s_waitcnt vmcnt(8)
	s_waitcnt lgkmcnt(0)
	s_barrier
	s_waitcnt lgkmcnt(7)
	v_mfma_f32_16x16x32_bf16 v[82:85], v[166:169], v[182:185], v[82:85]
	v_mfma_f32_16x16x32_bf16 v[78:81], v[174:177], v[182:185], v[78:81]
	s_waitcnt lgkmcnt(5)
	v_mfma_f32_16x16x32_bf16 v[74:77], v[166:169], v[190:193], v[74:77]
	v_mfma_f32_16x16x32_bf16 v[66:69], v[174:177], v[190:193], v[66:69]
	s_waitcnt lgkmcnt(3)
	v_mfma_f32_16x16x32_bf16 v[58:61], v[166:169], v[198:201], v[58:61]
	v_mfma_f32_16x16x32_bf16 v[50:53], v[174:177], v[198:201], v[50:53]
	s_waitcnt lgkmcnt(1)
	v_mfma_f32_16x16x32_bf16 v[42:45], v[166:169], v[206:209], v[42:45]
	v_mfma_f32_16x16x32_bf16 v[34:37], v[174:177], v[206:209], v[34:37]
	v_mfma_f32_16x16x32_bf16 v[82:85], v[170:173], v[186:189], v[82:85]
	v_mfma_f32_16x16x32_bf16 v[78:81], v[178:181], v[186:189], v[78:81]
	v_mfma_f32_16x16x32_bf16 v[74:77], v[170:173], v[194:197], v[74:77]
	v_mfma_f32_16x16x32_bf16 v[66:69], v[178:181], v[194:197], v[66:69]
	v_mfma_f32_16x16x32_bf16 v[58:61], v[170:173], v[202:205], v[58:61]
	v_mfma_f32_16x16x32_bf16 v[50:53], v[178:181], v[202:205], v[50:53]
	s_waitcnt lgkmcnt(0)
	v_mfma_f32_16x16x32_bf16 v[42:45], v[170:173], v[210:213], v[42:45]
	v_mfma_f32_16x16x32_bf16 v[34:37], v[178:181], v[210:213], v[34:37]
	v_mfma_f32_16x16x32_bf16 v[70:73], v[150:153], v[182:185], v[70:73]
	v_mfma_f32_16x16x32_bf16 v[62:65], v[158:161], v[182:185], v[62:65]
	v_mfma_f32_16x16x32_bf16 v[54:57], v[150:153], v[190:193], v[54:57]
	v_mfma_f32_16x16x32_bf16 v[46:49], v[158:161], v[190:193], v[46:49]
	v_mfma_f32_16x16x32_bf16 v[38:41], v[150:153], v[198:201], v[38:41]
	v_mfma_f32_16x16x32_bf16 v[30:33], v[158:161], v[198:201], v[30:33]
	v_mfma_f32_16x16x32_bf16 v[26:29], v[150:153], v[206:209], v[26:29]
	v_mfma_f32_16x16x32_bf16 v[22:25], v[158:161], v[206:209], v[22:25]
	v_mfma_f32_16x16x32_bf16 v[70:73], v[154:157], v[186:189], v[70:73]
	v_mfma_f32_16x16x32_bf16 v[62:65], v[162:165], v[186:189], v[62:65]
	v_mfma_f32_16x16x32_bf16 v[54:57], v[154:157], v[194:197], v[54:57]
	v_mfma_f32_16x16x32_bf16 v[46:49], v[162:165], v[194:197], v[46:49]
	v_mfma_f32_16x16x32_bf16 v[38:41], v[154:157], v[202:205], v[38:41]
	v_mfma_f32_16x16x32_bf16 v[30:33], v[162:165], v[202:205], v[30:33]
	v_mfma_f32_16x16x32_bf16 v[26:29], v[154:157], v[210:213], v[26:29]
	v_mfma_f32_16x16x32_bf16 v[22:25], v[162:165], v[210:213], v[22:25]
	s_barrier
	s_add_i32 s23, s23, 2
	s_addk_i32 s22, 0x1000
	s_add_u32 s95, s95, 0x100
	s_addc_u32 s38, s38, 0
	s_add_u32 s27, s27, 0x100
	s_addc_u32 s39, s39, 0
	s_cmp_gt_u32 s23, 5
	s_cbranch_scc1 .LBB0_271

; #define PG8_STAGE(bufoff, gbase, voff) do { _Pragma("unroll") for (int _i = 0; _i < 2; ++_i) glds16_s((voff)[_i], (const void*)(gbase), ldsbase + (unsigned)((bufoff) + _i * 8192) + ldsw); } while (0)
; #define PG8_STAGEX(pb, gbase) glds16_s(voffX, (const void*)(gbase), ldsbase + (unsigned)(XOFF + (pb) * 4096) + ldsx)
; #define PG8_LDA(dst, b, h) do { _Pragma("unroll") for (int m = 0; m < 4; ++m) _Pragma("unroll") for (int k = 0; k < 2; ++k) dst[m][k] = *(const PG8_LAS bf16x8*)(lds + PG8_SA(b, h) + aoff + m * 2048 + k * 1024); } while (0)
; #define PG8_LDB(dst, b, h) do { _Pragma("unroll") for (int n = 0; n < 2; ++n) _Pragma("unroll") for (int k = 0; k < 2; ++k) dst[n][k] = *(const PG8_LAS bf16x8*)(lds + PG8_SB(b, h) + boff + n * 2048 + k * 1024); } while (0)
; #define PG8_LDX(pb, tp) do { _Pragma("unroll") for (int k = 0; k < 2; ++k) Ax[k] = *(const PG8_LAS bf16x8*)(lds + xoff + (pb) * 4096 + (tp) * 128 + k * 64); } while (0)
; #define PG8_MMA(ai, bj, At, Bt) do { __builtin_amdgcn_s_setprio(1); _Pragma("unroll") for (int m = 0; m < 4; ++m) _Pragma("unroll") for (int n = 0; n < 2; ++n) _Pragma("unroll") for (int k = 0; k < 2; ++k) \
;         acc[ai][bj][m][n] = __builtin_amdgcn_mfma_f32_16x16x32_bf16(Bt[n][k], At[m][k], acc[ai][bj][m][n], 0, 0, 0); __builtin_amdgcn_s_setprio(0); } while (0)
; #define PG8_WAIT_V(n) asm volatile("s_waitcnt vmcnt(" #n ")" ::: "memory")
; #define PG8_WAIT_L(n) asm volatile("s_waitcnt lgkmcnt(" #n ")" ::: "memory")
; #define PG8_BAR __builtin_amdgcn_s_barrier()
; #define PG8_SCHED __builtin_amdgcn_sched_barrier(0)
; template <class Epi, class Sched, bool HM = false>
; __device__ __forceinline__ void gemm_phase(PG8_LAS unsigned char* lds, const Gemm g, const Sched& S, const Epi& E) {
;     ...
;             PG8_LDB(B0, 0, 0); PG8_LDB(B1, 0, 1); PG8_SCHED; PG8_LDA(At, 0, 0); if (hasx) PG8_LDX(pb, 0); PG8_STAGE(PG8_SA(1, 1), a1 + hstepA, voffA); PG8_STAGEX(pb ^ 1, a2 + xstep);
;             PG8_WAIT_V(9); PG8_WAIT_L(0); PG8_BAR; PG8_MMA(0, 0, At, B0); PG8_MMA(0, 1, At, B1); if (hasx) PG8_MMAX(); PG8_BAR; PG8_SCHED;
.LBB0_258:
	s_add_u32 s34, s34, 0x80000
	s_addc_u32 s35, s35, 0
	s_mov_b32 s21, m0
	s_mov_b32 m0, s59
	s_nop 0
	global_load_lds_dwordx4 v225, s[34:35]
	s_mov_b32 m0, s21
	s_nop 0
	s_mov_b32 s21, m0
	s_mov_b32 m0, s83
	s_nop 0
	global_load_lds_dwordx4 v227, s[34:35]
	s_mov_b32 m0, s21
	s_add_u32 s34, s92, 0x100000
	s_addc_u32 s35, s93, 0
	s_xor_b32 s20, s20, 0x21400
	s_add_i32 s20, s29, s20
	s_mov_b32 s21, m0
	s_mov_b32 m0, s20
	s_nop 0
	global_load_lds_dwordx4 v229, s[34:35]
	s_mov_b32 m0, s21
	s_waitcnt vmcnt(9)
	s_waitcnt lgkmcnt(0)
	s_barrier
	s_waitcnt lgkmcnt(7)
	v_mfma_f32_16x16x32_bf16 v[146:149], v[166:169], v[206:209], v[146:149]
	v_mfma_f32_16x16x32_bf16 v[142:145], v[174:177], v[206:209], v[142:145]
	s_waitcnt lgkmcnt(5)
	v_mfma_f32_16x16x32_bf16 v[138:141], v[166:169], v[198:201], v[138:141]
	v_mfma_f32_16x16x32_bf16 v[130:133], v[174:177], v[198:201], v[130:133]
	s_waitcnt lgkmcnt(3)
	v_mfma_f32_16x16x32_bf16 v[122:125], v[166:169], v[190:193], v[122:125]
	v_mfma_f32_16x16x32_bf16 v[114:117], v[174:177], v[190:193], v[114:117]
	s_waitcnt lgkmcnt(1)
	v_mfma_f32_16x16x32_bf16 v[106:109], v[166:169], v[182:185], v[106:109]
	v_mfma_f32_16x16x32_bf16 v[98:101], v[174:177], v[182:185], v[98:101]
	v_mfma_f32_16x16x32_bf16 v[146:149], v[170:173], v[210:213], v[146:149]
	v_mfma_f32_16x16x32_bf16 v[142:145], v[178:181], v[210:213], v[142:145]
	v_mfma_f32_16x16x32_bf16 v[138:141], v[170:173], v[202:205], v[138:141]
	v_mfma_f32_16x16x32_bf16 v[130:133], v[178:181], v[202:205], v[130:133]
	v_mfma_f32_16x16x32_bf16 v[122:125], v[170:173], v[194:197], v[122:125]
	v_mfma_f32_16x16x32_bf16 v[114:117], v[178:181], v[194:197], v[114:117]
	s_waitcnt lgkmcnt(0)
	v_mfma_f32_16x16x32_bf16 v[106:109], v[170:173], v[186:189], v[106:109]
	v_mfma_f32_16x16x32_bf16 v[98:101], v[178:181], v[186:189], v[98:101]
	v_mfma_f32_16x16x32_bf16 v[134:137], v[150:153], v[206:209], v[134:137]
	v_mfma_f32_16x16x32_bf16 v[126:129], v[158:161], v[206:209], v[126:129]
	v_mfma_f32_16x16x32_bf16 v[118:121], v[150:153], v[198:201], v[118:121]
	v_mfma_f32_16x16x32_bf16 v[110:113], v[158:161], v[198:201], v[110:113]
	v_mfma_f32_16x16x32_bf16 v[102:105], v[150:153], v[190:193], v[102:105]
	v_mfma_f32_16x16x32_bf16 v[94:97], v[158:161], v[190:193], v[94:97]
	v_mfma_f32_16x16x32_bf16 v[90:93], v[150:153], v[182:185], v[90:93]
	v_mfma_f32_16x16x32_bf16 v[86:89], v[158:161], v[182:185], v[86:89]
	v_mfma_f32_16x16x32_bf16 v[134:137], v[154:157], v[210:213], v[134:137]
	v_mfma_f32_16x16x32_bf16 v[126:129], v[162:165], v[210:213], v[126:129]
	v_mfma_f32_16x16x32_bf16 v[118:121], v[154:157], v[202:205], v[118:121]
	v_mfma_f32_16x16x32_bf16 v[110:113], v[162:165], v[202:205], v[110:113]
	v_mfma_f32_16x16x32_bf16 v[102:105], v[154:157], v[194:197], v[102:105]
	v_mfma_f32_16x16x32_bf16 v[94:97], v[162:165], v[194:197], v[94:97]
	v_mfma_f32_16x16x32_bf16 v[90:93], v[154:157], v[186:189], v[90:93]
	v_mfma_f32_16x16x32_bf16 v[86:89], v[162:165], v[186:189], v[86:89]
	s_andn2_b64 s[44:45], exec, s[76:77]
	s_and_b64 vcc, exec, s[42:43]
	s_cbranch_vccnz .LBB0_264
	s_and_b64 vcc, exec, s[44:45]
	s_cbranch_vccnz .LBB0_261
	v_mfma_f32_16x16x32_bf16 v[18:21], v[174:177], v[6:9], v[18:21]
	v_mfma_f32_16x16x32_bf16 v[14:17], v[158:161], v[6:9], v[14:17]
	v_mfma_f32_16x16x32_bf16 v[18:21], v[178:181], v[10:13], v[18:21]
	v_mfma_f32_16x16x32_bf16 v[14:17], v[162:165], v[10:13], v[14:17]
	s_branch .LBB0_264

; #define PG8_STAGE(bufoff, gbase, voff) do { _Pragma("unroll") for (int _i = 0; _i < 2; ++_i) glds16_s((voff)[_i], (const void*)(gbase), ldsbase + (unsigned)((bufoff) + _i * 8192) + ldsw); } while (0)
; #define PG8_LDA(dst, b, h) do { _Pragma("unroll") for (int m = 0; m < 4; ++m) _Pragma("unroll") for (int k = 0; k < 2; ++k) dst[m][k] = *(const PG8_LAS bf16x8*)(lds + PG8_SA(b, h) + aoff + m * 2048 + k * 1024); } while (0)
; #define PG8_LDB(dst, b, h) do { _Pragma("unroll") for (int n = 0; n < 2; ++n) _Pragma("unroll") for (int k = 0; k < 2; ++k) dst[n][k] = *(const PG8_LAS bf16x8*)(lds + PG8_SB(b, h) + boff + n * 2048 + k * 1024); } while (0)
; #define PG8_LDX(pb, tp) do { _Pragma("unroll") for (int k = 0; k < 2; ++k) Ax[k] = *(const PG8_LAS bf16x8*)(lds + xoff + (pb) * 4096 + (tp) * 128 + k * 64); } while (0)
; #define PG8_MMA(ai, bj, At, Bt) do { __builtin_amdgcn_s_setprio(1); _Pragma("unroll") for (int m = 0; m < 4; ++m) _Pragma("unroll") for (int n = 0; n < 2; ++n) _Pragma("unroll") for (int k = 0; k < 2; ++k) \
;         acc[ai][bj][m][n] = __builtin_amdgcn_mfma_f32_16x16x32_bf16(Bt[n][k], At[m][k], acc[ai][bj][m][n], 0, 0, 0); __builtin_amdgcn_s_setprio(0); } while (0)
; #define PG8_WAIT_V(n) asm volatile("s_waitcnt vmcnt(" #n ")" ::: "memory")
; #define PG8_WAIT_L(n) asm volatile("s_waitcnt lgkmcnt(" #n ")" ::: "memory")
; #define PG8_BAR __builtin_amdgcn_s_barrier()
; #define PG8_SCHED __builtin_amdgcn_sched_barrier(0)
; template <class Epi, class Sched, bool HM = false>
; __device__ __forceinline__ void gemm_phase(PG8_LAS unsigned char* lds, const Gemm g, const Sched& S, const Epi& E) {
;     ...
;             PG8_WAIT_V(9); PG8_WAIT_L(0); PG8_BAR; PG8_MMA(0, 0, At, B0); PG8_MMA(0, 1, At, B1); if (hasx) PG8_MMAX(); PG8_BAR; PG8_SCHED;
;             if (!HM) PG8_LDA(At, 0, 1); PG8_STAGE(PG8_SB(0, 0), b2, voffB); PG8_STAGE(PG8_SB(0, 1), b2 + hstepB, voffB); PG8_STAGE(PG8_SA(0, 0), a2, voffA);
;             PG8_WAIT_V(9); PG8_WAIT_L(0); PG8_BAR; if (!HM) { PG8_MMA(1, 0, At, B0); PG8_MMA(1, 1, At, B1); } PG8_BAR; PG8_SCHED;
;             PG8_LDB(B0, 1, 0); PG8_LDB(B1, 1, 1); PG8_SCHED; PG8_LDA(At, 1, 0); if (hasx) PG8_LDX(pb, 1); PG8_STAGE(PG8_SA(0, 1), a2 + hstepA, voffA);
.LBB0_263:
.LBB0_264:
	s_barrier
	ds_read_b128 v[182:185], v235 offset:16384
	ds_read_b128 v[186:189], v235 offset:17408
	ds_read_b128 v[190:193], v235 offset:18432
	ds_read_b128 v[194:197], v235 offset:19456
	ds_read_b128 v[198:201], v235 offset:20480
	ds_read_b128 v[202:205], v235 offset:21504
	ds_read_b128 v[206:209], v235 offset:22528
	ds_read_b128 v[210:213], v235 offset:23552
	s_mov_b32 s20, m0
	s_mov_b32 m0, s18
	s_nop 0
	global_load_lds_dwordx4 v226, s[8:9]
	s_mov_b32 m0, s20
	s_nop 0
	s_mov_b32 s20, m0
	s_mov_b32 m0, s19
	s_nop 0
	global_load_lds_dwordx4 v228, s[8:9]
	s_mov_b32 m0, s20
	s_add_u32 s8, s8, 0x20000
	s_addc_u32 s9, s9, 0
	s_mov_b32 s20, m0
	s_mov_b32 m0, s24
	s_nop 0
	global_load_lds_dwordx4 v226, s[8:9]
	s_mov_b32 m0, s20
	s_nop 0
	s_mov_b32 s20, m0
	s_mov_b32 m0, s25
	s_nop 0
	global_load_lds_dwordx4 v228, s[8:9]
	s_mov_b32 m0, s20
	s_mov_b32 s8, m0
	s_mov_b32 m0, s17
	s_nop 0
	global_load_lds_dwordx4 v225, s[92:93]
	s_mov_b32 m0, s8
	s_nop 0
	s_mov_b32 s8, m0
	s_mov_b32 m0, s28
	s_nop 0
	global_load_lds_dwordx4 v227, s[92:93]
	s_mov_b32 m0, s8
	s_waitcnt vmcnt(9)
	s_waitcnt lgkmcnt(0)
	s_barrier
	s_waitcnt lgkmcnt(7)
	v_mfma_f32_16x16x32_bf16 v[82:85], v[166:169], v[182:185], v[82:85]
	v_mfma_f32_16x16x32_bf16 v[78:81], v[174:177], v[182:185], v[78:81]
	s_waitcnt lgkmcnt(5)
	v_mfma_f32_16x16x32_bf16 v[74:77], v[166:169], v[190:193], v[74:77]
	v_mfma_f32_16x16x32_bf16 v[66:69], v[174:177], v[190:193], v[66:69]
	s_waitcnt lgkmcnt(3)
	v_mfma_f32_16x16x32_bf16 v[58:61], v[166:169], v[198:201], v[58:61]
	v_mfma_f32_16x16x32_bf16 v[50:53], v[174:177], v[198:201], v[50:53]
	s_waitcnt lgkmcnt(1)
	v_mfma_f32_16x16x32_bf16 v[42:45], v[166:169], v[206:209], v[42:45]
	v_mfma_f32_16x16x32_bf16 v[34:37], v[174:177], v[206:209], v[34:37]
	v_mfma_f32_16x16x32_bf16 v[82:85], v[170:173], v[186:189], v[82:85]
	v_mfma_f32_16x16x32_bf16 v[78:81], v[178:181], v[186:189], v[78:81]
	v_mfma_f32_16x16x32_bf16 v[74:77], v[170:173], v[194:197], v[74:77]
	v_mfma_f32_16x16x32_bf16 v[66:69], v[178:181], v[194:197], v[66:69]
	v_mfma_f32_16x16x32_bf16 v[58:61], v[170:173], v[202:205], v[58:61]
	v_mfma_f32_16x16x32_bf16 v[50:53], v[178:181], v[202:205], v[50:53]
	s_waitcnt lgkmcnt(0)
	v_mfma_f32_16x16x32_bf16 v[42:45], v[170:173], v[210:213], v[42:45]
	v_mfma_f32_16x16x32_bf16 v[34:37], v[178:181], v[210:213], v[34:37]
	v_mfma_f32_16x16x32_bf16 v[70:73], v[150:153], v[182:185], v[70:73]
	v_mfma_f32_16x16x32_bf16 v[62:65], v[158:161], v[182:185], v[62:65]
	v_mfma_f32_16x16x32_bf16 v[54:57], v[150:153], v[190:193], v[54:57]
	v_mfma_f32_16x16x32_bf16 v[46:49], v[158:161], v[190:193], v[46:49]
	v_mfma_f32_16x16x32_bf16 v[38:41], v[150:153], v[198:201], v[38:41]
	v_mfma_f32_16x16x32_bf16 v[30:33], v[158:161], v[198:201], v[30:33]
	v_mfma_f32_16x16x32_bf16 v[26:29], v[150:153], v[206:209], v[26:29]
	v_mfma_f32_16x16x32_bf16 v[22:25], v[158:161], v[206:209], v[22:25]
	v_mfma_f32_16x16x32_bf16 v[70:73], v[154:157], v[186:189], v[70:73]
	v_mfma_f32_16x16x32_bf16 v[62:65], v[162:165], v[186:189], v[62:65]
	v_mfma_f32_16x16x32_bf16 v[54:57], v[154:157], v[194:197], v[54:57]
	v_mfma_f32_16x16x32_bf16 v[46:49], v[162:165], v[194:197], v[46:49]
	v_mfma_f32_16x16x32_bf16 v[38:41], v[154:157], v[202:205], v[38:41]
	v_mfma_f32_16x16x32_bf16 v[30:33], v[162:165], v[202:205], v[30:33]
	v_mfma_f32_16x16x32_bf16 v[26:29], v[154:157], v[210:213], v[26:29]
	v_mfma_f32_16x16x32_bf16 v[22:25], v[162:165], v[210:213], v[22:25]
	s_barrier
	v_add_u32_e32 v4, 0x18000, v234
	ds_read_b128 v[166:169], v4
	ds_read_b128 v[170:173], v4 offset:1024
	ds_read_b128 v[174:177], v4 offset:2048
	ds_read_b128 v[178:181], v4 offset:3072
	v_add_u32_e32 v4, 0x1c000, v234
	ds_read_b128 v[150:153], v4
	ds_read_b128 v[154:157], v4 offset:1024
	ds_read_b128 v[158:161], v4 offset:2048
	ds_read_b128 v[162:165], v4 offset:3072
	ds_read_b128 v[206:209], v235 offset:32768
	ds_read_b128 v[210:213], v235 offset:33792
	ds_read_b128 v[198:201], v235 offset:34816
	ds_read_b128 v[202:205], v235 offset:35840
	ds_read_b128 v[190:193], v235 offset:36864
	ds_read_b128 v[194:197], v235 offset:37888
	ds_read_b128 v[182:185], v235 offset:38912
	ds_read_b128 v[186:189], v235 offset:39936
	s_and_b64 vcc, exec, s[42:43]
	s_cbranch_vccnz .LBB0_266
	v_xor_b32_e32 v6, 0x80, v2
	ds_read_b128 v[6:9], v6
	v_xor_b32_e32 v10, 0xc0, v2
	ds_read_b128 v[10:13], v10
; #define PG8_STAGE(bufoff, gbase, voff) do { _Pragma("unroll") for (int _i = 0; _i < 2; ++_i) glds16_s((voff)[_i], (const void*)(gbase), ldsbase + (unsigned)((bufoff) + _i * 8192) + ldsw); } while (0)
; #define PG8_LDA(dst, b, h) do { _Pragma("unroll") for (int m = 0; m < 4; ++m) _Pragma("unroll") for (int k = 0; k < 2; ++k) dst[m][k] = *(const PG8_LAS bf16x8*)(lds + PG8_SA(b, h) + aoff + m * 2048 + k * 1024); } while (0)
; #define PG8_LDB(dst, b, h) do { _Pragma("unroll") for (int n = 0; n < 2; ++n) _Pragma("unroll") for (int k = 0; k < 2; ++k) dst[n][k] = *(const PG8_LAS bf16x8*)(lds + PG8_SB(b, h) + boff + n * 2048 + k * 1024); } while (0)
; #define PG8_LDX(pb, tp) do { _Pragma("unroll") for (int k = 0; k < 2; ++k) Ax[k] = *(const PG8_LAS bf16x8*)(lds + xoff + (pb) * 4096 + (tp) * 128 + k * 64); } while (0)
; #define PG8_MMA(ai, bj, At, Bt) do { __builtin_amdgcn_s_setprio(1); _Pragma("unroll") for (int m = 0; m < 4; ++m) _Pragma("unroll") for (int n = 0; n < 2; ++n) _Pragma("unroll") for (int k = 0; k < 2; ++k) \
;         acc[ai][bj][m][n] = __builtin_amdgcn_mfma_f32_16x16x32_bf16(Bt[n][k], At[m][k], acc[ai][bj][m][n], 0, 0, 0); __builtin_amdgcn_s_setprio(0); } while (0)
; #define PG8_WAIT_V(n) asm volatile("s_waitcnt vmcnt(" #n ")" ::: "memory")
; #define PG8_WAIT_L(n) asm volatile("s_waitcnt lgkmcnt(" #n ")" ::: "memory")
; #define PG8_BAR __builtin_amdgcn_s_barrier()
; #define PG8_SCHED __builtin_amdgcn_sched_barrier(0)
; template <class Epi, class Sched, bool HM = false>
; __device__ __forceinline__ void gemm_phase(PG8_LAS unsigned char* lds, const Gemm g, const Sched& S, const Epi& E) {
;     ...
;             PG8_LDB(B0, 1, 0); PG8_LDB(B1, 1, 1); PG8_SCHED; PG8_LDA(At, 1, 0); if (hasx) PG8_LDX(pb, 1); PG8_STAGE(PG8_SA(0, 1), a2 + hstepA, voffA);
;             PG8_WAIT_V(9); PG8_WAIT_L(0); PG8_BAR; PG8_MMA(0, 0, At, B0); PG8_MMA(0, 1, At, B1); if (hasx) PG8_MMAX(); PG8_BAR; PG8_SCHED;
.LBB0_266:
	s_add_u32 s8, s92, 0x80000
	s_addc_u32 s9, s93, 0
	s_mov_b32 s20, m0
	s_mov_b32 m0, s30
	s_nop 0
	global_load_lds_dwordx4 v225, s[8:9]
	s_mov_b32 m0, s20
	s_nop 0
	s_mov_b32 s20, m0
	s_mov_b32 m0, s31
	s_nop 0
	global_load_lds_dwordx4 v227, s[8:9]
	s_mov_b32 m0, s20
	s_waitcnt vmcnt(9)
	s_waitcnt lgkmcnt(0)
	s_barrier
	s_waitcnt lgkmcnt(7)
	v_mfma_f32_16x16x32_bf16 v[146:149], v[166:169], v[206:209], v[146:149]
	v_mfma_f32_16x16x32_bf16 v[142:145], v[174:177], v[206:209], v[142:145]
	s_waitcnt lgkmcnt(5)
	v_mfma_f32_16x16x32_bf16 v[138:141], v[166:169], v[198:201], v[138:141]
	v_mfma_f32_16x16x32_bf16 v[130:133], v[174:177], v[198:201], v[130:133]
	s_waitcnt lgkmcnt(3)
	v_mfma_f32_16x16x32_bf16 v[122:125], v[166:169], v[190:193], v[122:125]
	v_mfma_f32_16x16x32_bf16 v[114:117], v[174:177], v[190:193], v[114:117]
	s_waitcnt lgkmcnt(1)
	v_mfma_f32_16x16x32_bf16 v[106:109], v[166:169], v[182:185], v[106:109]
	v_mfma_f32_16x16x32_bf16 v[98:101], v[174:177], v[182:185], v[98:101]
	v_mfma_f32_16x16x32_bf16 v[146:149], v[170:173], v[210:213], v[146:149]
	v_mfma_f32_16x16x32_bf16 v[142:145], v[178:181], v[210:213], v[142:145]
	v_mfma_f32_16x16x32_bf16 v[138:141], v[170:173], v[202:205], v[138:141]
	v_mfma_f32_16x16x32_bf16 v[130:133], v[178:181], v[202:205], v[130:133]
	v_mfma_f32_16x16x32_bf16 v[122:125], v[170:173], v[194:197], v[122:125]
	v_mfma_f32_16x16x32_bf16 v[114:117], v[178:181], v[194:197], v[114:117]
	s_waitcnt lgkmcnt(0)
	v_mfma_f32_16x16x32_bf16 v[106:109], v[170:173], v[186:189], v[106:109]
	v_mfma_f32_16x16x32_bf16 v[98:101], v[178:181], v[186:189], v[98:101]
	v_mfma_f32_16x16x32_bf16 v[134:137], v[150:153], v[206:209], v[134:137]
	v_mfma_f32_16x16x32_bf16 v[126:129], v[158:161], v[206:209], v[126:129]
	v_mfma_f32_16x16x32_bf16 v[118:121], v[150:153], v[198:201], v[118:121]
	v_mfma_f32_16x16x32_bf16 v[110:113], v[158:161], v[198:201], v[110:113]
	v_mfma_f32_16x16x32_bf16 v[102:105], v[150:153], v[190:193], v[102:105]
	v_mfma_f32_16x16x32_bf16 v[94:97], v[158:161], v[190:193], v[94:97]
	v_mfma_f32_16x16x32_bf16 v[90:93], v[150:153], v[182:185], v[90:93]
	v_mfma_f32_16x16x32_bf16 v[86:89], v[158:161], v[182:185], v[86:89]
	v_mfma_f32_16x16x32_bf16 v[134:137], v[154:157], v[210:213], v[134:137]
	v_mfma_f32_16x16x32_bf16 v[126:129], v[162:165], v[210:213], v[126:129]
	v_mfma_f32_16x16x32_bf16 v[118:121], v[154:157], v[202:205], v[118:121]
	v_mfma_f32_16x16x32_bf16 v[110:113], v[162:165], v[202:205], v[110:113]
	v_mfma_f32_16x16x32_bf16 v[102:105], v[154:157], v[194:197], v[102:105]
	v_mfma_f32_16x16x32_bf16 v[94:97], v[162:165], v[194:197], v[94:97]
	v_mfma_f32_16x16x32_bf16 v[90:93], v[154:157], v[186:189], v[90:93]
	v_mfma_f32_16x16x32_bf16 v[86:89], v[162:165], v[186:189], v[86:89]
	s_and_b64 vcc, exec, s[42:43]
	s_cbranch_vccnz .LBB0_255
	s_and_b64 vcc, exec, s[44:45]
	s_cbranch_vccnz .LBB0_269
	v_mfma_f32_16x16x32_bf16 v[18:21], v[174:177], v[6:9], v[18:21]
	v_mfma_f32_16x16x32_bf16 v[14:17], v[158:161], v[6:9], v[14:17]
	v_mfma_f32_16x16x32_bf16 v[18:21], v[178:181], v[10:13], v[18:21]
	v_mfma_f32_16x16x32_bf16 v[14:17], v[162:165], v[10:13], v[14:17]
	s_branch .LBB0_254

; #define PG8_WAIT_V(n) asm volatile("s_waitcnt vmcnt(" #n ")" ::: "memory")
; #define PG8_BAR __builtin_amdgcn_s_barrier()
; template <class Epi, class Sched, bool HM = false>
; __device__ __forceinline__ void gemm_phase(PG8_LAS unsigned char* lds, const Gemm g, const Sched& S, const Epi& E) {
;     ...
;     PG8_WAIT_V(0);
;     PG8_BAR;
.LBB0_513:
	s_waitcnt vmcnt(0)
	s_setprio 0
	v_readlane_b32 s30, v252, 46
	v_readlane_b32 s96, v255, 5
	v_readlane_b32 s28, v252, 50
	v_readlane_b32 s36, v255, 21
	v_readlane_b32 s88, v255, 23
	v_readlane_b32 s58, v255, 25
	v_readlane_b32 s31, v252, 47
	v_readlane_b32 s51, v252, 48
	v_readlane_b32 s52, v252, 49
	v_readlane_b32 s97, v255, 6
	v_readlane_b32 s57, v255, 8
	v_readlane_b32 s29, v252, 51
	v_readlane_b32 s83, v255, 7
	v_readlane_b32 s37, v255, 22
	v_readlane_b32 s89, v255, 24
	v_readlane_b32 s59, v255, 26
	s_barrier

; #define PG8_STAGE(bufoff, gbase, voff) do { _Pragma("unroll") for (int _i = 0; _i < 2; ++_i) glds16_s((voff)[_i], (const void*)(gbase), ldsbase + (unsigned)((bufoff) + _i * 8192) + ldsw); } while (0)
; template <class Epi, class Sched, bool HM = false>
; __device__ __forceinline__ void gemm_phase(PG8_LAS unsigned char* lds, const Gemm g, const Sched& S, const Epi& E) {
;     ...
;     const int tid = tid_, wid = __builtin_amdgcn_readfirstlane(tid >> 6), lane = tid & 63, wr = wid >> 2, wc = wid & 3, fr = lane & 15, fq = lane >> 4;
;     const int K = g.K, nt = K / BK;
;     unsigned voffA[2], voffB[2];
; #pragma unroll
;     for (int i = 0; i < 2; ++i) { int R, C; stage_rc(tid * 16 + i * 8192, R, C); const int Rb = Epi::PERM ? ((R & ~31) + perm32(R & 31)) : R;
;         voffA[i] = (unsigned)(R * g.lda + C) * 2u; voffB[i] = (unsigned)(Rb * g.ldb + C) * 2u; }
;     const unsigned voffX = (unsigned)((4 * (wid & 3) + (lane >> 4)) * g.lda + 8 * (lane & 15)) * 2u;
;     const size_t kstep = (size_t)(BK * 2);
;     const size_t hstepA = (size_t)HALF * g.lda * 2, hstepB = (size_t)HALF * g.ldb * 2;
;     const size_t tstepA = (size_t)(HM ? HALF : g.pms) * g.lda * 2, tstepB = 2 * hstepB, xstep = 2 * hstepA; const bool hasx = g.pms != BM;
;     const unsigned ldsw = (unsigned)wid * 1024u, ldsx = (unsigned)(wid & 3) * 1024u;
;     const unsigned ldsbase = (unsigned)__builtin_amdgcn_readfirstlane((int)(unsigned)(__UINTPTR_TYPE__)lds);
;     const int aoff = lds_byte(wr * 64 + fr, fq * 8), boff = lds_byte(wc * 32 + fr, fq * 8);
;     const int xoff = XOFF + fr * 256 + fq * 16;
;     ...
;     Unit cur, nxt; int ui = 0;
;     if (!S.next(0, cur)) return;
;     f32x4 acc[2][2][4][2]; f32x4 accx[2];
; #pragma unroll
;     for (int a = 0; a < 2; ++a)
; #pragma unroll
;         for (int b = 0; b < 2; ++b)
; #pragma unroll
;             for (int m = 0; m < 4; ++m)
; #pragma unroll
;                 for (int n = 0; n < 2; ++n) acc[a][b][m][n] = (f32x4){0.f, 0.f, 0.f, 0.f};
;     accx[0] = (f32x4){0.f, 0.f, 0.f, 0.f}; accx[1] = accx[0];
;     bf16x8 At[4][2], B0[2][2], B1[2][2], Ax[2];
;     const char* cA = PG8_APTR(cur); const char* cB = PG8_BPTR(cur);
;     S.a_ready(cur);
;     PG8_STAGE(PG8_SB(0, 0), cB, voffB); PG8_STAGE(PG8_SB(0, 1), cB + hstepB, voffB); PG8_STAGE(PG8_SA(0, 0), cA, voffA); PG8_STAGEX(0, cA + xstep); PG8_STAGE(PG8_SA(0, 1), cA + hstepA, voffA);
;     if (wr == 1) PG8_BAR;
.LBB0_515:
	s_mov_b64 s[0:1], s[30:31]
	s_mov_b64 s[4:5], s[30:31]
	s_mov_b64 s[8:9], s[30:31]
	s_waitcnt vmcnt(0)
	v_mov_b32_e32 v4, v0
	s_andn2_b64 vcc, exec, s[96:97]
	v_readfirstlane_b32 s20, v4
	s_cbranch_vccnz .LBB0_514
	v_bfe_i32 v7, v4, 27, 1
	v_lshlrev_b32_e32 v5, 4, v4
	v_lshrrev_b32_e32 v7, 22, v7
	v_add_u32_e32 v7, v5, v7
	v_and_b32_e32 v7, 0xfffffc00, v7
	v_sub_u32_e32 v7, v5, v7
	v_ashrrev_i32_e32 v6, 31, v4
	v_lshrrev_b32_e32 v8, 4, v7
	v_lshrrev_b32_e32 v6, 26, v6
	v_bitop3_b32 v7, v8, v7, 32 bitop3:0x6c
	s_add_u32 s14, s0, 0x1a1e4000
	v_add_u32_e32 v6, v4, v6
	v_ashrrev_i32_e32 v9, 31, v7
	s_addc_u32 s15, s1, 0
	v_ashrrev_i32_e32 v6, 6, v6
	v_lshrrev_b32_e32 v9, 26, v9
	s_add_u32 s0, s4, s12
	v_lshlrev_b32_e32 v8, 3, v6
	v_add_u32_e32 v9, v7, v9
	s_addc_u32 s1, s5, 0
	v_and_b32_e32 v8, -16, v8
	v_ashrrev_i32_e32 v10, 6, v9
	v_and_b32_e32 v9, 0xc0, v9
	s_add_u32 s16, s0, 0x42a0000
	v_add_u32_e32 v8, v10, v8
	v_sub_u32_e32 v7, v7, v9
	s_addc_u32 s17, s1, 0
	v_lshlrev_b32_e32 v6, 5, v6
	v_ashrrev_i16_sdwa v7, v1, sext(v7) dst_sel:DWORD dst_unused:UNUSED_PAD src0_sel:DWORD src1_sel:BYTE_0
	v_lshlrev_b32_e32 v9, 1, v8
	v_lshrrev_b32_e32 v11, 2, v8
	v_and_b32_e32 v10, 3, v10
	s_mov_b32 s1, 0xfffe0
	v_and_b32_e32 v6, 32, v6
	v_bfe_i32 v7, v7, 0, 16
	v_and_b32_e32 v9, 24, v9
	v_and_b32_e32 v11, 4, v11
	v_and_or_b32 v10, v8, s1, v10
	v_or3_b32 v9, v10, v11, v9
	v_add_lshl_u32 v6, v6, v7, 1
	v_add_u32_e32 v5, 0x2000, v5
	v_lshl_add_u32 v225, v8, 12, v6
	v_lshl_add_u32 v226, v9, 12, v6
	v_ashrrev_i32_e32 v6, 31, v5
	v_lshrrev_b32_e32 v6, 22, v6
	v_add_u32_e32 v6, v5, v6
	v_ashrrev_i32_e32 v6, 10, v6
	v_mul_i32_i24_e32 v7, 0x400, v6
	v_sub_u32_e32 v5, v5, v7
	v_lshrrev_b32_e32 v7, 4, v5
	v_bitop3_b32 v5, v7, v5, 32 bitop3:0x6c
	v_ashrrev_i32_e32 v8, 31, v5
	v_lshrrev_b32_e32 v8, 26, v8
	v_lshlrev_b32_e32 v7, 3, v6
	v_add_u32_e32 v8, v5, v8
	s_ashr_i32 s0, s20, 6
	v_and_b32_e32 v7, -16, v7
	v_ashrrev_i32_e32 v9, 6, v8
	v_and_b32_e32 v8, 0xc0, v8
	s_and_b32 s21, s0, 3
	v_add_u32_e32 v7, v9, v7
	v_sub_u32_e32 v5, v5, v8
	v_and_b32_e32 v9, 3, v9
	v_lshlrev_b32_e32 v6, 5, v6
	v_ashrrev_i16_sdwa v5, v1, sext(v5) dst_sel:DWORD dst_unused:UNUSED_PAD src0_sel:DWORD src1_sel:BYTE_0
	v_lshlrev_b32_e32 v8, 1, v7
	v_lshrrev_b32_e32 v10, 2, v7
	v_and_or_b32 v9, v7, s1, v9
	s_ashr_i32 s22, s20, 8
	s_lshl_b32 s1, s21, 14
	s_lshl_b32 s0, s0, 10
	s_lshl_b32 s23, s21, 10
	v_readlane_b32 s4, v254, 41
	v_and_b32_e32 v6, 32, v6
	v_bfe_i32 v5, v5, 0, 16
	v_and_b32_e32 v8, 24, v8
	v_and_b32_e32 v10, 4, v10
	v_readlane_b32 s5, v254, 42
	s_add_u32 s4, s16, s4
	v_bfe_u32 v2, v4, 4, 2
	v_or3_b32 v8, v9, v10, v8
	v_add_lshl_u32 v5, v6, v5, 1
	v_and_b32_e32 v4, 15, v4
	s_addc_u32 s5, s17, s5
	s_add_i32 s18, s0, 0
	v_lshl_add_u32 v227, v7, 12, v5
	v_lshl_add_u32 v228, v8, 12, v5
	v_lshlrev_b32_e32 v5, 4, v4
	v_lshlrev_b32_e32 v6, 12, v2
	s_add_i32 s19, s18, 0x10000
	s_mov_b32 s0, m0
	s_mov_b32 m0, s19
	s_nop 0
	global_load_lds_dwordx4 v226, s[4:5]
	s_mov_b32 m0, s0
	v_or3_b32 v229, s1, v6, v5
	v_lshrrev_b32_e32 v232, 8, v229
	v_and_b32_e32 v232, 0xf0, v232
	v_xor_b32_e32 v229, v229, v232
	s_add_i32 s24, s18, 0x12000
	s_mov_b32 s0, m0
	s_mov_b32 m0, s24
	s_nop 0
	global_load_lds_dwordx4 v228, s[4:5]
	s_mov_b32 m0, s0
	v_readlane_b32 s1, v254, 23
	s_mul_i32 s0, s1, s10
	s_add_u32 s6, s14, s0
	s_mul_hi_i32 s0, s1, s10
	s_addc_u32 s7, s15, s0
	s_add_u32 s0, s4, 0x80000
	s_addc_u32 s1, s5, 0
	s_add_i32 s25, s18, 0x14000
	s_mov_b32 s27, m0
	s_mov_b32 m0, s25
	s_nop 0
	global_load_lds_dwordx4 v226, s[0:1]
	s_mov_b32 m0, s27
	s_add_i32 s28, s18, 0x16000
	s_mov_b32 s27, m0
	s_mov_b32 m0, s28
	s_nop 0
	global_load_lds_dwordx4 v228, s[0:1]
	s_mov_b32 m0, s27
	v_readlane_b32 s0, v254, 38
	v_readlane_b32 s1, v254, 39
	s_add_u32 s6, s6, s0
	s_addc_u32 s7, s7, s1
	s_mov_b32 s0, m0
	s_mov_b32 m0, s18
	s_nop 0
	global_load_lds_dwordx4 v225, s[6:7]
	s_mov_b32 m0, s0
	s_add_i32 s29, s18, 0x2000
	s_mov_b32 s0, m0
	s_mov_b32 m0, s29
	s_nop 0
	global_load_lds_dwordx4 v227, s[6:7]
	s_mov_b32 m0, s0
	s_add_u32 s0, s6, 0x100000
	s_addc_u32 s1, s7, 0
	s_add_i32 s30, s23, 0
	s_add_i32 s23, s30, 0x20400
	s_mov_b32 s27, m0
	s_mov_b32 m0, s23
	s_nop 0
	global_load_lds_dwordx4 v229, s[0:1]
	s_mov_b32 m0, s27
	s_add_u32 s0, s6, 0x80000
	s_addc_u32 s1, s7, 0
	s_add_i32 s31, s18, 0x4000
	s_mov_b32 s23, m0
	s_mov_b32 m0, s31
	s_nop 0
	global_load_lds_dwordx4 v225, s[0:1]
	s_mov_b32 m0, s23
	s_add_i32 s36, s18, 0x6000
	s_mov_b32 s23, m0
	s_mov_b32 m0, s36
	s_nop 0
	global_load_lds_dwordx4 v227, s[0:1]
	s_mov_b32 m0, s23
	s_cmp_eq_u32 s22, 1
	s_cselect_b64 s[0:1], -1, 0
	s_cmp_lg_u32 s22, 1
	s_cbranch_scc1 .LBB0_518
	s_setprio 1
	s_barrier

; #define PG8_STAGE(bufoff, gbase, voff) do { _Pragma("unroll") for (int _i = 0; _i < 2; ++_i) glds16_s((voff)[_i], (const void*)(gbase), ldsbase + (unsigned)((bufoff) + _i * 8192) + ldsw); } while (0)
; #define PG8_LDA(dst, b, h) do { _Pragma("unroll") for (int m = 0; m < 4; ++m) _Pragma("unroll") for (int k = 0; k < 2; ++k) dst[m][k] = *(const PG8_LAS bf16x8*)(lds + PG8_SA(b, h) + aoff + m * 2048 + k * 1024); } while (0)
; #define PG8_MMA(ai, bj, At, Bt) do { __builtin_amdgcn_s_setprio(1); _Pragma("unroll") for (int m = 0; m < 4; ++m) _Pragma("unroll") for (int n = 0; n < 2; ++n) _Pragma("unroll") for (int k = 0; k < 2; ++k) \
;         acc[ai][bj][m][n] = __builtin_amdgcn_mfma_f32_16x16x32_bf16(Bt[n][k], At[m][k], acc[ai][bj][m][n], 0, 0, 0); __builtin_amdgcn_s_setprio(0); } while (0)
; #define PG8_WAIT_V(n) asm volatile("s_waitcnt vmcnt(" #n ")" ::: "memory")
; #define PG8_WAIT_L(n) asm volatile("s_waitcnt lgkmcnt(" #n ")" ::: "memory")
; #define PG8_BAR __builtin_amdgcn_s_barrier()
; #define PG8_SCHED __builtin_amdgcn_sched_barrier(0)
; template <class Epi, class Sched, bool HM = false>
; __device__ __forceinline__ void gemm_phase(PG8_LAS unsigned char* lds, const Gemm g, const Sched& S, const Epi& E) {
;     ...
;             if (!HM) PG8_LDA(At, 1, 1); PG8_STAGE(PG8_SB(1, 0), b3, voffB); PG8_STAGE(PG8_SB(1, 1), b3 + hstepB, voffB); PG8_STAGE(PG8_SA(1, 0), a3, voffA);
;             PG8_WAIT_V(8); PG8_WAIT_L(0); PG8_BAR; if (!HM) { PG8_MMA(1, 0, At, B0); PG8_MMA(1, 1, At, B1); } PG8_BAR; PG8_SCHED;
;         }
.LBB0_532:
.LBB0_533:
	s_barrier
	ds_read_b128 v[182:185], v235 offset:49152
	ds_read_b128 v[186:189], v235 offset:50176
	ds_read_b128 v[190:193], v235 offset:51200
	ds_read_b128 v[194:197], v235 offset:52224
	ds_read_b128 v[198:201], v235 offset:53248
	ds_read_b128 v[202:205], v235 offset:54272
	ds_read_b128 v[206:209], v235 offset:55296
	ds_read_b128 v[210:213], v235 offset:56320
	s_mov_b32 s8, m0
	s_mov_b32 m0, s37
	s_nop 0
	global_load_lds_dwordx4 v226, s[6:7]
	s_mov_b32 m0, s8
	s_nop 0
	s_mov_b32 s8, m0
	s_mov_b32 m0, s51
	s_nop 0
	global_load_lds_dwordx4 v228, s[6:7]
	s_mov_b32 m0, s8
	s_add_u32 s6, s6, 0x80000
	s_addc_u32 s7, s7, 0
	s_mov_b32 s8, m0
	s_mov_b32 m0, s58
	s_nop 0
	global_load_lds_dwordx4 v226, s[6:7]
	s_mov_b32 m0, s8
	s_nop 0
	s_mov_b32 s8, m0
	s_mov_b32 m0, s59
	s_nop 0
	global_load_lds_dwordx4 v228, s[6:7]
	s_mov_b32 m0, s8
	s_mov_b32 s6, m0
	s_mov_b32 m0, s52
	s_nop 0
	global_load_lds_dwordx4 v225, s[4:5]
	s_mov_b32 m0, s6
	s_nop 0
	s_mov_b32 s6, m0
	s_mov_b32 m0, s57
	s_nop 0
	global_load_lds_dwordx4 v227, s[4:5]
	s_mov_b32 m0, s6
	s_waitcnt vmcnt(8)
	s_waitcnt lgkmcnt(0)
	s_barrier
	s_waitcnt lgkmcnt(7)
	v_mfma_f32_16x16x32_bf16 v[82:85], v[166:169], v[182:185], v[82:85]
	v_mfma_f32_16x16x32_bf16 v[78:81], v[174:177], v[182:185], v[78:81]
	s_waitcnt lgkmcnt(5)
	v_mfma_f32_16x16x32_bf16 v[74:77], v[166:169], v[190:193], v[74:77]
	v_mfma_f32_16x16x32_bf16 v[66:69], v[174:177], v[190:193], v[66:69]
	s_waitcnt lgkmcnt(3)
	v_mfma_f32_16x16x32_bf16 v[58:61], v[166:169], v[198:201], v[58:61]
	v_mfma_f32_16x16x32_bf16 v[50:53], v[174:177], v[198:201], v[50:53]
	s_waitcnt lgkmcnt(1)
	v_mfma_f32_16x16x32_bf16 v[42:45], v[166:169], v[206:209], v[42:45]
	v_mfma_f32_16x16x32_bf16 v[34:37], v[174:177], v[206:209], v[34:37]
	v_mfma_f32_16x16x32_bf16 v[82:85], v[170:173], v[186:189], v[82:85]
	v_mfma_f32_16x16x32_bf16 v[78:81], v[178:181], v[186:189], v[78:81]
	v_mfma_f32_16x16x32_bf16 v[74:77], v[170:173], v[194:197], v[74:77]
	v_mfma_f32_16x16x32_bf16 v[66:69], v[178:181], v[194:197], v[66:69]
	v_mfma_f32_16x16x32_bf16 v[58:61], v[170:173], v[202:205], v[58:61]
	v_mfma_f32_16x16x32_bf16 v[50:53], v[178:181], v[202:205], v[50:53]
	s_waitcnt lgkmcnt(0)
	v_mfma_f32_16x16x32_bf16 v[42:45], v[170:173], v[210:213], v[42:45]
	v_mfma_f32_16x16x32_bf16 v[34:37], v[178:181], v[210:213], v[34:37]
	v_mfma_f32_16x16x32_bf16 v[70:73], v[150:153], v[182:185], v[70:73]
	v_mfma_f32_16x16x32_bf16 v[62:65], v[158:161], v[182:185], v[62:65]
	v_mfma_f32_16x16x32_bf16 v[54:57], v[150:153], v[190:193], v[54:57]
	v_mfma_f32_16x16x32_bf16 v[46:49], v[158:161], v[190:193], v[46:49]
	v_mfma_f32_16x16x32_bf16 v[38:41], v[150:153], v[198:201], v[38:41]
	v_mfma_f32_16x16x32_bf16 v[30:33], v[158:161], v[198:201], v[30:33]
	v_mfma_f32_16x16x32_bf16 v[26:29], v[150:153], v[206:209], v[26:29]
	v_mfma_f32_16x16x32_bf16 v[22:25], v[158:161], v[206:209], v[22:25]
	v_mfma_f32_16x16x32_bf16 v[70:73], v[154:157], v[186:189], v[70:73]
	v_mfma_f32_16x16x32_bf16 v[62:65], v[162:165], v[186:189], v[62:65]
	v_mfma_f32_16x16x32_bf16 v[54:57], v[154:157], v[194:197], v[54:57]
	v_mfma_f32_16x16x32_bf16 v[46:49], v[162:165], v[194:197], v[46:49]
	v_mfma_f32_16x16x32_bf16 v[38:41], v[154:157], v[202:205], v[38:41]
	v_mfma_f32_16x16x32_bf16 v[30:33], v[162:165], v[202:205], v[30:33]
	v_mfma_f32_16x16x32_bf16 v[26:29], v[154:157], v[210:213], v[26:29]
	v_mfma_f32_16x16x32_bf16 v[22:25], v[162:165], v[210:213], v[22:25]
	s_barrier
	s_add_i32 s23, s23, 2
	s_addk_i32 s22, 0x1000
	s_add_u32 s38, s38, 0x100
	s_addc_u32 s39, s39, 0
	s_add_u32 s27, s27, 0x100
	s_addc_u32 s82, s82, 0
	s_cmp_gt_u32 s23, 29
	s_cbranch_scc1 .LBB0_549

; #define PG8_STAGE(bufoff, gbase, voff) do { _Pragma("unroll") for (int _i = 0; _i < 2; ++_i) glds16_s((voff)[_i], (const void*)(gbase), ldsbase + (unsigned)((bufoff) + _i * 8192) + ldsw); } while (0)
; #define PG8_STAGEX(pb, gbase) glds16_s(voffX, (const void*)(gbase), ldsbase + (unsigned)(XOFF + (pb) * 4096) + ldsx)
; #define PG8_LDA(dst, b, h) do { _Pragma("unroll") for (int m = 0; m < 4; ++m) _Pragma("unroll") for (int k = 0; k < 2; ++k) dst[m][k] = *(const PG8_LAS bf16x8*)(lds + PG8_SA(b, h) + aoff + m * 2048 + k * 1024); } while (0)
; #define PG8_LDB(dst, b, h) do { _Pragma("unroll") for (int n = 0; n < 2; ++n) _Pragma("unroll") for (int k = 0; k < 2; ++k) dst[n][k] = *(const PG8_LAS bf16x8*)(lds + PG8_SB(b, h) + boff + n * 2048 + k * 1024); } while (0)
; #define PG8_LDX(pb, tp) do { _Pragma("unroll") for (int k = 0; k < 2; ++k) Ax[k] = *(const PG8_LAS bf16x8*)(lds + xoff + (pb) * 4096 + (tp) * 128 + k * 64); } while (0)
; #define PG8_MMA(ai, bj, At, Bt) do { __builtin_amdgcn_s_setprio(1); _Pragma("unroll") for (int m = 0; m < 4; ++m) _Pragma("unroll") for (int n = 0; n < 2; ++n) _Pragma("unroll") for (int k = 0; k < 2; ++k) \
;         acc[ai][bj][m][n] = __builtin_amdgcn_mfma_f32_16x16x32_bf16(Bt[n][k], At[m][k], acc[ai][bj][m][n], 0, 0, 0); __builtin_amdgcn_s_setprio(0); } while (0)
; #define PG8_WAIT_V(n) asm volatile("s_waitcnt vmcnt(" #n ")" ::: "memory")
; #define PG8_WAIT_L(n) asm volatile("s_waitcnt lgkmcnt(" #n ")" ::: "memory")
; #define PG8_BAR __builtin_amdgcn_s_barrier()
; #define PG8_SCHED __builtin_amdgcn_sched_barrier(0)
; template <class Epi, class Sched, bool HM = false>
; __device__ __forceinline__ void gemm_phase(PG8_LAS unsigned char* lds, const Gemm g, const Sched& S, const Epi& E) {
;     ...
;             PG8_LDB(B0, 0, 0); PG8_LDB(B1, 0, 1); PG8_SCHED; PG8_LDA(At, 0, 0); if (hasx) PG8_LDX(pb, 0); PG8_STAGE(PG8_SA(1, 1), a1 + hstepA, voffA); PG8_STAGEX(pb ^ 1, a2 + xstep);
;             PG8_WAIT_V(9); PG8_WAIT_L(0); PG8_BAR; PG8_MMA(0, 0, At, B0); PG8_MMA(0, 1, At, B1); if (hasx) PG8_MMAX(); PG8_BAR; PG8_SCHED;
.LBB0_536:
	s_add_u32 s34, s34, 0x80000
	s_addc_u32 s35, s35, 0
	s_mov_b32 s21, m0
	s_mov_b32 m0, s83
	s_nop 0
	global_load_lds_dwordx4 v225, s[34:35]
	s_mov_b32 m0, s21
	s_nop 0
	s_mov_b32 s21, m0
	s_mov_b32 m0, s88
	s_nop 0
	global_load_lds_dwordx4 v227, s[34:35]
	s_mov_b32 m0, s21
	s_add_u32 s34, s94, 0x100000
	s_addc_u32 s35, s95, 0
	s_xor_b32 s20, s20, 0x21400
	s_add_i32 s20, s30, s20
	s_mov_b32 s21, m0
	s_mov_b32 m0, s20
	s_nop 0
	global_load_lds_dwordx4 v229, s[34:35]
	s_mov_b32 m0, s21
	s_waitcnt vmcnt(9)
	s_waitcnt lgkmcnt(0)
	s_barrier
	s_waitcnt lgkmcnt(7)
	v_mfma_f32_16x16x32_bf16 v[146:149], v[166:169], v[206:209], v[146:149]
	v_mfma_f32_16x16x32_bf16 v[142:145], v[174:177], v[206:209], v[142:145]
	s_waitcnt lgkmcnt(5)
	v_mfma_f32_16x16x32_bf16 v[138:141], v[166:169], v[198:201], v[138:141]
	v_mfma_f32_16x16x32_bf16 v[130:133], v[174:177], v[198:201], v[130:133]
	s_waitcnt lgkmcnt(3)
	v_mfma_f32_16x16x32_bf16 v[122:125], v[166:169], v[190:193], v[122:125]
	v_mfma_f32_16x16x32_bf16 v[114:117], v[174:177], v[190:193], v[114:117]
	s_waitcnt lgkmcnt(1)
	v_mfma_f32_16x16x32_bf16 v[106:109], v[166:169], v[182:185], v[106:109]
	v_mfma_f32_16x16x32_bf16 v[98:101], v[174:177], v[182:185], v[98:101]
	v_mfma_f32_16x16x32_bf16 v[146:149], v[170:173], v[210:213], v[146:149]
	v_mfma_f32_16x16x32_bf16 v[142:145], v[178:181], v[210:213], v[142:145]
	v_mfma_f32_16x16x32_bf16 v[138:141], v[170:173], v[202:205], v[138:141]
	v_mfma_f32_16x16x32_bf16 v[130:133], v[178:181], v[202:205], v[130:133]
	v_mfma_f32_16x16x32_bf16 v[122:125], v[170:173], v[194:197], v[122:125]
	v_mfma_f32_16x16x32_bf16 v[114:117], v[178:181], v[194:197], v[114:117]
	s_waitcnt lgkmcnt(0)
	v_mfma_f32_16x16x32_bf16 v[106:109], v[170:173], v[186:189], v[106:109]
	v_mfma_f32_16x16x32_bf16 v[98:101], v[178:181], v[186:189], v[98:101]
	v_mfma_f32_16x16x32_bf16 v[134:137], v[150:153], v[206:209], v[134:137]
	v_mfma_f32_16x16x32_bf16 v[126:129], v[158:161], v[206:209], v[126:129]
	v_mfma_f32_16x16x32_bf16 v[118:121], v[150:153], v[198:201], v[118:121]
	v_mfma_f32_16x16x32_bf16 v[110:113], v[158:161], v[198:201], v[110:113]
	v_mfma_f32_16x16x32_bf16 v[102:105], v[150:153], v[190:193], v[102:105]
	v_mfma_f32_16x16x32_bf16 v[94:97], v[158:161], v[190:193], v[94:97]
	v_mfma_f32_16x16x32_bf16 v[90:93], v[150:153], v[182:185], v[90:93]
	v_mfma_f32_16x16x32_bf16 v[86:89], v[158:161], v[182:185], v[86:89]
	v_mfma_f32_16x16x32_bf16 v[134:137], v[154:157], v[210:213], v[134:137]
	v_mfma_f32_16x16x32_bf16 v[126:129], v[162:165], v[210:213], v[126:129]
	v_mfma_f32_16x16x32_bf16 v[118:121], v[154:157], v[202:205], v[118:121]
	v_mfma_f32_16x16x32_bf16 v[110:113], v[162:165], v[202:205], v[110:113]
	v_mfma_f32_16x16x32_bf16 v[102:105], v[154:157], v[194:197], v[102:105]
	v_mfma_f32_16x16x32_bf16 v[94:97], v[162:165], v[194:197], v[94:97]
	v_mfma_f32_16x16x32_bf16 v[90:93], v[154:157], v[186:189], v[90:93]
	v_mfma_f32_16x16x32_bf16 v[86:89], v[162:165], v[186:189], v[86:89]
	s_andn2_b64 s[44:45], exec, s[78:79]
	s_and_b64 vcc, exec, s[42:43]
	s_cbranch_vccnz .LBB0_542
	s_and_b64 vcc, exec, s[44:45]
	s_cbranch_vccnz .LBB0_539
	v_mfma_f32_16x16x32_bf16 v[18:21], v[174:177], v[6:9], v[18:21]
	v_mfma_f32_16x16x32_bf16 v[14:17], v[158:161], v[6:9], v[14:17]
	v_mfma_f32_16x16x32_bf16 v[18:21], v[178:181], v[10:13], v[18:21]
	v_mfma_f32_16x16x32_bf16 v[14:17], v[162:165], v[10:13], v[14:17]
	s_branch .LBB0_542

; #define PG8_STAGE(bufoff, gbase, voff) do { _Pragma("unroll") for (int _i = 0; _i < 2; ++_i) glds16_s((voff)[_i], (const void*)(gbase), ldsbase + (unsigned)((bufoff) + _i * 8192) + ldsw); } while (0)
; #define PG8_LDA(dst, b, h) do { _Pragma("unroll") for (int m = 0; m < 4; ++m) _Pragma("unroll") for (int k = 0; k < 2; ++k) dst[m][k] = *(const PG8_LAS bf16x8*)(lds + PG8_SA(b, h) + aoff + m * 2048 + k * 1024); } while (0)
; #define PG8_LDB(dst, b, h) do { _Pragma("unroll") for (int n = 0; n < 2; ++n) _Pragma("unroll") for (int k = 0; k < 2; ++k) dst[n][k] = *(const PG8_LAS bf16x8*)(lds + PG8_SB(b, h) + boff + n * 2048 + k * 1024); } while (0)
; #define PG8_LDX(pb, tp) do { _Pragma("unroll") for (int k = 0; k < 2; ++k) Ax[k] = *(const PG8_LAS bf16x8*)(lds + xoff + (pb) * 4096 + (tp) * 128 + k * 64); } while (0)
; #define PG8_MMA(ai, bj, At, Bt) do { __builtin_amdgcn_s_setprio(1); _Pragma("unroll") for (int m = 0; m < 4; ++m) _Pragma("unroll") for (int n = 0; n < 2; ++n) _Pragma("unroll") for (int k = 0; k < 2; ++k) \
;         acc[ai][bj][m][n] = __builtin_amdgcn_mfma_f32_16x16x32_bf16(Bt[n][k], At[m][k], acc[ai][bj][m][n], 0, 0, 0); __builtin_amdgcn_s_setprio(0); } while (0)
; #define PG8_WAIT_V(n) asm volatile("s_waitcnt vmcnt(" #n ")" ::: "memory")
; #define PG8_WAIT_L(n) asm volatile("s_waitcnt lgkmcnt(" #n ")" ::: "memory")
; #define PG8_BAR __builtin_amdgcn_s_barrier()
; #define PG8_SCHED __builtin_amdgcn_sched_barrier(0)
; template <class Epi, class Sched, bool HM = false>
; __device__ __forceinline__ void gemm_phase(PG8_LAS unsigned char* lds, const Gemm g, const Sched& S, const Epi& E) {
;     ...
;             PG8_WAIT_V(9); PG8_WAIT_L(0); PG8_BAR; PG8_MMA(0, 0, At, B0); PG8_MMA(0, 1, At, B1); if (hasx) PG8_MMAX(); PG8_BAR; PG8_SCHED;
;             if (!HM) PG8_LDA(At, 0, 1); PG8_STAGE(PG8_SB(0, 0), b2, voffB); PG8_STAGE(PG8_SB(0, 1), b2 + hstepB, voffB); PG8_STAGE(PG8_SA(0, 0), a2, voffA);
;             PG8_WAIT_V(9); PG8_WAIT_L(0); PG8_BAR; if (!HM) { PG8_MMA(1, 0, At, B0); PG8_MMA(1, 1, At, B1); } PG8_BAR; PG8_SCHED;
;             PG8_LDB(B0, 1, 0); PG8_LDB(B1, 1, 1); PG8_SCHED; PG8_LDA(At, 1, 0); if (hasx) PG8_LDX(pb, 1); PG8_STAGE(PG8_SA(0, 1), a2 + hstepA, voffA);
.LBB0_541:
.LBB0_542:
	s_barrier
	ds_read_b128 v[182:185], v235 offset:16384
	ds_read_b128 v[186:189], v235 offset:17408
	ds_read_b128 v[190:193], v235 offset:18432
	ds_read_b128 v[194:197], v235 offset:19456
	ds_read_b128 v[198:201], v235 offset:20480
	ds_read_b128 v[202:205], v235 offset:21504
	ds_read_b128 v[206:209], v235 offset:22528
	ds_read_b128 v[210:213], v235 offset:23552
	s_mov_b32 s20, m0
	s_mov_b32 m0, s19
	s_nop 0
	global_load_lds_dwordx4 v226, s[8:9]
	s_mov_b32 m0, s20
	s_nop 0
	s_mov_b32 s20, m0
	s_mov_b32 m0, s24
	s_nop 0
	global_load_lds_dwordx4 v228, s[8:9]
	s_mov_b32 m0, s20
	s_add_u32 s8, s8, 0x80000
	s_addc_u32 s9, s9, 0
	s_mov_b32 s20, m0
	s_mov_b32 m0, s25
	s_nop 0
	global_load_lds_dwordx4 v226, s[8:9]
	s_mov_b32 m0, s20
	s_nop 0
	s_mov_b32 s20, m0
	s_mov_b32 m0, s28
	s_nop 0
	global_load_lds_dwordx4 v228, s[8:9]
	s_mov_b32 m0, s20
	s_mov_b32 s8, m0
	s_mov_b32 m0, s18
	s_nop 0
	global_load_lds_dwordx4 v225, s[94:95]
	s_mov_b32 m0, s8
	s_nop 0
	s_mov_b32 s8, m0
	s_mov_b32 m0, s29
	s_nop 0
	global_load_lds_dwordx4 v227, s[94:95]
	s_mov_b32 m0, s8
	s_waitcnt vmcnt(9)
	s_waitcnt lgkmcnt(0)
	s_barrier
	s_waitcnt lgkmcnt(7)
	v_mfma_f32_16x16x32_bf16 v[82:85], v[166:169], v[182:185], v[82:85]
	v_mfma_f32_16x16x32_bf16 v[78:81], v[174:177], v[182:185], v[78:81]
	s_waitcnt lgkmcnt(5)
	v_mfma_f32_16x16x32_bf16 v[74:77], v[166:169], v[190:193], v[74:77]
	v_mfma_f32_16x16x32_bf16 v[66:69], v[174:177], v[190:193], v[66:69]
	s_waitcnt lgkmcnt(3)
	v_mfma_f32_16x16x32_bf16 v[58:61], v[166:169], v[198:201], v[58:61]
	v_mfma_f32_16x16x32_bf16 v[50:53], v[174:177], v[198:201], v[50:53]
	s_waitcnt lgkmcnt(1)
	v_mfma_f32_16x16x32_bf16 v[42:45], v[166:169], v[206:209], v[42:45]
	v_mfma_f32_16x16x32_bf16 v[34:37], v[174:177], v[206:209], v[34:37]
	v_mfma_f32_16x16x32_bf16 v[82:85], v[170:173], v[186:189], v[82:85]
	v_mfma_f32_16x16x32_bf16 v[78:81], v[178:181], v[186:189], v[78:81]
	v_mfma_f32_16x16x32_bf16 v[74:77], v[170:173], v[194:197], v[74:77]
	v_mfma_f32_16x16x32_bf16 v[66:69], v[178:181], v[194:197], v[66:69]
	v_mfma_f32_16x16x32_bf16 v[58:61], v[170:173], v[202:205], v[58:61]
	v_mfma_f32_16x16x32_bf16 v[50:53], v[178:181], v[202:205], v[50:53]
	s_waitcnt lgkmcnt(0)
	v_mfma_f32_16x16x32_bf16 v[42:45], v[170:173], v[210:213], v[42:45]
	v_mfma_f32_16x16x32_bf16 v[34:37], v[178:181], v[210:213], v[34:37]
	v_mfma_f32_16x16x32_bf16 v[70:73], v[150:153], v[182:185], v[70:73]
	v_mfma_f32_16x16x32_bf16 v[62:65], v[158:161], v[182:185], v[62:65]
	v_mfma_f32_16x16x32_bf16 v[54:57], v[150:153], v[190:193], v[54:57]
	v_mfma_f32_16x16x32_bf16 v[46:49], v[158:161], v[190:193], v[46:49]
	v_mfma_f32_16x16x32_bf16 v[38:41], v[150:153], v[198:201], v[38:41]
	v_mfma_f32_16x16x32_bf16 v[30:33], v[158:161], v[198:201], v[30:33]
	v_mfma_f32_16x16x32_bf16 v[26:29], v[150:153], v[206:209], v[26:29]
	v_mfma_f32_16x16x32_bf16 v[22:25], v[158:161], v[206:209], v[22:25]
	v_mfma_f32_16x16x32_bf16 v[70:73], v[154:157], v[186:189], v[70:73]
	v_mfma_f32_16x16x32_bf16 v[62:65], v[162:165], v[186:189], v[62:65]
	v_mfma_f32_16x16x32_bf16 v[54:57], v[154:157], v[194:197], v[54:57]
	v_mfma_f32_16x16x32_bf16 v[46:49], v[162:165], v[194:197], v[46:49]
	v_mfma_f32_16x16x32_bf16 v[38:41], v[154:157], v[202:205], v[38:41]
	v_mfma_f32_16x16x32_bf16 v[30:33], v[162:165], v[202:205], v[30:33]
	v_mfma_f32_16x16x32_bf16 v[26:29], v[154:157], v[210:213], v[26:29]
	v_mfma_f32_16x16x32_bf16 v[22:25], v[162:165], v[210:213], v[22:25]
	s_barrier
	v_add_u32_e32 v4, 0x18000, v234
	ds_read_b128 v[166:169], v4
	ds_read_b128 v[170:173], v4 offset:1024
	ds_read_b128 v[174:177], v4 offset:2048
	ds_read_b128 v[178:181], v4 offset:3072
	v_add_u32_e32 v4, 0x1c000, v234
	ds_read_b128 v[150:153], v4
	ds_read_b128 v[154:157], v4 offset:1024
	ds_read_b128 v[158:161], v4 offset:2048
	ds_read_b128 v[162:165], v4 offset:3072
	ds_read_b128 v[206:209], v235 offset:32768
	ds_read_b128 v[210:213], v235 offset:33792
	ds_read_b128 v[198:201], v235 offset:34816
	ds_read_b128 v[202:205], v235 offset:35840
	ds_read_b128 v[190:193], v235 offset:36864
	ds_read_b128 v[194:197], v235 offset:37888
	ds_read_b128 v[182:185], v235 offset:38912
	ds_read_b128 v[186:189], v235 offset:39936
	s_and_b64 vcc, exec, s[42:43]
	s_cbranch_vccnz .LBB0_544
	v_xor_b32_e32 v6, 0x80, v2
	ds_read_b128 v[6:9], v6
	v_xor_b32_e32 v10, 0xc0, v2
	ds_read_b128 v[10:13], v10
; #define PG8_STAGE(bufoff, gbase, voff) do { _Pragma("unroll") for (int _i = 0; _i < 2; ++_i) glds16_s((voff)[_i], (const void*)(gbase), ldsbase + (unsigned)((bufoff) + _i * 8192) + ldsw); } while (0)
; #define PG8_LDA(dst, b, h) do { _Pragma("unroll") for (int m = 0; m < 4; ++m) _Pragma("unroll") for (int k = 0; k < 2; ++k) dst[m][k] = *(const PG8_LAS bf16x8*)(lds + PG8_SA(b, h) + aoff + m * 2048 + k * 1024); } while (0)
; #define PG8_LDB(dst, b, h) do { _Pragma("unroll") for (int n = 0; n < 2; ++n) _Pragma("unroll") for (int k = 0; k < 2; ++k) dst[n][k] = *(const PG8_LAS bf16x8*)(lds + PG8_SB(b, h) + boff + n * 2048 + k * 1024); } while (0)
; #define PG8_LDX(pb, tp) do { _Pragma("unroll") for (int k = 0; k < 2; ++k) Ax[k] = *(const PG8_LAS bf16x8*)(lds + xoff + (pb) * 4096 + (tp) * 128 + k * 64); } while (0)
; #define PG8_MMA(ai, bj, At, Bt) do { __builtin_amdgcn_s_setprio(1); _Pragma("unroll") for (int m = 0; m < 4; ++m) _Pragma("unroll") for (int n = 0; n < 2; ++n) _Pragma("unroll") for (int k = 0; k < 2; ++k) \
;         acc[ai][bj][m][n] = __builtin_amdgcn_mfma_f32_16x16x32_bf16(Bt[n][k], At[m][k], acc[ai][bj][m][n], 0, 0, 0); __builtin_amdgcn_s_setprio(0); } while (0)
; #define PG8_WAIT_V(n) asm volatile("s_waitcnt vmcnt(" #n ")" ::: "memory")
; #define PG8_WAIT_L(n) asm volatile("s_waitcnt lgkmcnt(" #n ")" ::: "memory")
; #define PG8_BAR __builtin_amdgcn_s_barrier()
; #define PG8_SCHED __builtin_amdgcn_sched_barrier(0)
; template <class Epi, class Sched, bool HM = false>
; __device__ __forceinline__ void gemm_phase(PG8_LAS unsigned char* lds, const Gemm g, const Sched& S, const Epi& E) {
;     ...
;             PG8_LDB(B0, 1, 0); PG8_LDB(B1, 1, 1); PG8_SCHED; PG8_LDA(At, 1, 0); if (hasx) PG8_LDX(pb, 1); PG8_STAGE(PG8_SA(0, 1), a2 + hstepA, voffA);
;             PG8_WAIT_V(9); PG8_WAIT_L(0); PG8_BAR; PG8_MMA(0, 0, At, B0); PG8_MMA(0, 1, At, B1); if (hasx) PG8_MMAX(); PG8_BAR; PG8_SCHED;
.LBB0_544:
	s_add_u32 s8, s94, 0x80000
	s_addc_u32 s9, s95, 0
	s_mov_b32 s20, m0
	s_mov_b32 m0, s31
	s_nop 0
	global_load_lds_dwordx4 v225, s[8:9]
	s_mov_b32 m0, s20
	s_nop 0
	s_mov_b32 s20, m0
	s_mov_b32 m0, s36
	s_nop 0
	global_load_lds_dwordx4 v227, s[8:9]
	s_mov_b32 m0, s20
	s_waitcnt vmcnt(9)
	s_waitcnt lgkmcnt(0)
	s_barrier
	s_waitcnt lgkmcnt(7)
	v_mfma_f32_16x16x32_bf16 v[146:149], v[166:169], v[206:209], v[146:149]
	v_mfma_f32_16x16x32_bf16 v[142:145], v[174:177], v[206:209], v[142:145]
	s_waitcnt lgkmcnt(5)
	v_mfma_f32_16x16x32_bf16 v[138:141], v[166:169], v[198:201], v[138:141]
	v_mfma_f32_16x16x32_bf16 v[130:133], v[174:177], v[198:201], v[130:133]
	s_waitcnt lgkmcnt(3)
	v_mfma_f32_16x16x32_bf16 v[122:125], v[166:169], v[190:193], v[122:125]
	v_mfma_f32_16x16x32_bf16 v[114:117], v[174:177], v[190:193], v[114:117]
	s_waitcnt lgkmcnt(1)
	v_mfma_f32_16x16x32_bf16 v[106:109], v[166:169], v[182:185], v[106:109]
	v_mfma_f32_16x16x32_bf16 v[98:101], v[174:177], v[182:185], v[98:101]
	v_mfma_f32_16x16x32_bf16 v[146:149], v[170:173], v[210:213], v[146:149]
	v_mfma_f32_16x16x32_bf16 v[142:145], v[178:181], v[210:213], v[142:145]
	v_mfma_f32_16x16x32_bf16 v[138:141], v[170:173], v[202:205], v[138:141]
	v_mfma_f32_16x16x32_bf16 v[130:133], v[178:181], v[202:205], v[130:133]
	v_mfma_f32_16x16x32_bf16 v[122:125], v[170:173], v[194:197], v[122:125]
	v_mfma_f32_16x16x32_bf16 v[114:117], v[178:181], v[194:197], v[114:117]
	s_waitcnt lgkmcnt(0)
	v_mfma_f32_16x16x32_bf16 v[106:109], v[170:173], v[186:189], v[106:109]
	v_mfma_f32_16x16x32_bf16 v[98:101], v[178:181], v[186:189], v[98:101]
	v_mfma_f32_16x16x32_bf16 v[134:137], v[150:153], v[206:209], v[134:137]
	v_mfma_f32_16x16x32_bf16 v[126:129], v[158:161], v[206:209], v[126:129]
	v_mfma_f32_16x16x32_bf16 v[118:121], v[150:153], v[198:201], v[118:121]
	v_mfma_f32_16x16x32_bf16 v[110:113], v[158:161], v[198:201], v[110:113]
	v_mfma_f32_16x16x32_bf16 v[102:105], v[150:153], v[190:193], v[102:105]
	v_mfma_f32_16x16x32_bf16 v[94:97], v[158:161], v[190:193], v[94:97]
	v_mfma_f32_16x16x32_bf16 v[90:93], v[150:153], v[182:185], v[90:93]
	v_mfma_f32_16x16x32_bf16 v[86:89], v[158:161], v[182:185], v[86:89]
	v_mfma_f32_16x16x32_bf16 v[134:137], v[154:157], v[210:213], v[134:137]
	v_mfma_f32_16x16x32_bf16 v[126:129], v[162:165], v[210:213], v[126:129]
	v_mfma_f32_16x16x32_bf16 v[118:121], v[154:157], v[202:205], v[118:121]
	v_mfma_f32_16x16x32_bf16 v[110:113], v[162:165], v[202:205], v[110:113]
	v_mfma_f32_16x16x32_bf16 v[102:105], v[154:157], v[194:197], v[102:105]
	v_mfma_f32_16x16x32_bf16 v[94:97], v[162:165], v[194:197], v[94:97]
	v_mfma_f32_16x16x32_bf16 v[90:93], v[154:157], v[186:189], v[90:93]
	v_mfma_f32_16x16x32_bf16 v[86:89], v[162:165], v[186:189], v[86:89]
	s_and_b64 vcc, exec, s[42:43]
	s_cbranch_vccnz .LBB0_533
	s_and_b64 vcc, exec, s[44:45]
	s_cbranch_vccnz .LBB0_547
	v_mfma_f32_16x16x32_bf16 v[18:21], v[174:177], v[6:9], v[18:21]
	v_mfma_f32_16x16x32_bf16 v[14:17], v[158:161], v[6:9], v[14:17]
	v_mfma_f32_16x16x32_bf16 v[18:21], v[178:181], v[10:13], v[18:21]
	v_mfma_f32_16x16x32_bf16 v[14:17], v[162:165], v[10:13], v[14:17]
	s_branch .LBB0_532

; #define PG8_STAGE(bufoff, gbase, voff) do { _Pragma("unroll") for (int _i = 0; _i < 2; ++_i) glds16_s((voff)[_i], (const void*)(gbase), ldsbase + (unsigned)((bufoff) + _i * 8192) + ldsw); } while (0)
; template <class Epi, class Sched, bool HM = false>
; __device__ __forceinline__ void gemm_phase(PG8_LAS unsigned char* lds, const Gemm g, const Sched& S, const Epi& E) {
;     ...
;     const int tid = tid_, wid = __builtin_amdgcn_readfirstlane(tid >> 6), lane = tid & 63, wr = wid >> 2, wc = wid & 3, fr = lane & 15, fq = lane >> 4;
;     const int K = g.K, nt = K / BK;
;     unsigned voffA[2], voffB[2];
; #pragma unroll
;     for (int i = 0; i < 2; ++i) { int R, C; stage_rc(tid * 16 + i * 8192, R, C); const int Rb = Epi::PERM ? ((R & ~31) + perm32(R & 31)) : R;
;         voffA[i] = (unsigned)(R * g.lda + C) * 2u; voffB[i] = (unsigned)(Rb * g.ldb + C) * 2u; }
;     const unsigned voffX = (unsigned)((4 * (wid & 3) + (lane >> 4)) * g.lda + 8 * (lane & 15)) * 2u;
;     const size_t kstep = (size_t)(BK * 2);
;     const size_t hstepA = (size_t)HALF * g.lda * 2, hstepB = (size_t)HALF * g.ldb * 2;
;     const size_t tstepA = (size_t)(HM ? HALF : g.pms) * g.lda * 2, tstepB = 2 * hstepB, xstep = 2 * hstepA; const bool hasx = g.pms != BM;
;     const unsigned ldsw = (unsigned)wid * 1024u, ldsx = (unsigned)(wid & 3) * 1024u;
;     const unsigned ldsbase = (unsigned)__builtin_amdgcn_readfirstlane((int)(unsigned)(__UINTPTR_TYPE__)lds);
;     const int aoff = lds_byte(wr * 64 + fr, fq * 8), boff = lds_byte(wc * 32 + fr, fq * 8);
;     const int xoff = XOFF + fr * 256 + fq * 16;
;     ...
;     Unit cur, nxt; int ui = 0;
;     if (!S.next(0, cur)) return;
;     f32x4 acc[2][2][4][2]; f32x4 accx[2];
; #pragma unroll
;     for (int a = 0; a < 2; ++a)
; #pragma unroll
;         for (int b = 0; b < 2; ++b)
; #pragma unroll
;             for (int m = 0; m < 4; ++m)
; #pragma unroll
;                 for (int n = 0; n < 2; ++n) acc[a][b][m][n] = (f32x4){0.f, 0.f, 0.f, 0.f};
;     accx[0] = (f32x4){0.f, 0.f, 0.f, 0.f}; accx[1] = accx[0];
;     bf16x8 At[4][2], B0[2][2], B1[2][2], Ax[2];
;     const char* cA = PG8_APTR(cur); const char* cB = PG8_BPTR(cur);
;     S.a_ready(cur);
;     PG8_STAGE(PG8_SB(0, 0), cB, voffB); PG8_STAGE(PG8_SB(0, 1), cB + hstepB, voffB); PG8_STAGE(PG8_SA(0, 0), cA, voffA); PG8_STAGEX(0, cA + xstep); PG8_STAGE(PG8_SA(0, 1), cA + hstepA, voffA);
;     if (wr == 1) PG8_BAR;
.LBB0_566:
	v_readlane_b32 s12, v254, 5
	s_mov_b64 s[4:5], s[30:31]
	s_mov_b64 s[6:7], s[30:31]
	s_mov_b64 s[38:39], s[30:31]
	s_mov_b64 s[34:35], s[30:31]
	s_mov_b64 s[8:9], s[30:31]
	s_mov_b64 s[0:1], s[30:31]
	s_waitcnt vmcnt(0)
	v_mov_b32_e32 v4, v0
	v_readlane_b32 s13, v254, 6
	s_andn2_b64 vcc, exec, s[12:13]
	v_readfirstlane_b32 s20, v4
	s_cbranch_vccnz .LBB0_616
	v_bfe_i32 v6, v4, 27, 1
	v_lshlrev_b32_e32 v2, 4, v4
	v_lshrrev_b32_e32 v6, 22, v6
	v_add_u32_e32 v6, v2, v6
	v_and_b32_e32 v6, 0xfffffc00, v6
	v_sub_u32_e32 v6, v2, v6
	v_ashrrev_i32_e32 v5, 31, v4
	v_lshrrev_b32_e32 v7, 4, v6
	v_lshrrev_b32_e32 v5, 26, v5
	v_bitop3_b32 v6, v7, v6, 32 bitop3:0x6c
	s_add_u32 s10, s4, 0x1a1e4000
	v_add_u32_e32 v5, v4, v5
	v_ashrrev_i32_e32 v8, 31, v6
	s_addc_u32 s14, s5, 0
	v_ashrrev_i32_e32 v5, 6, v5
	v_lshrrev_b32_e32 v8, 26, v8
	s_add_u32 s4, s6, s66
	v_lshlrev_b32_e32 v7, 3, v5
	v_add_u32_e32 v8, v6, v8
	s_addc_u32 s5, s7, s67
	v_and_b32_e32 v7, -16, v7
	v_ashrrev_i32_e32 v9, 6, v8
	v_and_b32_e32 v8, 0xc0, v8
	s_add_u32 s15, s4, 0xa0000
	v_add_u32_e32 v7, v9, v7
	v_sub_u32_e32 v6, v6, v8
	s_addc_u32 s45, s5, 0
	v_lshlrev_b32_e32 v5, 5, v5
	v_ashrrev_i16_sdwa v6, v1, sext(v6) dst_sel:DWORD dst_unused:UNUSED_PAD src0_sel:DWORD src1_sel:BYTE_0
	v_lshlrev_b32_e32 v8, 1, v7
	v_lshrrev_b32_e32 v10, 2, v7
	v_and_b32_e32 v9, 3, v9
	s_mov_b32 s5, 0xfffe0
	v_and_b32_e32 v5, 32, v5
	v_bfe_i32 v6, v6, 0, 16
	v_and_b32_e32 v8, 24, v8
	v_and_b32_e32 v10, 4, v10
	v_and_or_b32 v9, v7, s5, v9
	v_or3_b32 v8, v9, v10, v8
	v_add_lshl_u32 v5, v5, v6, 1
	v_add_u32_e32 v2, 0x2000, v2
	v_lshl_add_u32 v225, v7, 12, v5
	v_lshl_add_u32 v226, v8, 12, v5
	v_ashrrev_i32_e32 v5, 31, v2
	v_lshrrev_b32_e32 v5, 22, v5
	v_add_u32_e32 v5, v2, v5
	v_ashrrev_i32_e32 v5, 10, v5
	v_mul_i32_i24_e32 v6, 0x400, v5
	v_sub_u32_e32 v2, v2, v6
	v_lshrrev_b32_e32 v6, 4, v2
	v_bitop3_b32 v2, v6, v2, 32 bitop3:0x6c
	v_ashrrev_i32_e32 v7, 31, v2
	v_lshrrev_b32_e32 v7, 26, v7
	v_lshlrev_b32_e32 v6, 3, v5
	v_add_u32_e32 v7, v2, v7
	v_and_b32_e32 v6, -16, v6
	v_ashrrev_i32_e32 v8, 6, v7
	v_and_b32_e32 v7, 0xc0, v7
	v_add_u32_e32 v6, v8, v6
	v_sub_u32_e32 v2, v2, v7
	v_lshlrev_b32_e32 v5, 5, v5
	v_ashrrev_i16_sdwa v2, v1, sext(v2) dst_sel:DWORD dst_unused:UNUSED_PAD src0_sel:DWORD src1_sel:BYTE_0
	v_lshlrev_b32_e32 v7, 1, v6
	v_lshrrev_b32_e32 v9, 2, v6
	v_and_b32_e32 v8, 3, v8
	v_and_b32_e32 v5, 32, v5
	v_bfe_i32 v2, v2, 0, 16
	v_and_b32_e32 v7, 24, v7
	v_and_b32_e32 v9, 4, v9
	v_and_or_b32 v8, v6, s5, v8
	s_ashr_i32 s4, s20, 6
	v_or3_b32 v7, v8, v9, v7
	v_add_lshl_u32 v2, v5, v2, 1
	s_and_b32 s21, s4, 3
	v_lshl_add_u32 v227, v6, 12, v2
	v_lshl_add_u32 v228, v7, 12, v2
	v_and_b32_e32 v2, 15, v4
	v_bfe_u32 v4, v4, 4, 2
	s_lshl_b32 s5, s21, 14
	v_lshlrev_b32_e32 v5, 12, v4
	v_lshlrev_b32_e32 v6, 4, v2
	s_ashr_i32 s22, s20, 8
	v_or3_b32 v229, s5, v5, v6
	v_lshrrev_b32_e32 v232, 8, v229
	v_and_b32_e32 v232, 0xf0, v232
	v_xor_b32_e32 v229, v229, v232
	s_lshl_b32 s6, s4, 10
	s_lshl_b32 s18, s21, 10
	v_readlane_b32 s4, v254, 46
	v_readlane_b32 s5, v254, 47
	s_add_u32 s4, s15, s4
	s_addc_u32 s5, s45, s5
	s_add_i32 s51, s6, 0
	s_add_i32 s83, s51, 0x10000
	s_mov_b32 s6, m0
	s_mov_b32 m0, s83
	s_nop 0
	global_load_lds_dwordx4 v226, s[4:5]
	s_mov_b32 m0, s6
	s_add_i32 s36, s51, 0x12000
	s_mov_b32 s6, m0
	s_mov_b32 m0, s36
	s_nop 0
	global_load_lds_dwordx4 v228, s[4:5]
	s_mov_b32 m0, s6
	v_readlane_b32 s7, v254, 26
	s_mul_i32 s6, s7, s57
	s_add_u32 s12, s10, s6
	s_mul_hi_i32 s6, s7, s57
	s_addc_u32 s13, s14, s6
	s_add_u32 s6, s4, 0x80000
	s_addc_u32 s7, s5, 0
	s_add_i32 s37, s51, 0x14000
	s_mov_b32 s16, m0
	s_mov_b32 m0, s37
	s_nop 0
	global_load_lds_dwordx4 v226, s[6:7]
	s_mov_b32 m0, s16
	s_add_i32 s16, s51, 0x16000
	s_mov_b32 s17, m0
	s_mov_b32 m0, s16
	s_nop 0
	global_load_lds_dwordx4 v228, s[6:7]
	s_mov_b32 m0, s17
	v_readlane_b32 s6, v254, 43
	v_readlane_b32 s7, v254, 44
	s_add_u32 s6, s12, s6
	s_addc_u32 s7, s13, s7
	s_mov_b32 s12, m0
	s_mov_b32 m0, s51
	s_nop 0
	global_load_lds_dwordx4 v225, s[6:7]
	s_mov_b32 m0, s12
	s_add_i32 s17, s51, 0x2000
	s_mov_b32 s12, m0
	s_mov_b32 m0, s17
	s_nop 0
	global_load_lds_dwordx4 v227, s[6:7]
	s_mov_b32 m0, s12
	s_add_u32 s12, s6, 0x100000
	s_addc_u32 s13, s7, 0
	s_add_i32 s18, s18, 0
	s_add_i32 s19, s18, 0x20400
	s_mov_b32 s23, m0
	s_mov_b32 m0, s19
	s_nop 0
	global_load_lds_dwordx4 v229, s[12:13]
	s_mov_b32 m0, s23
	s_add_u32 s12, s6, 0x80000
	s_addc_u32 s13, s7, 0
	s_add_i32 s19, s51, 0x4000
	s_mov_b32 s23, m0
	s_mov_b32 m0, s19
	s_nop 0
	global_load_lds_dwordx4 v225, s[12:13]
	s_mov_b32 m0, s23
	s_add_i32 s28, s51, 0x6000
	s_mov_b32 s23, m0
	s_mov_b32 m0, s28
	s_nop 0
	global_load_lds_dwordx4 v227, s[12:13]
	s_mov_b32 m0, s23
	s_cmp_eq_u32 s22, 1
	s_cselect_b64 s[74:75], -1, 0
	s_cmp_lg_u32 s22, 1
	s_cbranch_scc1 .LBB0_569
	s_setprio 1
	s_barrier

; #define PG8_STAGE(bufoff, gbase, voff) do { _Pragma("unroll") for (int _i = 0; _i < 2; ++_i) glds16_s((voff)[_i], (const void*)(gbase), ldsbase + (unsigned)((bufoff) + _i * 8192) + ldsw); } while (0)
; #define PG8_LDA(dst, b, h) do { _Pragma("unroll") for (int m = 0; m < 4; ++m) _Pragma("unroll") for (int k = 0; k < 2; ++k) dst[m][k] = *(const PG8_LAS bf16x8*)(lds + PG8_SA(b, h) + aoff + m * 2048 + k * 1024); } while (0)
; #define PG8_MMA(ai, bj, At, Bt) do { __builtin_amdgcn_s_setprio(1); _Pragma("unroll") for (int m = 0; m < 4; ++m) _Pragma("unroll") for (int n = 0; n < 2; ++n) _Pragma("unroll") for (int k = 0; k < 2; ++k) \
;         acc[ai][bj][m][n] = __builtin_amdgcn_mfma_f32_16x16x32_bf16(Bt[n][k], At[m][k], acc[ai][bj][m][n], 0, 0, 0); __builtin_amdgcn_s_setprio(0); } while (0)
; #define PG8_WAIT_V(n) asm volatile("s_waitcnt vmcnt(" #n ")" ::: "memory")
; #define PG8_WAIT_L(n) asm volatile("s_waitcnt lgkmcnt(" #n ")" ::: "memory")
; #define PG8_BAR __builtin_amdgcn_s_barrier()
; #define PG8_SCHED __builtin_amdgcn_sched_barrier(0)
; template <class Epi, class Sched, bool HM = false>
; __device__ __forceinline__ void gemm_phase(PG8_LAS unsigned char* lds, const Gemm g, const Sched& S, const Epi& E) {
;     ...
;             if (!HM) PG8_LDA(At, 1, 1); PG8_STAGE(PG8_SB(1, 0), b3, voffB); PG8_STAGE(PG8_SB(1, 1), b3 + hstepB, voffB); PG8_STAGE(PG8_SA(1, 0), a3, voffA);
;             PG8_WAIT_V(8); PG8_WAIT_L(0); PG8_BAR; if (!HM) { PG8_MMA(1, 0, At, B0); PG8_MMA(1, 1, At, B1); } PG8_BAR; PG8_SCHED;
;         }
.LBB0_579:
.LBB0_580:
	s_barrier
	ds_read_b128 v[182:185], v235 offset:49152
	ds_read_b128 v[186:189], v235 offset:50176
	ds_read_b128 v[190:193], v235 offset:51200
	ds_read_b128 v[194:197], v235 offset:52224
	ds_read_b128 v[198:201], v235 offset:53248
	ds_read_b128 v[202:205], v235 offset:54272
	ds_read_b128 v[206:209], v235 offset:55296
	ds_read_b128 v[210:213], v235 offset:56320
	s_mov_b32 s8, m0
	s_mov_b32 m0, s29
	s_nop 0
	global_load_lds_dwordx4 v226, s[6:7]
	s_mov_b32 m0, s8
	s_nop 0
	s_mov_b32 s8, m0
	s_mov_b32 m0, s30
	s_nop 0
	global_load_lds_dwordx4 v228, s[6:7]
	s_mov_b32 m0, s8
	s_add_u32 s6, s6, 0x80000
	s_addc_u32 s7, s7, 0
	s_mov_b32 s8, m0
	s_mov_b32 m0, s25
	s_nop 0
	global_load_lds_dwordx4 v226, s[6:7]
	s_mov_b32 m0, s8
	s_nop 0
	s_mov_b32 s8, m0
	s_mov_b32 m0, s12
	s_nop 0
	global_load_lds_dwordx4 v228, s[6:7]
	s_mov_b32 m0, s8
	s_mov_b32 s6, m0
	s_mov_b32 m0, s31
	s_nop 0
	global_load_lds_dwordx4 v225, s[4:5]
	s_mov_b32 m0, s6
	s_nop 0
	s_mov_b32 s6, m0
	s_mov_b32 m0, s24
	s_nop 0
	global_load_lds_dwordx4 v227, s[4:5]
	s_mov_b32 m0, s6
	s_waitcnt vmcnt(8)
	s_waitcnt lgkmcnt(0)
	s_barrier
	s_waitcnt lgkmcnt(7)
	v_mfma_f32_16x16x32_bf16 v[82:85], v[166:169], v[182:185], v[82:85]
	v_mfma_f32_16x16x32_bf16 v[78:81], v[174:177], v[182:185], v[78:81]
	s_waitcnt lgkmcnt(5)
	v_mfma_f32_16x16x32_bf16 v[66:69], v[166:169], v[190:193], v[66:69]
	v_mfma_f32_16x16x32_bf16 v[62:65], v[174:177], v[190:193], v[62:65]
	s_waitcnt lgkmcnt(3)
	v_mfma_f32_16x16x32_bf16 v[50:53], v[166:169], v[198:201], v[50:53]
	v_mfma_f32_16x16x32_bf16 v[46:49], v[174:177], v[198:201], v[46:49]
	s_waitcnt lgkmcnt(1)
	v_mfma_f32_16x16x32_bf16 v[34:37], v[166:169], v[206:209], v[34:37]
	v_mfma_f32_16x16x32_bf16 v[30:33], v[174:177], v[206:209], v[30:33]
	v_mfma_f32_16x16x32_bf16 v[82:85], v[170:173], v[186:189], v[82:85]
	v_mfma_f32_16x16x32_bf16 v[78:81], v[178:181], v[186:189], v[78:81]
	v_mfma_f32_16x16x32_bf16 v[66:69], v[170:173], v[194:197], v[66:69]
	v_mfma_f32_16x16x32_bf16 v[62:65], v[178:181], v[194:197], v[62:65]
	v_mfma_f32_16x16x32_bf16 v[50:53], v[170:173], v[202:205], v[50:53]
	v_mfma_f32_16x16x32_bf16 v[46:49], v[178:181], v[202:205], v[46:49]
	s_waitcnt lgkmcnt(0)
	v_mfma_f32_16x16x32_bf16 v[34:37], v[170:173], v[210:213], v[34:37]
	v_mfma_f32_16x16x32_bf16 v[30:33], v[178:181], v[210:213], v[30:33]
	v_mfma_f32_16x16x32_bf16 v[74:77], v[150:153], v[182:185], v[74:77]
	v_mfma_f32_16x16x32_bf16 v[70:73], v[158:161], v[182:185], v[70:73]
	v_mfma_f32_16x16x32_bf16 v[58:61], v[150:153], v[190:193], v[58:61]
	v_mfma_f32_16x16x32_bf16 v[54:57], v[158:161], v[190:193], v[54:57]
	v_mfma_f32_16x16x32_bf16 v[42:45], v[150:153], v[198:201], v[42:45]
	v_mfma_f32_16x16x32_bf16 v[38:41], v[158:161], v[198:201], v[38:41]
	v_mfma_f32_16x16x32_bf16 v[26:29], v[150:153], v[206:209], v[26:29]
	v_mfma_f32_16x16x32_bf16 v[22:25], v[158:161], v[206:209], v[22:25]
	v_mfma_f32_16x16x32_bf16 v[74:77], v[154:157], v[186:189], v[74:77]
	v_mfma_f32_16x16x32_bf16 v[70:73], v[162:165], v[186:189], v[70:73]
	v_mfma_f32_16x16x32_bf16 v[58:61], v[154:157], v[194:197], v[58:61]
	v_mfma_f32_16x16x32_bf16 v[54:57], v[162:165], v[194:197], v[54:57]
	v_mfma_f32_16x16x32_bf16 v[42:45], v[154:157], v[202:205], v[42:45]
	v_mfma_f32_16x16x32_bf16 v[38:41], v[162:165], v[202:205], v[38:41]
	v_mfma_f32_16x16x32_bf16 v[26:29], v[154:157], v[210:213], v[26:29]
	v_mfma_f32_16x16x32_bf16 v[22:25], v[162:165], v[210:213], v[22:25]
	s_barrier
	s_add_i32 s23, s23, 2
	s_addk_i32 s22, 0x1000
	s_add_u32 s61, s61, 0x100
	s_addc_u32 s44, s44, 0
	s_add_u32 s82, s82, 0x100
	s_addc_u32 s27, s27, 0
	s_cmp_gt_u32 s23, 29
	s_cbranch_scc1 .LBB0_596

; #define PG8_STAGE(bufoff, gbase, voff) do { _Pragma("unroll") for (int _i = 0; _i < 2; ++_i) glds16_s((voff)[_i], (const void*)(gbase), ldsbase + (unsigned)((bufoff) + _i * 8192) + ldsw); } while (0)
; #define PG8_STAGEX(pb, gbase) glds16_s(voffX, (const void*)(gbase), ldsbase + (unsigned)(XOFF + (pb) * 4096) + ldsx)
; #define PG8_LDA(dst, b, h) do { _Pragma("unroll") for (int m = 0; m < 4; ++m) _Pragma("unroll") for (int k = 0; k < 2; ++k) dst[m][k] = *(const PG8_LAS bf16x8*)(lds + PG8_SA(b, h) + aoff + m * 2048 + k * 1024); } while (0)
; #define PG8_LDB(dst, b, h) do { _Pragma("unroll") for (int n = 0; n < 2; ++n) _Pragma("unroll") for (int k = 0; k < 2; ++k) dst[n][k] = *(const PG8_LAS bf16x8*)(lds + PG8_SB(b, h) + boff + n * 2048 + k * 1024); } while (0)
; #define PG8_LDX(pb, tp) do { _Pragma("unroll") for (int k = 0; k < 2; ++k) Ax[k] = *(const PG8_LAS bf16x8*)(lds + xoff + (pb) * 4096 + (tp) * 128 + k * 64); } while (0)
; #define PG8_MMA(ai, bj, At, Bt) do { __builtin_amdgcn_s_setprio(1); _Pragma("unroll") for (int m = 0; m < 4; ++m) _Pragma("unroll") for (int n = 0; n < 2; ++n) _Pragma("unroll") for (int k = 0; k < 2; ++k) \
;         acc[ai][bj][m][n] = __builtin_amdgcn_mfma_f32_16x16x32_bf16(Bt[n][k], At[m][k], acc[ai][bj][m][n], 0, 0, 0); __builtin_amdgcn_s_setprio(0); } while (0)
; #define PG8_WAIT_V(n) asm volatile("s_waitcnt vmcnt(" #n ")" ::: "memory")
; #define PG8_WAIT_L(n) asm volatile("s_waitcnt lgkmcnt(" #n ")" ::: "memory")
; #define PG8_BAR __builtin_amdgcn_s_barrier()
; #define PG8_SCHED __builtin_amdgcn_sched_barrier(0)
; template <class Epi, class Sched, bool HM = false>
; __device__ __forceinline__ void gemm_phase(PG8_LAS unsigned char* lds, const Gemm g, const Sched& S, const Epi& E) {
;     ...
;             PG8_LDB(B0, 0, 0); PG8_LDB(B1, 0, 1); PG8_SCHED; PG8_LDA(At, 0, 0); if (hasx) PG8_LDX(pb, 0); PG8_STAGE(PG8_SA(1, 1), a1 + hstepA, voffA); PG8_STAGEX(pb ^ 1, a2 + xstep);
;             PG8_WAIT_V(9); PG8_WAIT_L(0); PG8_BAR; PG8_MMA(0, 0, At, B0); PG8_MMA(0, 1, At, B1); if (hasx) PG8_MMAX(); PG8_BAR; PG8_SCHED;
.LBB0_583:
	s_add_u32 s42, s42, 0x80000
	s_addc_u32 s43, s43, 0
	s_mov_b32 s21, m0
	s_mov_b32 m0, s13
	s_nop 0
	global_load_lds_dwordx4 v225, s[42:43]
	s_mov_b32 m0, s21
	s_nop 0
	s_mov_b32 s21, m0
	s_mov_b32 m0, s52
	s_nop 0
	global_load_lds_dwordx4 v227, s[42:43]
	s_mov_b32 m0, s21
	s_add_u32 s42, s8, 0x100000
	s_addc_u32 s43, s9, 0
	s_xor_b32 s20, s20, 0x21400
	s_add_i32 s20, s18, s20
	s_mov_b32 s21, m0
	s_mov_b32 m0, s20
	s_nop 0
	global_load_lds_dwordx4 v229, s[42:43]
	s_mov_b32 m0, s21
	s_waitcnt vmcnt(9)
	s_waitcnt lgkmcnt(0)
	s_barrier
	s_waitcnt lgkmcnt(7)
	v_mfma_f32_16x16x32_bf16 v[146:149], v[166:169], v[206:209], v[146:149]
	v_mfma_f32_16x16x32_bf16 v[142:145], v[174:177], v[206:209], v[142:145]
	s_waitcnt lgkmcnt(5)
	v_mfma_f32_16x16x32_bf16 v[130:133], v[166:169], v[198:201], v[130:133]
	v_mfma_f32_16x16x32_bf16 v[126:129], v[174:177], v[198:201], v[126:129]
	s_waitcnt lgkmcnt(3)
	v_mfma_f32_16x16x32_bf16 v[114:117], v[166:169], v[190:193], v[114:117]
	v_mfma_f32_16x16x32_bf16 v[110:113], v[174:177], v[190:193], v[110:113]
	s_waitcnt lgkmcnt(1)
	v_mfma_f32_16x16x32_bf16 v[98:101], v[166:169], v[182:185], v[98:101]
	v_mfma_f32_16x16x32_bf16 v[94:97], v[174:177], v[182:185], v[94:97]
	v_mfma_f32_16x16x32_bf16 v[146:149], v[170:173], v[210:213], v[146:149]
	v_mfma_f32_16x16x32_bf16 v[142:145], v[178:181], v[210:213], v[142:145]
	v_mfma_f32_16x16x32_bf16 v[130:133], v[170:173], v[202:205], v[130:133]
	v_mfma_f32_16x16x32_bf16 v[126:129], v[178:181], v[202:205], v[126:129]
	v_mfma_f32_16x16x32_bf16 v[114:117], v[170:173], v[194:197], v[114:117]
	v_mfma_f32_16x16x32_bf16 v[110:113], v[178:181], v[194:197], v[110:113]
	s_waitcnt lgkmcnt(0)
	v_mfma_f32_16x16x32_bf16 v[98:101], v[170:173], v[186:189], v[98:101]
	v_mfma_f32_16x16x32_bf16 v[94:97], v[178:181], v[186:189], v[94:97]
	v_mfma_f32_16x16x32_bf16 v[138:141], v[150:153], v[206:209], v[138:141]
	v_mfma_f32_16x16x32_bf16 v[134:137], v[158:161], v[206:209], v[134:137]
	v_mfma_f32_16x16x32_bf16 v[122:125], v[150:153], v[198:201], v[122:125]
	v_mfma_f32_16x16x32_bf16 v[118:121], v[158:161], v[198:201], v[118:121]
	v_mfma_f32_16x16x32_bf16 v[106:109], v[150:153], v[190:193], v[106:109]
	v_mfma_f32_16x16x32_bf16 v[102:105], v[158:161], v[190:193], v[102:105]
	v_mfma_f32_16x16x32_bf16 v[90:93], v[150:153], v[182:185], v[90:93]
	v_mfma_f32_16x16x32_bf16 v[86:89], v[158:161], v[182:185], v[86:89]
	v_mfma_f32_16x16x32_bf16 v[138:141], v[154:157], v[210:213], v[138:141]
	v_mfma_f32_16x16x32_bf16 v[134:137], v[162:165], v[210:213], v[134:137]
	v_mfma_f32_16x16x32_bf16 v[122:125], v[154:157], v[202:205], v[122:125]
	v_mfma_f32_16x16x32_bf16 v[118:121], v[162:165], v[202:205], v[118:121]
	v_mfma_f32_16x16x32_bf16 v[106:109], v[154:157], v[194:197], v[106:109]
	v_mfma_f32_16x16x32_bf16 v[102:105], v[162:165], v[194:197], v[102:105]
	v_mfma_f32_16x16x32_bf16 v[90:93], v[154:157], v[186:189], v[90:93]
	v_mfma_f32_16x16x32_bf16 v[86:89], v[162:165], v[186:189], v[86:89]
	s_andn2_b64 s[42:43], exec, s[96:97]
	s_and_b64 vcc, exec, s[40:41]
	s_cbranch_vccnz .LBB0_589
	s_and_b64 vcc, exec, s[42:43]
	s_cbranch_vccnz .LBB0_586
	v_mfma_f32_16x16x32_bf16 v[18:21], v[174:177], v[6:9], v[18:21]
	v_mfma_f32_16x16x32_bf16 v[14:17], v[158:161], v[6:9], v[14:17]
	v_mfma_f32_16x16x32_bf16 v[18:21], v[178:181], v[10:13], v[18:21]
	v_mfma_f32_16x16x32_bf16 v[14:17], v[162:165], v[10:13], v[14:17]
	s_branch .LBB0_589

; #define PG8_STAGE(bufoff, gbase, voff) do { _Pragma("unroll") for (int _i = 0; _i < 2; ++_i) glds16_s((voff)[_i], (const void*)(gbase), ldsbase + (unsigned)((bufoff) + _i * 8192) + ldsw); } while (0)
; #define PG8_LDA(dst, b, h) do { _Pragma("unroll") for (int m = 0; m < 4; ++m) _Pragma("unroll") for (int k = 0; k < 2; ++k) dst[m][k] = *(const PG8_LAS bf16x8*)(lds + PG8_SA(b, h) + aoff + m * 2048 + k * 1024); } while (0)
; #define PG8_LDB(dst, b, h) do { _Pragma("unroll") for (int n = 0; n < 2; ++n) _Pragma("unroll") for (int k = 0; k < 2; ++k) dst[n][k] = *(const PG8_LAS bf16x8*)(lds + PG8_SB(b, h) + boff + n * 2048 + k * 1024); } while (0)
; #define PG8_LDX(pb, tp) do { _Pragma("unroll") for (int k = 0; k < 2; ++k) Ax[k] = *(const PG8_LAS bf16x8*)(lds + xoff + (pb) * 4096 + (tp) * 128 + k * 64); } while (0)
; #define PG8_MMA(ai, bj, At, Bt) do { __builtin_amdgcn_s_setprio(1); _Pragma("unroll") for (int m = 0; m < 4; ++m) _Pragma("unroll") for (int n = 0; n < 2; ++n) _Pragma("unroll") for (int k = 0; k < 2; ++k) \
;         acc[ai][bj][m][n] = __builtin_amdgcn_mfma_f32_16x16x32_bf16(Bt[n][k], At[m][k], acc[ai][bj][m][n], 0, 0, 0); __builtin_amdgcn_s_setprio(0); } while (0)
; #define PG8_WAIT_V(n) asm volatile("s_waitcnt vmcnt(" #n ")" ::: "memory")
; #define PG8_WAIT_L(n) asm volatile("s_waitcnt lgkmcnt(" #n ")" ::: "memory")
; #define PG8_BAR __builtin_amdgcn_s_barrier()
; #define PG8_SCHED __builtin_amdgcn_sched_barrier(0)
; template <class Epi, class Sched, bool HM = false>
; __device__ __forceinline__ void gemm_phase(PG8_LAS unsigned char* lds, const Gemm g, const Sched& S, const Epi& E) {
;     ...
;             PG8_WAIT_V(9); PG8_WAIT_L(0); PG8_BAR; PG8_MMA(0, 0, At, B0); PG8_MMA(0, 1, At, B1); if (hasx) PG8_MMAX(); PG8_BAR; PG8_SCHED;
;             if (!HM) PG8_LDA(At, 0, 1); PG8_STAGE(PG8_SB(0, 0), b2, voffB); PG8_STAGE(PG8_SB(0, 1), b2 + hstepB, voffB); PG8_STAGE(PG8_SA(0, 0), a2, voffA);
;             PG8_WAIT_V(9); PG8_WAIT_L(0); PG8_BAR; if (!HM) { PG8_MMA(1, 0, At, B0); PG8_MMA(1, 1, At, B1); } PG8_BAR; PG8_SCHED;
;             PG8_LDB(B0, 1, 0); PG8_LDB(B1, 1, 1); PG8_SCHED; PG8_LDA(At, 1, 0); if (hasx) PG8_LDX(pb, 1); PG8_STAGE(PG8_SA(0, 1), a2 + hstepA, voffA);
.LBB0_588:
.LBB0_589:
	s_barrier
	ds_read_b128 v[182:185], v235 offset:16384
	ds_read_b128 v[186:189], v235 offset:17408
	ds_read_b128 v[190:193], v235 offset:18432
	ds_read_b128 v[194:197], v235 offset:19456
	ds_read_b128 v[198:201], v235 offset:20480
	ds_read_b128 v[202:205], v235 offset:21504
	ds_read_b128 v[206:209], v235 offset:22528
	ds_read_b128 v[210:213], v235 offset:23552
	s_mov_b32 s20, m0
	s_mov_b32 m0, s83
	s_nop 0
	global_load_lds_dwordx4 v226, s[34:35]
	s_mov_b32 m0, s20
	s_nop 0
	s_mov_b32 s20, m0
	s_mov_b32 m0, s36
	s_nop 0
	global_load_lds_dwordx4 v228, s[34:35]
	s_mov_b32 m0, s20
	s_add_u32 s20, s34, 0x80000
	s_addc_u32 s21, s35, 0
	s_mov_b32 s34, m0
	s_mov_b32 m0, s37
	s_nop 0
	global_load_lds_dwordx4 v226, s[20:21]
	s_mov_b32 m0, s34
	s_nop 0
	s_mov_b32 s34, m0
	s_mov_b32 m0, s16
	s_nop 0
	global_load_lds_dwordx4 v228, s[20:21]
	s_mov_b32 m0, s34
	s_mov_b32 s20, m0
	s_mov_b32 m0, s51
	s_nop 0
	global_load_lds_dwordx4 v225, s[8:9]
	s_mov_b32 m0, s20
	s_nop 0
	s_mov_b32 s20, m0
	s_mov_b32 m0, s17
	s_nop 0
	global_load_lds_dwordx4 v227, s[8:9]
	s_mov_b32 m0, s20
	s_waitcnt vmcnt(9)
	s_waitcnt lgkmcnt(0)
	s_barrier
	s_waitcnt lgkmcnt(7)
	v_mfma_f32_16x16x32_bf16 v[82:85], v[166:169], v[182:185], v[82:85]
	v_mfma_f32_16x16x32_bf16 v[78:81], v[174:177], v[182:185], v[78:81]
	s_waitcnt lgkmcnt(5)
	v_mfma_f32_16x16x32_bf16 v[66:69], v[166:169], v[190:193], v[66:69]
	v_mfma_f32_16x16x32_bf16 v[62:65], v[174:177], v[190:193], v[62:65]
	s_waitcnt lgkmcnt(3)
	v_mfma_f32_16x16x32_bf16 v[50:53], v[166:169], v[198:201], v[50:53]
	v_mfma_f32_16x16x32_bf16 v[46:49], v[174:177], v[198:201], v[46:49]
	s_waitcnt lgkmcnt(1)
	v_mfma_f32_16x16x32_bf16 v[34:37], v[166:169], v[206:209], v[34:37]
	v_mfma_f32_16x16x32_bf16 v[30:33], v[174:177], v[206:209], v[30:33]
	v_mfma_f32_16x16x32_bf16 v[82:85], v[170:173], v[186:189], v[82:85]
	v_mfma_f32_16x16x32_bf16 v[78:81], v[178:181], v[186:189], v[78:81]
	v_mfma_f32_16x16x32_bf16 v[66:69], v[170:173], v[194:197], v[66:69]
	v_mfma_f32_16x16x32_bf16 v[62:65], v[178:181], v[194:197], v[62:65]
	v_mfma_f32_16x16x32_bf16 v[50:53], v[170:173], v[202:205], v[50:53]
	v_mfma_f32_16x16x32_bf16 v[46:49], v[178:181], v[202:205], v[46:49]
	s_waitcnt lgkmcnt(0)
	v_mfma_f32_16x16x32_bf16 v[34:37], v[170:173], v[210:213], v[34:37]
	v_mfma_f32_16x16x32_bf16 v[30:33], v[178:181], v[210:213], v[30:33]
	v_mfma_f32_16x16x32_bf16 v[74:77], v[150:153], v[182:185], v[74:77]
	v_mfma_f32_16x16x32_bf16 v[70:73], v[158:161], v[182:185], v[70:73]
	v_mfma_f32_16x16x32_bf16 v[58:61], v[150:153], v[190:193], v[58:61]
	v_mfma_f32_16x16x32_bf16 v[54:57], v[158:161], v[190:193], v[54:57]
	v_mfma_f32_16x16x32_bf16 v[42:45], v[150:153], v[198:201], v[42:45]
	v_mfma_f32_16x16x32_bf16 v[38:41], v[158:161], v[198:201], v[38:41]
	v_mfma_f32_16x16x32_bf16 v[26:29], v[150:153], v[206:209], v[26:29]
	v_mfma_f32_16x16x32_bf16 v[22:25], v[158:161], v[206:209], v[22:25]
	v_mfma_f32_16x16x32_bf16 v[74:77], v[154:157], v[186:189], v[74:77]
	v_mfma_f32_16x16x32_bf16 v[70:73], v[162:165], v[186:189], v[70:73]
	v_mfma_f32_16x16x32_bf16 v[58:61], v[154:157], v[194:197], v[58:61]
	v_mfma_f32_16x16x32_bf16 v[54:57], v[162:165], v[194:197], v[54:57]
	v_mfma_f32_16x16x32_bf16 v[42:45], v[154:157], v[202:205], v[42:45]
	v_mfma_f32_16x16x32_bf16 v[38:41], v[162:165], v[202:205], v[38:41]
	v_mfma_f32_16x16x32_bf16 v[26:29], v[154:157], v[210:213], v[26:29]
	v_mfma_f32_16x16x32_bf16 v[22:25], v[162:165], v[210:213], v[22:25]
	s_barrier
	v_add_u32_e32 v4, 0x18000, v234
	ds_read_b128 v[166:169], v4
	ds_read_b128 v[170:173], v4 offset:1024
	ds_read_b128 v[174:177], v4 offset:2048
	ds_read_b128 v[178:181], v4 offset:3072
	v_add_u32_e32 v4, 0x1c000, v234
	ds_read_b128 v[150:153], v4
	ds_read_b128 v[154:157], v4 offset:1024
	ds_read_b128 v[158:161], v4 offset:2048
	ds_read_b128 v[162:165], v4 offset:3072
	ds_read_b128 v[206:209], v235 offset:32768
	ds_read_b128 v[210:213], v235 offset:33792
	ds_read_b128 v[198:201], v235 offset:34816
	ds_read_b128 v[202:205], v235 offset:35840
	ds_read_b128 v[190:193], v235 offset:36864
	ds_read_b128 v[194:197], v235 offset:37888
	ds_read_b128 v[182:185], v235 offset:38912
	ds_read_b128 v[186:189], v235 offset:39936
	s_and_b64 vcc, exec, s[40:41]
	s_cbranch_vccnz .LBB0_591
	v_xor_b32_e32 v6, 0x80, v2
	ds_read_b128 v[6:9], v6
	v_xor_b32_e32 v10, 0xc0, v2
	ds_read_b128 v[10:13], v10
; #define PG8_STAGE(bufoff, gbase, voff) do { _Pragma("unroll") for (int _i = 0; _i < 2; ++_i) glds16_s((voff)[_i], (const void*)(gbase), ldsbase + (unsigned)((bufoff) + _i * 8192) + ldsw); } while (0)
; #define PG8_LDA(dst, b, h) do { _Pragma("unroll") for (int m = 0; m < 4; ++m) _Pragma("unroll") for (int k = 0; k < 2; ++k) dst[m][k] = *(const PG8_LAS bf16x8*)(lds + PG8_SA(b, h) + aoff + m * 2048 + k * 1024); } while (0)
; #define PG8_LDB(dst, b, h) do { _Pragma("unroll") for (int n = 0; n < 2; ++n) _Pragma("unroll") for (int k = 0; k < 2; ++k) dst[n][k] = *(const PG8_LAS bf16x8*)(lds + PG8_SB(b, h) + boff + n * 2048 + k * 1024); } while (0)
; #define PG8_LDX(pb, tp) do { _Pragma("unroll") for (int k = 0; k < 2; ++k) Ax[k] = *(const PG8_LAS bf16x8*)(lds + xoff + (pb) * 4096 + (tp) * 128 + k * 64); } while (0)
; #define PG8_MMA(ai, bj, At, Bt) do { __builtin_amdgcn_s_setprio(1); _Pragma("unroll") for (int m = 0; m < 4; ++m) _Pragma("unroll") for (int n = 0; n < 2; ++n) _Pragma("unroll") for (int k = 0; k < 2; ++k) \
;         acc[ai][bj][m][n] = __builtin_amdgcn_mfma_f32_16x16x32_bf16(Bt[n][k], At[m][k], acc[ai][bj][m][n], 0, 0, 0); __builtin_amdgcn_s_setprio(0); } while (0)
; #define PG8_WAIT_V(n) asm volatile("s_waitcnt vmcnt(" #n ")" ::: "memory")
; #define PG8_WAIT_L(n) asm volatile("s_waitcnt lgkmcnt(" #n ")" ::: "memory")
; #define PG8_BAR __builtin_amdgcn_s_barrier()
; #define PG8_SCHED __builtin_amdgcn_sched_barrier(0)
; template <class Epi, class Sched, bool HM = false>
; __device__ __forceinline__ void gemm_phase(PG8_LAS unsigned char* lds, const Gemm g, const Sched& S, const Epi& E) {
;     ...
;             PG8_LDB(B0, 1, 0); PG8_LDB(B1, 1, 1); PG8_SCHED; PG8_LDA(At, 1, 0); if (hasx) PG8_LDX(pb, 1); PG8_STAGE(PG8_SA(0, 1), a2 + hstepA, voffA);
;             PG8_WAIT_V(9); PG8_WAIT_L(0); PG8_BAR; PG8_MMA(0, 0, At, B0); PG8_MMA(0, 1, At, B1); if (hasx) PG8_MMAX(); PG8_BAR; PG8_SCHED;
.LBB0_591:
	s_add_u32 s8, s8, 0x80000
	s_addc_u32 s9, s9, 0
	s_mov_b32 s20, m0
	s_mov_b32 m0, s19
	s_nop 0
	global_load_lds_dwordx4 v225, s[8:9]
	s_mov_b32 m0, s20
	s_nop 0
	s_mov_b32 s20, m0
	s_mov_b32 m0, s28
	s_nop 0
	global_load_lds_dwordx4 v227, s[8:9]
	s_mov_b32 m0, s20
	s_waitcnt vmcnt(9)
	s_waitcnt lgkmcnt(0)
	s_barrier
	s_waitcnt lgkmcnt(7)
	v_mfma_f32_16x16x32_bf16 v[146:149], v[166:169], v[206:209], v[146:149]
	v_mfma_f32_16x16x32_bf16 v[142:145], v[174:177], v[206:209], v[142:145]
	s_waitcnt lgkmcnt(5)
	v_mfma_f32_16x16x32_bf16 v[130:133], v[166:169], v[198:201], v[130:133]
	v_mfma_f32_16x16x32_bf16 v[126:129], v[174:177], v[198:201], v[126:129]
	s_waitcnt lgkmcnt(3)
	v_mfma_f32_16x16x32_bf16 v[114:117], v[166:169], v[190:193], v[114:117]
	v_mfma_f32_16x16x32_bf16 v[110:113], v[174:177], v[190:193], v[110:113]
	s_waitcnt lgkmcnt(1)
	v_mfma_f32_16x16x32_bf16 v[98:101], v[166:169], v[182:185], v[98:101]
	v_mfma_f32_16x16x32_bf16 v[94:97], v[174:177], v[182:185], v[94:97]
	v_mfma_f32_16x16x32_bf16 v[146:149], v[170:173], v[210:213], v[146:149]
	v_mfma_f32_16x16x32_bf16 v[142:145], v[178:181], v[210:213], v[142:145]
	v_mfma_f32_16x16x32_bf16 v[130:133], v[170:173], v[202:205], v[130:133]
	v_mfma_f32_16x16x32_bf16 v[126:129], v[178:181], v[202:205], v[126:129]
	v_mfma_f32_16x16x32_bf16 v[114:117], v[170:173], v[194:197], v[114:117]
	v_mfma_f32_16x16x32_bf16 v[110:113], v[178:181], v[194:197], v[110:113]
	s_waitcnt lgkmcnt(0)
	v_mfma_f32_16x16x32_bf16 v[98:101], v[170:173], v[186:189], v[98:101]
	v_mfma_f32_16x16x32_bf16 v[94:97], v[178:181], v[186:189], v[94:97]
	v_mfma_f32_16x16x32_bf16 v[138:141], v[150:153], v[206:209], v[138:141]
	v_mfma_f32_16x16x32_bf16 v[134:137], v[158:161], v[206:209], v[134:137]
	v_mfma_f32_16x16x32_bf16 v[122:125], v[150:153], v[198:201], v[122:125]
	v_mfma_f32_16x16x32_bf16 v[118:121], v[158:161], v[198:201], v[118:121]
	v_mfma_f32_16x16x32_bf16 v[106:109], v[150:153], v[190:193], v[106:109]
	v_mfma_f32_16x16x32_bf16 v[102:105], v[158:161], v[190:193], v[102:105]
	v_mfma_f32_16x16x32_bf16 v[90:93], v[150:153], v[182:185], v[90:93]
	v_mfma_f32_16x16x32_bf16 v[86:89], v[158:161], v[182:185], v[86:89]
	v_mfma_f32_16x16x32_bf16 v[138:141], v[154:157], v[210:213], v[138:141]
	v_mfma_f32_16x16x32_bf16 v[134:137], v[162:165], v[210:213], v[134:137]
	v_mfma_f32_16x16x32_bf16 v[122:125], v[154:157], v[202:205], v[122:125]
	v_mfma_f32_16x16x32_bf16 v[118:121], v[162:165], v[202:205], v[118:121]
	v_mfma_f32_16x16x32_bf16 v[106:109], v[154:157], v[194:197], v[106:109]
	v_mfma_f32_16x16x32_bf16 v[102:105], v[162:165], v[194:197], v[102:105]
	v_mfma_f32_16x16x32_bf16 v[90:93], v[154:157], v[186:189], v[90:93]
	v_mfma_f32_16x16x32_bf16 v[86:89], v[162:165], v[186:189], v[86:89]
	s_and_b64 vcc, exec, s[40:41]
	s_cbranch_vccnz .LBB0_580
	s_and_b64 vcc, exec, s[42:43]
	s_cbranch_vccnz .LBB0_594
	v_mfma_f32_16x16x32_bf16 v[18:21], v[174:177], v[6:9], v[18:21]
	v_mfma_f32_16x16x32_bf16 v[14:17], v[158:161], v[6:9], v[14:17]
	v_mfma_f32_16x16x32_bf16 v[18:21], v[178:181], v[10:13], v[18:21]
	v_mfma_f32_16x16x32_bf16 v[14:17], v[162:165], v[10:13], v[14:17]
	s_branch .LBB0_579

; #define PG8_WAIT_V(n) asm volatile("s_waitcnt vmcnt(" #n ")" ::: "memory")
; #define PG8_BAR __builtin_amdgcn_s_barrier()
; template <class Epi, class Sched, bool HM = false>
; __device__ __forceinline__ void gemm_phase(PG8_LAS unsigned char* lds, const Gemm g, const Sched& S, const Epi& E) {
;     ...
;     PG8_WAIT_V(0);
;     PG8_BAR;
.LBB0_615:
	s_waitcnt vmcnt(0)
	s_setprio 0
	v_readlane_b32 s30, v252, 46
	v_readlane_b32 s96, v255, 5
	v_readlane_b32 s28, v252, 50
	v_readlane_b32 s36, v255, 21
	v_readlane_b32 s88, v255, 23
	v_readlane_b32 s58, v255, 25
	v_readlane_b32 s31, v252, 47
	v_readlane_b32 s97, v255, 6
	v_readlane_b32 s29, v252, 51
	v_readlane_b32 s83, v255, 7
	v_readlane_b32 s37, v255, 22
	v_readlane_b32 s89, v255, 24
	v_readlane_b32 s59, v255, 26
	s_barrier

; #define PG8_STAGE(bufoff, gbase, voff) do { _Pragma("unroll") for (int _i = 0; _i < 2; ++_i) glds16_s((voff)[_i], (const void*)(gbase), ldsbase + (unsigned)((bufoff) + _i * 8192) + ldsw); } while (0)
; template <class Epi, class Sched, bool HM = false>
; __device__ __forceinline__ void gemm_phase(PG8_LAS unsigned char* lds, const Gemm g, const Sched& S, const Epi& E) {
;     ...
;     const int tid = tid_, wid = __builtin_amdgcn_readfirstlane(tid >> 6), lane = tid & 63, wr = wid >> 2, wc = wid & 3, fr = lane & 15, fq = lane >> 4;
;     const int K = g.K, nt = K / BK;
;     unsigned voffA[2], voffB[2];
; #pragma unroll
;     for (int i = 0; i < 2; ++i) { int R, C; stage_rc(tid * 16 + i * 8192, R, C); const int Rb = Epi::PERM ? ((R & ~31) + perm32(R & 31)) : R;
;         voffA[i] = (unsigned)(R * g.lda + C) * 2u; voffB[i] = (unsigned)(Rb * g.ldb + C) * 2u; }
;     const unsigned voffX = (unsigned)((4 * (wid & 3) + (lane >> 4)) * g.lda + 8 * (lane & 15)) * 2u;
;     const size_t kstep = (size_t)(BK * 2);
;     const size_t hstepA = (size_t)HALF * g.lda * 2, hstepB = (size_t)HALF * g.ldb * 2;
;     const size_t tstepA = (size_t)(HM ? HALF : g.pms) * g.lda * 2, tstepB = 2 * hstepB, xstep = 2 * hstepA; const bool hasx = g.pms != BM;
;     const unsigned ldsw = (unsigned)wid * 1024u, ldsx = (unsigned)(wid & 3) * 1024u;
;     const unsigned ldsbase = (unsigned)__builtin_amdgcn_readfirstlane((int)(unsigned)(__UINTPTR_TYPE__)lds);
;     const int aoff = lds_byte(wr * 64 + fr, fq * 8), boff = lds_byte(wc * 32 + fr, fq * 8);
;     const int xoff = XOFF + fr * 256 + fq * 16;
;     ...
;     Unit cur, nxt; int ui = 0;
;     if (!S.next(0, cur)) return;
;     f32x4 acc[2][2][4][2]; f32x4 accx[2];
; #pragma unroll
;     for (int a = 0; a < 2; ++a)
; #pragma unroll
;         for (int b = 0; b < 2; ++b)
; #pragma unroll
;             for (int m = 0; m < 4; ++m)
; #pragma unroll
;                 for (int n = 0; n < 2; ++n) acc[a][b][m][n] = (f32x4){0.f, 0.f, 0.f, 0.f};
;     accx[0] = (f32x4){0.f, 0.f, 0.f, 0.f}; accx[1] = accx[0];
;     bf16x8 At[4][2], B0[2][2], B1[2][2], Ax[2];
;     const char* cA = PG8_APTR(cur); const char* cB = PG8_BPTR(cur);
;     S.a_ready(cur);
;     PG8_STAGE(PG8_SB(0, 0), cB, voffB); PG8_STAGE(PG8_SB(0, 1), cB + hstepB, voffB); PG8_STAGE(PG8_SA(0, 0), cA, voffA); PG8_STAGEX(0, cA + xstep); PG8_STAGE(PG8_SA(0, 1), cA + hstepA, voffA);
;     if (wr == 1) PG8_BAR;
.LBB0_968:
	s_mov_b64 s[0:1], s[30:31]
	s_mov_b64 s[4:5], s[30:31]
	s_mov_b64 s[8:9], s[30:31]
	v_mov_b32_e32 v4, v0
	s_andn2_b64 vcc, exec, s[96:97]
	v_readfirstlane_b32 s20, v4
	s_cbranch_vccnz .LBB0_967
	v_bfe_i32 v7, v4, 27, 1
	v_lshlrev_b32_e32 v5, 4, v4
	v_lshrrev_b32_e32 v7, 22, v7
	v_add_u32_e32 v7, v5, v7
	v_and_b32_e32 v7, 0xfffffc00, v7
	v_sub_u32_e32 v7, v5, v7
	v_ashrrev_i32_e32 v6, 31, v4
	v_lshrrev_b32_e32 v8, 4, v7
	v_lshrrev_b32_e32 v6, 26, v6
	v_bitop3_b32 v7, v8, v7, 32 bitop3:0x6c
	s_add_u32 s14, s0, 0x1a1e4000
	v_add_u32_e32 v6, v4, v6
	v_ashrrev_i32_e32 v9, 31, v7
	s_addc_u32 s15, s1, 0
	v_ashrrev_i32_e32 v6, 6, v6
	v_lshrrev_b32_e32 v9, 26, v9
	s_add_u32 s0, s4, s12
	v_lshlrev_b32_e32 v8, 3, v6
	v_add_u32_e32 v9, v7, v9
	s_addc_u32 s1, s5, 0
	v_and_b32_e32 v8, -16, v8
	v_ashrrev_i32_e32 v10, 6, v9
	v_and_b32_e32 v9, 0xc0, v9
	s_add_u32 s16, s0, 0x32a0000
	v_add_u32_e32 v8, v10, v8
	v_sub_u32_e32 v7, v7, v9
	s_addc_u32 s17, s1, 0
	v_lshlrev_b32_e32 v6, 5, v6
	v_ashrrev_i16_sdwa v7, v1, sext(v7) dst_sel:DWORD dst_unused:UNUSED_PAD src0_sel:DWORD src1_sel:BYTE_0
	v_lshlrev_b32_e32 v9, 1, v8
	v_lshrrev_b32_e32 v11, 2, v8
	v_and_b32_e32 v10, 3, v10
	s_mov_b32 s1, 0xfffe0
	v_and_b32_e32 v6, 32, v6
	v_bfe_i32 v7, v7, 0, 16
	v_and_b32_e32 v9, 24, v9
	v_and_b32_e32 v11, 4, v11
	v_and_or_b32 v10, v8, s1, v10
	v_or3_b32 v9, v10, v11, v9
	v_add_lshl_u32 v6, v6, v7, 1
	v_add_u32_e32 v5, 0x2000, v5
	v_lshl_add_u32 v225, v8, 12, v6
	v_lshl_add_u32 v226, v9, 12, v6
	v_ashrrev_i32_e32 v6, 31, v5
	v_lshrrev_b32_e32 v6, 22, v6
	v_add_u32_e32 v6, v5, v6
	v_ashrrev_i32_e32 v6, 10, v6
	v_mul_i32_i24_e32 v7, 0x400, v6
	v_sub_u32_e32 v5, v5, v7
	v_lshrrev_b32_e32 v7, 4, v5
	v_bitop3_b32 v5, v7, v5, 32 bitop3:0x6c
	v_ashrrev_i32_e32 v8, 31, v5
	v_lshrrev_b32_e32 v8, 26, v8
	v_lshlrev_b32_e32 v7, 3, v6
	v_add_u32_e32 v8, v5, v8
	s_ashr_i32 s0, s20, 6
	v_and_b32_e32 v7, -16, v7
	v_ashrrev_i32_e32 v9, 6, v8
	v_and_b32_e32 v8, 0xc0, v8
	s_and_b32 s21, s0, 3
	v_add_u32_e32 v7, v9, v7
	v_sub_u32_e32 v5, v5, v8
	v_and_b32_e32 v9, 3, v9
	v_lshlrev_b32_e32 v6, 5, v6
	v_ashrrev_i16_sdwa v5, v1, sext(v5) dst_sel:DWORD dst_unused:UNUSED_PAD src0_sel:DWORD src1_sel:BYTE_0
	v_lshlrev_b32_e32 v8, 1, v7
	v_lshrrev_b32_e32 v10, 2, v7
	v_and_or_b32 v9, v7, s1, v9
	s_ashr_i32 s22, s20, 8
	s_lshl_b32 s1, s21, 14
	s_lshl_b32 s0, s0, 10
	s_lshl_b32 s23, s21, 10
	v_readlane_b32 s4, v254, 41
	v_and_b32_e32 v6, 32, v6
	v_bfe_i32 v5, v5, 0, 16
	v_and_b32_e32 v8, 24, v8
	v_and_b32_e32 v10, 4, v10
	v_readlane_b32 s5, v254, 42
	s_add_u32 s4, s16, s4
	v_bfe_u32 v2, v4, 4, 2
	v_or3_b32 v8, v9, v10, v8
	v_add_lshl_u32 v5, v6, v5, 1
	v_and_b32_e32 v4, 15, v4
	s_addc_u32 s5, s17, s5
	s_add_i32 s18, s0, 0
	v_lshl_add_u32 v227, v7, 12, v5
	v_lshl_add_u32 v228, v8, 12, v5
	v_lshlrev_b32_e32 v5, 4, v4
	v_lshlrev_b32_e32 v6, 12, v2
	s_add_i32 s19, s18, 0x10000
	s_mov_b32 s0, m0
	s_mov_b32 m0, s19
	s_nop 0
	global_load_lds_dwordx4 v226, s[4:5]
	s_mov_b32 m0, s0
	v_or3_b32 v229, s1, v6, v5
	v_lshrrev_b32_e32 v232, 8, v229
	v_and_b32_e32 v232, 0xf0, v232
	v_xor_b32_e32 v229, v229, v232
	s_add_i32 s24, s18, 0x12000
	s_mov_b32 s0, m0
	s_mov_b32 m0, s24
	s_nop 0
	global_load_lds_dwordx4 v228, s[4:5]
	s_mov_b32 m0, s0
	v_readlane_b32 s1, v254, 23
	s_mul_i32 s0, s1, s10
	s_add_u32 s6, s14, s0
	s_mul_hi_i32 s0, s1, s10
	s_addc_u32 s7, s15, s0
	s_add_u32 s0, s4, 0x80000
	s_addc_u32 s1, s5, 0
	s_add_i32 s25, s18, 0x14000
	s_mov_b32 s27, m0
	s_mov_b32 m0, s25
	s_nop 0
	global_load_lds_dwordx4 v226, s[0:1]
	s_mov_b32 m0, s27
	s_add_i32 s28, s18, 0x16000
	s_mov_b32 s27, m0
	s_mov_b32 m0, s28
	s_nop 0
	global_load_lds_dwordx4 v228, s[0:1]
	s_mov_b32 m0, s27
	v_readlane_b32 s0, v254, 38
	v_readlane_b32 s1, v254, 39
	s_add_u32 s6, s6, s0
	s_addc_u32 s7, s7, s1
	s_mov_b32 s0, m0
	s_mov_b32 m0, s18
	s_nop 0
	global_load_lds_dwordx4 v225, s[6:7]
	s_mov_b32 m0, s0
	s_add_i32 s29, s18, 0x2000
	s_mov_b32 s0, m0
	s_mov_b32 m0, s29
	s_nop 0
	global_load_lds_dwordx4 v227, s[6:7]
	s_mov_b32 m0, s0
	s_add_u32 s0, s6, 0x100000
	s_addc_u32 s1, s7, 0
	s_add_i32 s30, s23, 0
	s_add_i32 s23, s30, 0x20400
	s_mov_b32 s27, m0
	s_mov_b32 m0, s23
	s_nop 0
	global_load_lds_dwordx4 v229, s[0:1]
	s_mov_b32 m0, s27
	s_add_u32 s0, s6, 0x80000
	s_addc_u32 s1, s7, 0
	s_add_i32 s31, s18, 0x4000
	s_mov_b32 s23, m0
	s_mov_b32 m0, s31
	s_nop 0
	global_load_lds_dwordx4 v225, s[0:1]
	s_mov_b32 m0, s23
	s_add_i32 s36, s18, 0x6000
	s_mov_b32 s23, m0
	s_mov_b32 m0, s36
	s_nop 0
	global_load_lds_dwordx4 v227, s[0:1]
	s_mov_b32 m0, s23
	s_cmp_eq_u32 s22, 1
	s_cselect_b64 s[0:1], -1, 0
	s_cmp_lg_u32 s22, 1
	s_cbranch_scc1 .LBB0_971
	s_setprio 1
	s_barrier

; #define PG8_STAGE(bufoff, gbase, voff) do { _Pragma("unroll") for (int _i = 0; _i < 2; ++_i) glds16_s((voff)[_i], (const void*)(gbase), ldsbase + (unsigned)((bufoff) + _i * 8192) + ldsw); } while (0)
; #define PG8_LDA(dst, b, h) do { _Pragma("unroll") for (int m = 0; m < 4; ++m) _Pragma("unroll") for (int k = 0; k < 2; ++k) dst[m][k] = *(const PG8_LAS bf16x8*)(lds + PG8_SA(b, h) + aoff + m * 2048 + k * 1024); } while (0)
; #define PG8_MMA(ai, bj, At, Bt) do { __builtin_amdgcn_s_setprio(1); _Pragma("unroll") for (int m = 0; m < 4; ++m) _Pragma("unroll") for (int n = 0; n < 2; ++n) _Pragma("unroll") for (int k = 0; k < 2; ++k) \
;         acc[ai][bj][m][n] = __builtin_amdgcn_mfma_f32_16x16x32_bf16(Bt[n][k], At[m][k], acc[ai][bj][m][n], 0, 0, 0); __builtin_amdgcn_s_setprio(0); } while (0)
; #define PG8_WAIT_V(n) asm volatile("s_waitcnt vmcnt(" #n ")" ::: "memory")
; #define PG8_WAIT_L(n) asm volatile("s_waitcnt lgkmcnt(" #n ")" ::: "memory")
; #define PG8_BAR __builtin_amdgcn_s_barrier()
; #define PG8_SCHED __builtin_amdgcn_sched_barrier(0)
; template <class Epi, class Sched, bool HM = false>
; __device__ __forceinline__ void gemm_phase(PG8_LAS unsigned char* lds, const Gemm g, const Sched& S, const Epi& E) {
;     ...
;             if (!HM) PG8_LDA(At, 1, 1); PG8_STAGE(PG8_SB(1, 0), b3, voffB); PG8_STAGE(PG8_SB(1, 1), b3 + hstepB, voffB); PG8_STAGE(PG8_SA(1, 0), a3, voffA);
;             PG8_WAIT_V(8); PG8_WAIT_L(0); PG8_BAR; if (!HM) { PG8_MMA(1, 0, At, B0); PG8_MMA(1, 1, At, B1); } PG8_BAR; PG8_SCHED;
;         }
.LBB0_985:
.LBB0_986:
	s_barrier
	ds_read_b128 v[182:185], v235 offset:49152
	ds_read_b128 v[186:189], v235 offset:50176
	ds_read_b128 v[190:193], v235 offset:51200
	ds_read_b128 v[194:197], v235 offset:52224
	ds_read_b128 v[198:201], v235 offset:53248
	ds_read_b128 v[202:205], v235 offset:54272
	ds_read_b128 v[206:209], v235 offset:55296
	ds_read_b128 v[210:213], v235 offset:56320
	s_mov_b32 s8, m0
	s_mov_b32 m0, s37
	s_nop 0
	global_load_lds_dwordx4 v226, s[6:7]
	s_mov_b32 m0, s8
	s_nop 0
	s_mov_b32 s8, m0
	s_mov_b32 m0, s51
	s_nop 0
	global_load_lds_dwordx4 v228, s[6:7]
	s_mov_b32 m0, s8
	s_add_u32 s6, s6, 0x80000
	s_addc_u32 s7, s7, 0
	s_mov_b32 s8, m0
	s_mov_b32 m0, s57
	s_nop 0
	global_load_lds_dwordx4 v226, s[6:7]
	s_mov_b32 m0, s8
	s_nop 0
	s_mov_b32 s8, m0
	s_mov_b32 m0, s58
	s_nop 0
	global_load_lds_dwordx4 v228, s[6:7]
	s_mov_b32 m0, s8
	s_mov_b32 s6, m0
	s_mov_b32 m0, s52
	s_nop 0
	global_load_lds_dwordx4 v225, s[4:5]
	s_mov_b32 m0, s6
	s_nop 0
	s_mov_b32 s6, m0
	s_mov_b32 m0, s56
	s_nop 0
	global_load_lds_dwordx4 v227, s[4:5]
	s_mov_b32 m0, s6
	s_waitcnt vmcnt(8)
	s_waitcnt lgkmcnt(0)
	s_barrier
	s_waitcnt lgkmcnt(7)
	v_mfma_f32_16x16x32_bf16 v[82:85], v[166:169], v[182:185], v[82:85]
	v_mfma_f32_16x16x32_bf16 v[78:81], v[174:177], v[182:185], v[78:81]
	s_waitcnt lgkmcnt(5)
	v_mfma_f32_16x16x32_bf16 v[74:77], v[166:169], v[190:193], v[74:77]
	v_mfma_f32_16x16x32_bf16 v[66:69], v[174:177], v[190:193], v[66:69]
	s_waitcnt lgkmcnt(3)
	v_mfma_f32_16x16x32_bf16 v[58:61], v[166:169], v[198:201], v[58:61]
	v_mfma_f32_16x16x32_bf16 v[50:53], v[174:177], v[198:201], v[50:53]
	s_waitcnt lgkmcnt(1)
	v_mfma_f32_16x16x32_bf16 v[42:45], v[166:169], v[206:209], v[42:45]
	v_mfma_f32_16x16x32_bf16 v[34:37], v[174:177], v[206:209], v[34:37]
	v_mfma_f32_16x16x32_bf16 v[82:85], v[170:173], v[186:189], v[82:85]
	v_mfma_f32_16x16x32_bf16 v[78:81], v[178:181], v[186:189], v[78:81]
	v_mfma_f32_16x16x32_bf16 v[74:77], v[170:173], v[194:197], v[74:77]
	v_mfma_f32_16x16x32_bf16 v[66:69], v[178:181], v[194:197], v[66:69]
	v_mfma_f32_16x16x32_bf16 v[58:61], v[170:173], v[202:205], v[58:61]
	v_mfma_f32_16x16x32_bf16 v[50:53], v[178:181], v[202:205], v[50:53]
	s_waitcnt lgkmcnt(0)
	v_mfma_f32_16x16x32_bf16 v[42:45], v[170:173], v[210:213], v[42:45]
	v_mfma_f32_16x16x32_bf16 v[34:37], v[178:181], v[210:213], v[34:37]
	v_mfma_f32_16x16x32_bf16 v[70:73], v[150:153], v[182:185], v[70:73]
	v_mfma_f32_16x16x32_bf16 v[62:65], v[158:161], v[182:185], v[62:65]
	v_mfma_f32_16x16x32_bf16 v[54:57], v[150:153], v[190:193], v[54:57]
	v_mfma_f32_16x16x32_bf16 v[46:49], v[158:161], v[190:193], v[46:49]
	v_mfma_f32_16x16x32_bf16 v[38:41], v[150:153], v[198:201], v[38:41]
	v_mfma_f32_16x16x32_bf16 v[30:33], v[158:161], v[198:201], v[30:33]
	v_mfma_f32_16x16x32_bf16 v[26:29], v[150:153], v[206:209], v[26:29]
	v_mfma_f32_16x16x32_bf16 v[22:25], v[158:161], v[206:209], v[22:25]
	v_mfma_f32_16x16x32_bf16 v[70:73], v[154:157], v[186:189], v[70:73]
	v_mfma_f32_16x16x32_bf16 v[62:65], v[162:165], v[186:189], v[62:65]
	v_mfma_f32_16x16x32_bf16 v[54:57], v[154:157], v[194:197], v[54:57]
	v_mfma_f32_16x16x32_bf16 v[46:49], v[162:165], v[194:197], v[46:49]
	v_mfma_f32_16x16x32_bf16 v[38:41], v[154:157], v[202:205], v[38:41]
	v_mfma_f32_16x16x32_bf16 v[30:33], v[162:165], v[202:205], v[30:33]
	v_mfma_f32_16x16x32_bf16 v[26:29], v[154:157], v[210:213], v[26:29]
	v_mfma_f32_16x16x32_bf16 v[22:25], v[162:165], v[210:213], v[22:25]
	s_barrier
	s_add_i32 s23, s23, 2
	s_addk_i32 s22, 0x1000
	s_add_u32 s89, s89, 0x100
	s_addc_u32 s90, s90, 0
	s_add_u32 s27, s27, 0x100
	s_addc_u32 s82, s82, 0
	s_cmp_gt_u32 s23, 29
	s_cbranch_scc1 .LBB0_1002

; #define PG8_STAGE(bufoff, gbase, voff) do { _Pragma("unroll") for (int _i = 0; _i < 2; ++_i) glds16_s((voff)[_i], (const void*)(gbase), ldsbase + (unsigned)((bufoff) + _i * 8192) + ldsw); } while (0)
; #define PG8_STAGEX(pb, gbase) glds16_s(voffX, (const void*)(gbase), ldsbase + (unsigned)(XOFF + (pb) * 4096) + ldsx)
; #define PG8_LDA(dst, b, h) do { _Pragma("unroll") for (int m = 0; m < 4; ++m) _Pragma("unroll") for (int k = 0; k < 2; ++k) dst[m][k] = *(const PG8_LAS bf16x8*)(lds + PG8_SA(b, h) + aoff + m * 2048 + k * 1024); } while (0)
; #define PG8_LDB(dst, b, h) do { _Pragma("unroll") for (int n = 0; n < 2; ++n) _Pragma("unroll") for (int k = 0; k < 2; ++k) dst[n][k] = *(const PG8_LAS bf16x8*)(lds + PG8_SB(b, h) + boff + n * 2048 + k * 1024); } while (0)
; #define PG8_LDX(pb, tp) do { _Pragma("unroll") for (int k = 0; k < 2; ++k) Ax[k] = *(const PG8_LAS bf16x8*)(lds + xoff + (pb) * 4096 + (tp) * 128 + k * 64); } while (0)
; #define PG8_MMA(ai, bj, At, Bt) do { __builtin_amdgcn_s_setprio(1); _Pragma("unroll") for (int m = 0; m < 4; ++m) _Pragma("unroll") for (int n = 0; n < 2; ++n) _Pragma("unroll") for (int k = 0; k < 2; ++k) \
;         acc[ai][bj][m][n] = __builtin_amdgcn_mfma_f32_16x16x32_bf16(Bt[n][k], At[m][k], acc[ai][bj][m][n], 0, 0, 0); __builtin_amdgcn_s_setprio(0); } while (0)
; #define PG8_WAIT_V(n) asm volatile("s_waitcnt vmcnt(" #n ")" ::: "memory")
; #define PG8_WAIT_L(n) asm volatile("s_waitcnt lgkmcnt(" #n ")" ::: "memory")
; #define PG8_BAR __builtin_amdgcn_s_barrier()
; #define PG8_SCHED __builtin_amdgcn_sched_barrier(0)
; template <class Epi, class Sched, bool HM = false>
; __device__ __forceinline__ void gemm_phase(PG8_LAS unsigned char* lds, const Gemm g, const Sched& S, const Epi& E) {
;     ...
;             PG8_LDB(B0, 0, 0); PG8_LDB(B1, 0, 1); PG8_SCHED; PG8_LDA(At, 0, 0); if (hasx) PG8_LDX(pb, 0); PG8_STAGE(PG8_SA(1, 1), a1 + hstepA, voffA); PG8_STAGEX(pb ^ 1, a2 + xstep);
;             PG8_WAIT_V(9); PG8_WAIT_L(0); PG8_BAR; PG8_MMA(0, 0, At, B0); PG8_MMA(0, 1, At, B1); if (hasx) PG8_MMAX(); PG8_BAR; PG8_SCHED;
.LBB0_989:
	s_add_u32 s42, s42, 0x80000
	s_addc_u32 s43, s43, 0
	s_mov_b32 s21, m0
	s_mov_b32 m0, s59
	s_nop 0
	global_load_lds_dwordx4 v225, s[42:43]
	s_mov_b32 m0, s21
	s_nop 0
	s_mov_b32 s21, m0
	s_mov_b32 m0, s83
	s_nop 0
	global_load_lds_dwordx4 v227, s[42:43]
	s_mov_b32 m0, s21
	s_add_u32 s42, s8, 0x100000
	s_addc_u32 s43, s9, 0
	s_xor_b32 s20, s20, 0x21400
	s_add_i32 s20, s30, s20
	s_mov_b32 s21, m0
	s_mov_b32 m0, s20
	s_nop 0
	global_load_lds_dwordx4 v229, s[42:43]
	s_mov_b32 m0, s21
	s_waitcnt vmcnt(9)
	s_waitcnt lgkmcnt(0)
	s_barrier
	s_waitcnt lgkmcnt(7)
	v_mfma_f32_16x16x32_bf16 v[146:149], v[166:169], v[206:209], v[146:149]
	v_mfma_f32_16x16x32_bf16 v[142:145], v[174:177], v[206:209], v[142:145]
	s_waitcnt lgkmcnt(5)
	v_mfma_f32_16x16x32_bf16 v[138:141], v[166:169], v[198:201], v[138:141]
	v_mfma_f32_16x16x32_bf16 v[130:133], v[174:177], v[198:201], v[130:133]
	s_waitcnt lgkmcnt(3)
	v_mfma_f32_16x16x32_bf16 v[122:125], v[166:169], v[190:193], v[122:125]
	v_mfma_f32_16x16x32_bf16 v[114:117], v[174:177], v[190:193], v[114:117]
	s_waitcnt lgkmcnt(1)
	v_mfma_f32_16x16x32_bf16 v[106:109], v[166:169], v[182:185], v[106:109]
	v_mfma_f32_16x16x32_bf16 v[98:101], v[174:177], v[182:185], v[98:101]
	v_mfma_f32_16x16x32_bf16 v[146:149], v[170:173], v[210:213], v[146:149]
	v_mfma_f32_16x16x32_bf16 v[142:145], v[178:181], v[210:213], v[142:145]
	v_mfma_f32_16x16x32_bf16 v[138:141], v[170:173], v[202:205], v[138:141]
	v_mfma_f32_16x16x32_bf16 v[130:133], v[178:181], v[202:205], v[130:133]
	v_mfma_f32_16x16x32_bf16 v[122:125], v[170:173], v[194:197], v[122:125]
	v_mfma_f32_16x16x32_bf16 v[114:117], v[178:181], v[194:197], v[114:117]
	s_waitcnt lgkmcnt(0)
	v_mfma_f32_16x16x32_bf16 v[106:109], v[170:173], v[186:189], v[106:109]
	v_mfma_f32_16x16x32_bf16 v[98:101], v[178:181], v[186:189], v[98:101]
	v_mfma_f32_16x16x32_bf16 v[134:137], v[150:153], v[206:209], v[134:137]
	v_mfma_f32_16x16x32_bf16 v[126:129], v[158:161], v[206:209], v[126:129]
	v_mfma_f32_16x16x32_bf16 v[118:121], v[150:153], v[198:201], v[118:121]
	v_mfma_f32_16x16x32_bf16 v[110:113], v[158:161], v[198:201], v[110:113]
	v_mfma_f32_16x16x32_bf16 v[102:105], v[150:153], v[190:193], v[102:105]
	v_mfma_f32_16x16x32_bf16 v[94:97], v[158:161], v[190:193], v[94:97]
	v_mfma_f32_16x16x32_bf16 v[90:93], v[150:153], v[182:185], v[90:93]
	v_mfma_f32_16x16x32_bf16 v[86:89], v[158:161], v[182:185], v[86:89]
	v_mfma_f32_16x16x32_bf16 v[134:137], v[154:157], v[210:213], v[134:137]
	v_mfma_f32_16x16x32_bf16 v[126:129], v[162:165], v[210:213], v[126:129]
	v_mfma_f32_16x16x32_bf16 v[118:121], v[154:157], v[202:205], v[118:121]
	v_mfma_f32_16x16x32_bf16 v[110:113], v[162:165], v[202:205], v[110:113]
	v_mfma_f32_16x16x32_bf16 v[102:105], v[154:157], v[194:197], v[102:105]
	v_mfma_f32_16x16x32_bf16 v[94:97], v[162:165], v[194:197], v[94:97]
	v_mfma_f32_16x16x32_bf16 v[90:93], v[154:157], v[186:189], v[90:93]
	v_mfma_f32_16x16x32_bf16 v[86:89], v[162:165], v[186:189], v[86:89]
	s_andn2_b64 s[42:43], exec, s[62:63]
	s_and_b64 vcc, exec, s[40:41]
	s_cbranch_vccnz .LBB0_995
	s_and_b64 vcc, exec, s[42:43]
	s_cbranch_vccnz .LBB0_992
	v_mfma_f32_16x16x32_bf16 v[18:21], v[174:177], v[6:9], v[18:21]
	v_mfma_f32_16x16x32_bf16 v[14:17], v[158:161], v[6:9], v[14:17]
	v_mfma_f32_16x16x32_bf16 v[18:21], v[178:181], v[10:13], v[18:21]
	v_mfma_f32_16x16x32_bf16 v[14:17], v[162:165], v[10:13], v[14:17]
	s_branch .LBB0_995

; #define PG8_STAGE(bufoff, gbase, voff) do { _Pragma("unroll") for (int _i = 0; _i < 2; ++_i) glds16_s((voff)[_i], (const void*)(gbase), ldsbase + (unsigned)((bufoff) + _i * 8192) + ldsw); } while (0)
; #define PG8_LDA(dst, b, h) do { _Pragma("unroll") for (int m = 0; m < 4; ++m) _Pragma("unroll") for (int k = 0; k < 2; ++k) dst[m][k] = *(const PG8_LAS bf16x8*)(lds + PG8_SA(b, h) + aoff + m * 2048 + k * 1024); } while (0)
; #define PG8_LDB(dst, b, h) do { _Pragma("unroll") for (int n = 0; n < 2; ++n) _Pragma("unroll") for (int k = 0; k < 2; ++k) dst[n][k] = *(const PG8_LAS bf16x8*)(lds + PG8_SB(b, h) + boff + n * 2048 + k * 1024); } while (0)
; #define PG8_LDX(pb, tp) do { _Pragma("unroll") for (int k = 0; k < 2; ++k) Ax[k] = *(const PG8_LAS bf16x8*)(lds + xoff + (pb) * 4096 + (tp) * 128 + k * 64); } while (0)
; #define PG8_MMA(ai, bj, At, Bt) do { __builtin_amdgcn_s_setprio(1); _Pragma("unroll") for (int m = 0; m < 4; ++m) _Pragma("unroll") for (int n = 0; n < 2; ++n) _Pragma("unroll") for (int k = 0; k < 2; ++k) \
;         acc[ai][bj][m][n] = __builtin_amdgcn_mfma_f32_16x16x32_bf16(Bt[n][k], At[m][k], acc[ai][bj][m][n], 0, 0, 0); __builtin_amdgcn_s_setprio(0); } while (0)
; #define PG8_WAIT_V(n) asm volatile("s_waitcnt vmcnt(" #n ")" ::: "memory")
; #define PG8_WAIT_L(n) asm volatile("s_waitcnt lgkmcnt(" #n ")" ::: "memory")
; #define PG8_BAR __builtin_amdgcn_s_barrier()
; #define PG8_SCHED __builtin_amdgcn_sched_barrier(0)
; template <class Epi, class Sched, bool HM = false>
; __device__ __forceinline__ void gemm_phase(PG8_LAS unsigned char* lds, const Gemm g, const Sched& S, const Epi& E) {
;     ...
;             PG8_WAIT_V(9); PG8_WAIT_L(0); PG8_BAR; PG8_MMA(0, 0, At, B0); PG8_MMA(0, 1, At, B1); if (hasx) PG8_MMAX(); PG8_BAR; PG8_SCHED;
;             if (!HM) PG8_LDA(At, 0, 1); PG8_STAGE(PG8_SB(0, 0), b2, voffB); PG8_STAGE(PG8_SB(0, 1), b2 + hstepB, voffB); PG8_STAGE(PG8_SA(0, 0), a2, voffA);
;             PG8_WAIT_V(9); PG8_WAIT_L(0); PG8_BAR; if (!HM) { PG8_MMA(1, 0, At, B0); PG8_MMA(1, 1, At, B1); } PG8_BAR; PG8_SCHED;
;             PG8_LDB(B0, 1, 0); PG8_LDB(B1, 1, 1); PG8_SCHED; PG8_LDA(At, 1, 0); if (hasx) PG8_LDX(pb, 1); PG8_STAGE(PG8_SA(0, 1), a2 + hstepA, voffA);
.LBB0_994:
.LBB0_995:
	s_barrier
	ds_read_b128 v[182:185], v235 offset:16384
	ds_read_b128 v[186:189], v235 offset:17408
	ds_read_b128 v[190:193], v235 offset:18432
	ds_read_b128 v[194:197], v235 offset:19456
	ds_read_b128 v[198:201], v235 offset:20480
	ds_read_b128 v[202:205], v235 offset:21504
	ds_read_b128 v[206:209], v235 offset:22528
	ds_read_b128 v[210:213], v235 offset:23552
	s_mov_b32 s20, m0
	s_mov_b32 m0, s19
	s_nop 0
	global_load_lds_dwordx4 v226, s[34:35]
	s_mov_b32 m0, s20
	s_nop 0
	s_mov_b32 s20, m0
	s_mov_b32 m0, s24
	s_nop 0
	global_load_lds_dwordx4 v228, s[34:35]
	s_mov_b32 m0, s20
	s_add_u32 s20, s34, 0x80000
	s_addc_u32 s21, s35, 0
	s_mov_b32 s34, m0
	s_mov_b32 m0, s25
	s_nop 0
	global_load_lds_dwordx4 v226, s[20:21]
	s_mov_b32 m0, s34
	s_nop 0
	s_mov_b32 s34, m0
	s_mov_b32 m0, s28
	s_nop 0
	global_load_lds_dwordx4 v228, s[20:21]
	s_mov_b32 m0, s34
	s_mov_b32 s20, m0
	s_mov_b32 m0, s18
	s_nop 0
	global_load_lds_dwordx4 v225, s[8:9]
	s_mov_b32 m0, s20
	s_nop 0
	s_mov_b32 s20, m0
	s_mov_b32 m0, s29
	s_nop 0
	global_load_lds_dwordx4 v227, s[8:9]
	s_mov_b32 m0, s20
	s_waitcnt vmcnt(9)
	s_waitcnt lgkmcnt(0)
	s_barrier
	s_waitcnt lgkmcnt(7)
	v_mfma_f32_16x16x32_bf16 v[82:85], v[166:169], v[182:185], v[82:85]
	v_mfma_f32_16x16x32_bf16 v[78:81], v[174:177], v[182:185], v[78:81]
	s_waitcnt lgkmcnt(5)
	v_mfma_f32_16x16x32_bf16 v[74:77], v[166:169], v[190:193], v[74:77]
	v_mfma_f32_16x16x32_bf16 v[66:69], v[174:177], v[190:193], v[66:69]
	s_waitcnt lgkmcnt(3)
	v_mfma_f32_16x16x32_bf16 v[58:61], v[166:169], v[198:201], v[58:61]
	v_mfma_f32_16x16x32_bf16 v[50:53], v[174:177], v[198:201], v[50:53]
	s_waitcnt lgkmcnt(1)
	v_mfma_f32_16x16x32_bf16 v[42:45], v[166:169], v[206:209], v[42:45]
	v_mfma_f32_16x16x32_bf16 v[34:37], v[174:177], v[206:209], v[34:37]
	v_mfma_f32_16x16x32_bf16 v[82:85], v[170:173], v[186:189], v[82:85]
	v_mfma_f32_16x16x32_bf16 v[78:81], v[178:181], v[186:189], v[78:81]
	v_mfma_f32_16x16x32_bf16 v[74:77], v[170:173], v[194:197], v[74:77]
	v_mfma_f32_16x16x32_bf16 v[66:69], v[178:181], v[194:197], v[66:69]
	v_mfma_f32_16x16x32_bf16 v[58:61], v[170:173], v[202:205], v[58:61]
	v_mfma_f32_16x16x32_bf16 v[50:53], v[178:181], v[202:205], v[50:53]
	s_waitcnt lgkmcnt(0)
	v_mfma_f32_16x16x32_bf16 v[42:45], v[170:173], v[210:213], v[42:45]
	v_mfma_f32_16x16x32_bf16 v[34:37], v[178:181], v[210:213], v[34:37]
	v_mfma_f32_16x16x32_bf16 v[70:73], v[150:153], v[182:185], v[70:73]
	v_mfma_f32_16x16x32_bf16 v[62:65], v[158:161], v[182:185], v[62:65]
	v_mfma_f32_16x16x32_bf16 v[54:57], v[150:153], v[190:193], v[54:57]
	v_mfma_f32_16x16x32_bf16 v[46:49], v[158:161], v[190:193], v[46:49]
	v_mfma_f32_16x16x32_bf16 v[38:41], v[150:153], v[198:201], v[38:41]
	v_mfma_f32_16x16x32_bf16 v[30:33], v[158:161], v[198:201], v[30:33]
	v_mfma_f32_16x16x32_bf16 v[26:29], v[150:153], v[206:209], v[26:29]
	v_mfma_f32_16x16x32_bf16 v[22:25], v[158:161], v[206:209], v[22:25]
	v_mfma_f32_16x16x32_bf16 v[70:73], v[154:157], v[186:189], v[70:73]
	v_mfma_f32_16x16x32_bf16 v[62:65], v[162:165], v[186:189], v[62:65]
	v_mfma_f32_16x16x32_bf16 v[54:57], v[154:157], v[194:197], v[54:57]
	v_mfma_f32_16x16x32_bf16 v[46:49], v[162:165], v[194:197], v[46:49]
	v_mfma_f32_16x16x32_bf16 v[38:41], v[154:157], v[202:205], v[38:41]
	v_mfma_f32_16x16x32_bf16 v[30:33], v[162:165], v[202:205], v[30:33]
	v_mfma_f32_16x16x32_bf16 v[26:29], v[154:157], v[210:213], v[26:29]
	v_mfma_f32_16x16x32_bf16 v[22:25], v[162:165], v[210:213], v[22:25]
	s_barrier
	v_add_u32_e32 v4, 0x18000, v234
	ds_read_b128 v[166:169], v4
	ds_read_b128 v[170:173], v4 offset:1024
	ds_read_b128 v[174:177], v4 offset:2048
	ds_read_b128 v[178:181], v4 offset:3072
	v_add_u32_e32 v4, 0x1c000, v234
	ds_read_b128 v[150:153], v4
	ds_read_b128 v[154:157], v4 offset:1024
	ds_read_b128 v[158:161], v4 offset:2048
	ds_read_b128 v[162:165], v4 offset:3072
	ds_read_b128 v[206:209], v235 offset:32768
	ds_read_b128 v[210:213], v235 offset:33792
	ds_read_b128 v[198:201], v235 offset:34816
	ds_read_b128 v[202:205], v235 offset:35840
	ds_read_b128 v[190:193], v235 offset:36864
	ds_read_b128 v[194:197], v235 offset:37888
	ds_read_b128 v[182:185], v235 offset:38912
	ds_read_b128 v[186:189], v235 offset:39936
	s_and_b64 vcc, exec, s[40:41]
	s_cbranch_vccnz .LBB0_997
	v_xor_b32_e32 v6, 0x80, v2
	ds_read_b128 v[6:9], v6
	v_xor_b32_e32 v10, 0xc0, v2
	ds_read_b128 v[10:13], v10
; #define PG8_STAGE(bufoff, gbase, voff) do { _Pragma("unroll") for (int _i = 0; _i < 2; ++_i) glds16_s((voff)[_i], (const void*)(gbase), ldsbase + (unsigned)((bufoff) + _i * 8192) + ldsw); } while (0)
; #define PG8_LDA(dst, b, h) do { _Pragma("unroll") for (int m = 0; m < 4; ++m) _Pragma("unroll") for (int k = 0; k < 2; ++k) dst[m][k] = *(const PG8_LAS bf16x8*)(lds + PG8_SA(b, h) + aoff + m * 2048 + k * 1024); } while (0)
; #define PG8_LDB(dst, b, h) do { _Pragma("unroll") for (int n = 0; n < 2; ++n) _Pragma("unroll") for (int k = 0; k < 2; ++k) dst[n][k] = *(const PG8_LAS bf16x8*)(lds + PG8_SB(b, h) + boff + n * 2048 + k * 1024); } while (0)
; #define PG8_LDX(pb, tp) do { _Pragma("unroll") for (int k = 0; k < 2; ++k) Ax[k] = *(const PG8_LAS bf16x8*)(lds + xoff + (pb) * 4096 + (tp) * 128 + k * 64); } while (0)
; #define PG8_MMA(ai, bj, At, Bt) do { __builtin_amdgcn_s_setprio(1); _Pragma("unroll") for (int m = 0; m < 4; ++m) _Pragma("unroll") for (int n = 0; n < 2; ++n) _Pragma("unroll") for (int k = 0; k < 2; ++k) \
;         acc[ai][bj][m][n] = __builtin_amdgcn_mfma_f32_16x16x32_bf16(Bt[n][k], At[m][k], acc[ai][bj][m][n], 0, 0, 0); __builtin_amdgcn_s_setprio(0); } while (0)
; #define PG8_WAIT_V(n) asm volatile("s_waitcnt vmcnt(" #n ")" ::: "memory")
; #define PG8_WAIT_L(n) asm volatile("s_waitcnt lgkmcnt(" #n ")" ::: "memory")
; #define PG8_BAR __builtin_amdgcn_s_barrier()
; #define PG8_SCHED __builtin_amdgcn_sched_barrier(0)
; template <class Epi, class Sched, bool HM = false>
; __device__ __forceinline__ void gemm_phase(PG8_LAS unsigned char* lds, const Gemm g, const Sched& S, const Epi& E) {
;     ...
;             PG8_LDB(B0, 1, 0); PG8_LDB(B1, 1, 1); PG8_SCHED; PG8_LDA(At, 1, 0); if (hasx) PG8_LDX(pb, 1); PG8_STAGE(PG8_SA(0, 1), a2 + hstepA, voffA);
;             PG8_WAIT_V(9); PG8_WAIT_L(0); PG8_BAR; PG8_MMA(0, 0, At, B0); PG8_MMA(0, 1, At, B1); if (hasx) PG8_MMAX(); PG8_BAR; PG8_SCHED;
.LBB0_997:
	s_add_u32 s8, s8, 0x80000
	s_addc_u32 s9, s9, 0
	s_mov_b32 s20, m0
	s_mov_b32 m0, s31
	s_nop 0
	global_load_lds_dwordx4 v225, s[8:9]
	s_mov_b32 m0, s20
	s_nop 0
	s_mov_b32 s20, m0
	s_mov_b32 m0, s36
	s_nop 0
	global_load_lds_dwordx4 v227, s[8:9]
	s_mov_b32 m0, s20
	s_waitcnt vmcnt(9)
	s_waitcnt lgkmcnt(0)
	s_barrier
	s_waitcnt lgkmcnt(7)
	v_mfma_f32_16x16x32_bf16 v[146:149], v[166:169], v[206:209], v[146:149]
	v_mfma_f32_16x16x32_bf16 v[142:145], v[174:177], v[206:209], v[142:145]
	s_waitcnt lgkmcnt(5)
	v_mfma_f32_16x16x32_bf16 v[138:141], v[166:169], v[198:201], v[138:141]
	v_mfma_f32_16x16x32_bf16 v[130:133], v[174:177], v[198:201], v[130:133]
	s_waitcnt lgkmcnt(3)
	v_mfma_f32_16x16x32_bf16 v[122:125], v[166:169], v[190:193], v[122:125]
	v_mfma_f32_16x16x32_bf16 v[114:117], v[174:177], v[190:193], v[114:117]
	s_waitcnt lgkmcnt(1)
	v_mfma_f32_16x16x32_bf16 v[106:109], v[166:169], v[182:185], v[106:109]
	v_mfma_f32_16x16x32_bf16 v[98:101], v[174:177], v[182:185], v[98:101]
	v_mfma_f32_16x16x32_bf16 v[146:149], v[170:173], v[210:213], v[146:149]
	v_mfma_f32_16x16x32_bf16 v[142:145], v[178:181], v[210:213], v[142:145]
	v_mfma_f32_16x16x32_bf16 v[138:141], v[170:173], v[202:205], v[138:141]
	v_mfma_f32_16x16x32_bf16 v[130:133], v[178:181], v[202:205], v[130:133]
	v_mfma_f32_16x16x32_bf16 v[122:125], v[170:173], v[194:197], v[122:125]
	v_mfma_f32_16x16x32_bf16 v[114:117], v[178:181], v[194:197], v[114:117]
	s_waitcnt lgkmcnt(0)
	v_mfma_f32_16x16x32_bf16 v[106:109], v[170:173], v[186:189], v[106:109]
	v_mfma_f32_16x16x32_bf16 v[98:101], v[178:181], v[186:189], v[98:101]
	v_mfma_f32_16x16x32_bf16 v[134:137], v[150:153], v[206:209], v[134:137]
	v_mfma_f32_16x16x32_bf16 v[126:129], v[158:161], v[206:209], v[126:129]
	v_mfma_f32_16x16x32_bf16 v[118:121], v[150:153], v[198:201], v[118:121]
	v_mfma_f32_16x16x32_bf16 v[110:113], v[158:161], v[198:201], v[110:113]
	v_mfma_f32_16x16x32_bf16 v[102:105], v[150:153], v[190:193], v[102:105]
	v_mfma_f32_16x16x32_bf16 v[94:97], v[158:161], v[190:193], v[94:97]
	v_mfma_f32_16x16x32_bf16 v[90:93], v[150:153], v[182:185], v[90:93]
	v_mfma_f32_16x16x32_bf16 v[86:89], v[158:161], v[182:185], v[86:89]
	v_mfma_f32_16x16x32_bf16 v[134:137], v[154:157], v[210:213], v[134:137]
	v_mfma_f32_16x16x32_bf16 v[126:129], v[162:165], v[210:213], v[126:129]
	v_mfma_f32_16x16x32_bf16 v[118:121], v[154:157], v[202:205], v[118:121]
	v_mfma_f32_16x16x32_bf16 v[110:113], v[162:165], v[202:205], v[110:113]
	v_mfma_f32_16x16x32_bf16 v[102:105], v[154:157], v[194:197], v[102:105]
	v_mfma_f32_16x16x32_bf16 v[94:97], v[162:165], v[194:197], v[94:97]
	v_mfma_f32_16x16x32_bf16 v[90:93], v[154:157], v[186:189], v[90:93]
	v_mfma_f32_16x16x32_bf16 v[86:89], v[162:165], v[186:189], v[86:89]
	s_and_b64 vcc, exec, s[40:41]
	s_cbranch_vccnz .LBB0_986
	s_and_b64 vcc, exec, s[42:43]
	s_cbranch_vccnz .LBB0_1000
	v_mfma_f32_16x16x32_bf16 v[18:21], v[174:177], v[6:9], v[18:21]
	v_mfma_f32_16x16x32_bf16 v[14:17], v[158:161], v[6:9], v[14:17]
	v_mfma_f32_16x16x32_bf16 v[18:21], v[178:181], v[10:13], v[18:21]
	v_mfma_f32_16x16x32_bf16 v[14:17], v[162:165], v[10:13], v[14:17]
	s_branch .LBB0_985

; #define PG8_WAIT_V(n) asm volatile("s_waitcnt vmcnt(" #n ")" ::: "memory")
; #define PG8_BAR __builtin_amdgcn_s_barrier()
; template <class Epi, class Sched, bool HM = false>
; __device__ __forceinline__ void gemm_phase(PG8_LAS unsigned char* lds, const Gemm g, const Sched& S, const Epi& E) {
;     ...
;     PG8_WAIT_V(0);
;     PG8_BAR;
.LBB0_1147:
	s_waitcnt vmcnt(0)
	s_setprio 0
	v_readlane_b32 s30, v252, 46
	v_readlane_b32 s28, v252, 50
	v_readlane_b32 s31, v252, 47
	v_readlane_b32 s29, v252, 51
	s_barrier

; #define PG8_STAGE(bufoff, gbase, voff) do { _Pragma("unroll") for (int _i = 0; _i < 2; ++_i) glds16_s((voff)[_i], (const void*)(gbase), ldsbase + (unsigned)((bufoff) + _i * 8192) + ldsw); } while (0)
; template <class Epi, class Sched, bool HM = false>
; __device__ __forceinline__ void gemm_phase(PG8_LAS unsigned char* lds, const Gemm g, const Sched& S, const Epi& E) {
;     ...
;     const int tid = tid_, wid = __builtin_amdgcn_readfirstlane(tid >> 6), lane = tid & 63, wr = wid >> 2, wc = wid & 3, fr = lane & 15, fq = lane >> 4;
;     const int K = g.K, nt = K / BK;
;     unsigned voffA[2], voffB[2];
; #pragma unroll
;     for (int i = 0; i < 2; ++i) { int R, C; stage_rc(tid * 16 + i * 8192, R, C); const int Rb = Epi::PERM ? ((R & ~31) + perm32(R & 31)) : R;
;         voffA[i] = (unsigned)(R * g.lda + C) * 2u; voffB[i] = (unsigned)(Rb * g.ldb + C) * 2u; }
;     const unsigned voffX = (unsigned)((4 * (wid & 3) + (lane >> 4)) * g.lda + 8 * (lane & 15)) * 2u;
;     const size_t kstep = (size_t)(BK * 2);
;     const size_t hstepA = (size_t)HALF * g.lda * 2, hstepB = (size_t)HALF * g.ldb * 2;
;     const size_t tstepA = (size_t)(HM ? HALF : g.pms) * g.lda * 2, tstepB = 2 * hstepB, xstep = 2 * hstepA; const bool hasx = g.pms != BM;
;     const unsigned ldsw = (unsigned)wid * 1024u, ldsx = (unsigned)(wid & 3) * 1024u;
;     const unsigned ldsbase = (unsigned)__builtin_amdgcn_readfirstlane((int)(unsigned)(__UINTPTR_TYPE__)lds);
;     const int aoff = lds_byte(wr * 64 + fr, fq * 8), boff = lds_byte(wc * 32 + fr, fq * 8);
;     const int xoff = XOFF + fr * 256 + fq * 16;
;     ...
;     Unit cur, nxt; int ui = 0;
;     if (!S.next(0, cur)) return;
;     f32x4 acc[2][2][4][2]; f32x4 accx[2];
; #pragma unroll
;     for (int a = 0; a < 2; ++a)
; #pragma unroll
;         for (int b = 0; b < 2; ++b)
; #pragma unroll
;             for (int m = 0; m < 4; ++m)
; #pragma unroll
;                 for (int n = 0; n < 2; ++n) acc[a][b][m][n] = (f32x4){0.f, 0.f, 0.f, 0.f};
;     accx[0] = (f32x4){0.f, 0.f, 0.f, 0.f}; accx[1] = accx[0];
;     bf16x8 At[4][2], B0[2][2], B1[2][2], Ax[2];
;     const char* cA = PG8_APTR(cur); const char* cB = PG8_BPTR(cur);
;     S.a_ready(cur);
;     PG8_STAGE(PG8_SB(0, 0), cB, voffB); PG8_STAGE(PG8_SB(0, 1), cB + hstepB, voffB); PG8_STAGE(PG8_SA(0, 0), cA, voffA); PG8_STAGEX(0, cA + xstep); PG8_STAGE(PG8_SA(0, 1), cA + hstepA, voffA);
;     if (wr == 1) PG8_BAR;
.LBB0_1149:
	s_mov_b64 s[0:1], s[30:31]
	s_mov_b64 s[4:5], s[30:31]
	s_mov_b64 s[6:7], s[30:31]
	v_mov_b32_e32 v5, v0
	s_andn2_b64 vcc, exec, s[70:71]
	v_readfirstlane_b32 s8, v5
	s_cbranch_vccnz .LBB0_1169
	v_bfe_i32 v6, v5, 27, 1
	v_lshlrev_b32_e32 v4, 4, v5
	v_lshrrev_b32_e32 v6, 22, v6
	v_add_u32_e32 v6, v4, v6
	v_and_b32_e32 v6, 0xfffffc00, v6
	v_sub_u32_e32 v6, v4, v6
	v_ashrrev_i32_e32 v2, 31, v5
	v_lshrrev_b32_e32 v7, 4, v6
	v_lshrrev_b32_e32 v2, 26, v2
	v_bitop3_b32 v6, v7, v6, 32 bitop3:0x6c
	s_add_u32 s34, s0, 0x1a1e4000
	v_add_u32_e32 v2, v5, v2
	v_ashrrev_i32_e32 v8, 31, v6
	s_addc_u32 s35, s1, 0
	v_readlane_b32 s0, v255, 25
	v_ashrrev_i32_e32 v2, 6, v2
	v_lshrrev_b32_e32 v8, 26, v8
	s_add_u32 s0, s4, s0
	v_lshlrev_b32_e32 v7, 3, v2
	v_add_u32_e32 v8, v6, v8
	s_addc_u32 s1, s5, s89
	v_and_b32_e32 v7, -16, v7
	v_ashrrev_i32_e32 v9, 6, v8
	v_and_b32_e32 v8, 0xc0, v8
	s_add_u32 s43, s0, 0x52a0000
	v_add_u32_e32 v7, v9, v7
	v_sub_u32_e32 v6, v6, v8
	s_addc_u32 s46, s1, 0
	v_lshlrev_b32_e32 v2, 5, v2
	v_ashrrev_i16_sdwa v6, v1, sext(v6) dst_sel:DWORD dst_unused:UNUSED_PAD src0_sel:DWORD src1_sel:BYTE_0
	v_lshlrev_b32_e32 v8, 1, v7
	v_lshrrev_b32_e32 v10, 2, v7
	v_and_b32_e32 v9, 3, v9
	s_mov_b32 s1, 0xfffe0
	v_and_b32_e32 v2, 32, v2
	v_bfe_i32 v6, v6, 0, 16
	v_and_b32_e32 v8, 24, v8
	v_and_b32_e32 v10, 4, v10
	v_and_or_b32 v9, v7, s1, v9
	v_or3_b32 v8, v9, v10, v8
	v_add_lshl_u32 v6, v2, v6, 1
	v_add_u32_e32 v4, 0x2000, v4
	v_lshl_add_u32 v2, v7, 12, v6
	v_lshl_add_u32 v134, v8, 12, v6
	v_ashrrev_i32_e32 v6, 31, v4
	v_lshrrev_b32_e32 v6, 22, v6
	v_add_u32_e32 v6, v4, v6
	v_ashrrev_i32_e32 v6, 10, v6
	v_mul_i32_i24_e32 v7, 0x400, v6
	v_sub_u32_e32 v4, v4, v7
	v_lshrrev_b32_e32 v7, 4, v4
	v_bitop3_b32 v4, v7, v4, 32 bitop3:0x6c
	v_ashrrev_i32_e32 v8, 31, v4
	v_lshrrev_b32_e32 v8, 26, v8
	v_lshlrev_b32_e32 v7, 3, v6
	v_add_u32_e32 v8, v4, v8
	v_and_b32_e32 v7, -16, v7
	v_ashrrev_i32_e32 v9, 6, v8
	v_and_b32_e32 v8, 0xc0, v8
	v_add_u32_e32 v7, v9, v7
	v_sub_u32_e32 v4, v4, v8
	v_lshlrev_b32_e32 v6, 5, v6
	v_ashrrev_i16_sdwa v4, v1, sext(v4) dst_sel:DWORD dst_unused:UNUSED_PAD src0_sel:DWORD src1_sel:BYTE_0
	v_lshlrev_b32_e32 v8, 1, v7
	v_lshrrev_b32_e32 v10, 2, v7
	v_and_b32_e32 v9, 3, v9
	v_and_b32_e32 v6, 32, v6
	v_bfe_i32 v4, v4, 0, 16
	v_and_b32_e32 v8, 24, v8
	v_and_b32_e32 v10, 4, v10
	v_and_or_b32 v9, v7, s1, v9
	s_ashr_i32 s0, s8, 6
	v_or3_b32 v8, v9, v10, v8
	v_add_lshl_u32 v4, v6, v4, 1
	s_and_b32 s9, s0, 3
	v_lshl_add_u32 v135, v7, 12, v4
	v_lshl_add_u32 v136, v8, 12, v4
	v_and_b32_e32 v4, 15, v5
	v_bfe_u32 v5, v5, 4, 2
	s_lshl_b32 s1, s9, 14
	v_lshlrev_b32_e32 v6, 12, v5
	v_lshlrev_b32_e32 v7, 4, v4
	s_ashr_i32 s12, s8, 8
	v_or3_b32 v137, s1, v6, v7
	s_lshl_b32 s4, s0, 10
	s_lshl_b32 s13, s9, 10
	s_mov_b64 s[0:1], s[68:69]
	s_add_u32 s0, s43, s0
	s_addc_u32 s1, s46, s1
	s_add_i32 s47, s4, 0
	s_add_i32 s90, s47, 0x10000
	s_mov_b32 s4, m0
	s_mov_b32 m0, s90
	s_nop 0
	global_load_lds_dwordx4 v134, s[0:1]
	s_mov_b32 m0, s4
	s_add_i32 s91, s47, 0x12000
	s_mov_b32 s4, m0
	s_mov_b32 m0, s91
	s_nop 0
	global_load_lds_dwordx4 v136, s[0:1]
	s_mov_b32 m0, s4
	s_nop 0
	v_readlane_b32 s4, v255, 23
	v_readlane_b32 s5, v255, 24
	s_add_u32 s14, s34, s4
	s_addc_u32 s15, s35, s5
	s_add_u32 s4, s0, 0x80000
	s_addc_u32 s5, s1, 0
	s_add_i32 s92, s47, 0x14000
	s_mov_b32 s16, m0
	s_mov_b32 m0, s92
	s_nop 0
	global_load_lds_dwordx4 v134, s[4:5]
	s_mov_b32 m0, s16
	s_add_i32 s20, s47, 0x16000
	s_mov_b32 s16, m0
	s_mov_b32 m0, s20
	s_nop 0
	global_load_lds_dwordx4 v136, s[4:5]
	s_mov_b32 m0, s16
	s_mov_b64 s[4:5], s[66:67]
	s_add_u32 s4, s14, s4
	s_addc_u32 s5, s15, s5
	s_mov_b32 s14, m0
	s_mov_b32 m0, s47
	s_nop 0
	global_load_lds_dwordx4 v2, s[4:5]
	s_mov_b32 m0, s14
	s_add_i32 s21, s47, 0x2000
	s_mov_b32 s14, m0
	s_mov_b32 m0, s21
	s_nop 0
	global_load_lds_dwordx4 v135, s[4:5]
	s_mov_b32 m0, s14
	s_add_u32 s14, s4, 0x100000
	s_addc_u32 s15, s5, 0
	s_add_i32 s97, s13, 0
	s_add_i32 s13, s97, 0x20400
	s_mov_b32 s16, m0
	s_mov_b32 m0, s13
	s_nop 0
	global_load_lds_dwordx4 v137, s[14:15]
	s_mov_b32 m0, s16
	s_add_u32 s14, s4, 0x80000
	s_addc_u32 s15, s5, 0
	s_add_i32 s42, s47, 0x4000
	s_mov_b32 s13, m0
	s_mov_b32 m0, s42
	s_nop 0
	global_load_lds_dwordx4 v2, s[14:15]
	s_mov_b32 m0, s13
	s_add_i32 s40, s47, 0x6000
	s_mov_b32 s13, m0
	s_mov_b32 m0, s40
	s_nop 0
	global_load_lds_dwordx4 v135, s[14:15]
	s_mov_b32 m0, s13
	s_cmp_eq_u32 s12, 1
	s_cselect_b64 s[62:63], -1, 0
	s_cmp_lg_u32 s12, 1
	s_cbranch_scc1 .LBB0_1152
	s_setprio 1
	s_barrier

; #define PG8_STAGE(bufoff, gbase, voff) do { _Pragma("unroll") for (int _i = 0; _i < 2; ++_i) glds16_s((voff)[_i], (const void*)(gbase), ldsbase + (unsigned)((bufoff) + _i * 8192) + ldsw); } while (0)
; #define PG8_STAGEX(pb, gbase) glds16_s(voffX, (const void*)(gbase), ldsbase + (unsigned)(XOFF + (pb) * 4096) + ldsx)
; #define PG8_LDA(dst, b, h) do { _Pragma("unroll") for (int m = 0; m < 4; ++m) _Pragma("unroll") for (int k = 0; k < 2; ++k) dst[m][k] = *(const PG8_LAS bf16x8*)(lds + PG8_SA(b, h) + aoff + m * 2048 + k * 1024); } while (0)
; #define PG8_LDB(dst, b, h) do { _Pragma("unroll") for (int n = 0; n < 2; ++n) _Pragma("unroll") for (int k = 0; k < 2; ++k) dst[n][k] = *(const PG8_LAS bf16x8*)(lds + PG8_SB(b, h) + boff + n * 2048 + k * 1024); } while (0)
; #define PG8_LDX(pb, tp) do { _Pragma("unroll") for (int k = 0; k < 2; ++k) Ax[k] = *(const PG8_LAS bf16x8*)(lds + xoff + (pb) * 4096 + (tp) * 128 + k * 64); } while (0)
; #define PG8_WAIT_V(n) asm volatile("s_waitcnt vmcnt(" #n ")" ::: "memory")
; #define PG8_WAIT_L(n) asm volatile("s_waitcnt lgkmcnt(" #n ")" ::: "memory")
; template <class Epi, class Sched, bool HM = false>
; __device__ __forceinline__ void gemm_phase(PG8_LAS unsigned char* lds, const Gemm g, const Sched& S, const Epi& E) {
;     ...
;             const bool last = (t == nt - 2);
;             const char* a1 = cA + (size_t)(t + 1) * kstep;
;             const char* a2 = last ? nA : cA + (size_t)(t + 2) * kstep; const char* b2 = last ? nB : cB + (size_t)(t + 2) * kstep;
;             const char* a3 = a2 + kstep; const char* b3 = b2 + kstep;
;             asm volatile("; uniform bases" : "+s"(a1), "+s"(a2), "+s"(a3), "+s"(b2), "+s"(b3));
;             if (last && has_next) S.a_ready(nxt);
;             const int pb = (t >> 1) & 1;
;             PG8_LDB(B0, 0, 0); PG8_LDB(B1, 0, 1); PG8_SCHED; PG8_LDA(At, 0, 0); if (hasx) PG8_LDX(pb, 0); PG8_STAGE(PG8_SA(1, 1), a1 + hstepA, voffA); PG8_STAGEX(pb ^ 1, a2 + xstep);
;             PG8_WAIT_V(9); PG8_WAIT_L(0); PG8_BAR; PG8_MMA(0, 0, At, B0); PG8_MMA(0, 1, At, B1); if (hasx) PG8_MMAX(); PG8_BAR; PG8_SCHED;
;             if (!HM) PG8_LDA(At, 0, 1); PG8_STAGE(PG8_SB(0, 0), b2, voffB); PG8_STAGE(PG8_SB(0, 1), b2 + hstepB, voffB); PG8_STAGE(PG8_SA(0, 0), a2, voffA);
;             PG8_WAIT_V(9); PG8_WAIT_L(0); PG8_BAR; if (!HM) { PG8_MMA(1, 0, At, B0); PG8_MMA(1, 1, At, B1); } PG8_BAR; PG8_SCHED;
.LBB0_1162:
	s_add_u32 s24, s17, 0xffffff80
	s_addc_u32 s25, s18, -1
	s_cmp_eq_u32 s19, 28
	s_cselect_b32 s6, s38, s17
	s_cselect_b32 s7, s39, s18
	s_cselect_b32 s9, s85, s16
	s_cselect_b32 s8, s84, s15
	s_add_u32 s0, s6, 0x80
	s_addc_u32 s1, s7, 0
	s_add_u32 s4, s8, 0x80
	s_addc_u32 s5, s9, 0
	v_add_u32_e32 v132, 0x10000, v140
	ds_read_b128 v[142:145], v132
	ds_read_b128 v[146:149], v132 offset:1024
	ds_read_b128 v[150:153], v132 offset:2048
	ds_read_b128 v[154:157], v132 offset:3072
	v_add_u32_e32 v132, 0x14000, v140
	ds_read_b128 v[158:161], v132
	s_waitcnt lgkmcnt(5)
	ds_read_b128 v[162:165], v132 offset:1024
	ds_read_b128 v[166:169], v132 offset:2048
	ds_read_b128 v[170:173], v132 offset:3072
	ds_read_b128 v[174:177], v141
	ds_read_b128 v[178:181], v141 offset:1024
	ds_read_b128 v[182:185], v141 offset:2048
	ds_read_b128 v[186:189], v141 offset:3072
	ds_read_b128 v[190:193], v141 offset:4096
	ds_read_b128 v[194:197], v141 offset:5120
	ds_read_b128 v[198:201], v141 offset:6144
	ds_read_b128 v[202:205], v141 offset:7168
	s_add_u32 s24, s24, 0x80000
	s_addc_u32 s25, s25, 0
	s_mov_b32 s23, m0
	s_mov_b32 m0, s61
	s_nop 0
	global_load_lds_dwordx4 v2, s[24:25]
	s_mov_b32 m0, s23
	s_nop 0
	s_mov_b32 s23, m0
	s_mov_b32 m0, s83
	s_nop 0
	global_load_lds_dwordx4 v135, s[24:25]
	s_mov_b32 m0, s23
	s_add_u32 s24, s6, 0x100000
	s_addc_u32 s25, s7, 0
	s_and_b32 s23, s22, 0x1000
	s_xor_b32 s23, s23, 0x21400
	s_add_i32 s23, s97, s23
	s_mov_b32 s27, m0
	s_mov_b32 m0, s23
	s_nop 0
	global_load_lds_dwordx4 v137, s[24:25]
	s_mov_b32 m0, s27
	s_waitcnt vmcnt(9)
	s_waitcnt lgkmcnt(0)
	s_barrier
	s_waitcnt lgkmcnt(7)
	v_mfma_f32_16x16x32_bf16 v[128:131], v[142:145], v[174:177], v[128:131]
	v_mfma_f32_16x16x32_bf16 v[120:123], v[150:153], v[174:177], v[120:123]
	s_waitcnt lgkmcnt(5)
	v_mfma_f32_16x16x32_bf16 v[112:115], v[142:145], v[182:185], v[112:115]
	v_mfma_f32_16x16x32_bf16 v[104:107], v[150:153], v[182:185], v[104:107]
	s_waitcnt lgkmcnt(3)
	v_mfma_f32_16x16x32_bf16 v[96:99], v[142:145], v[190:193], v[96:99]
	v_mfma_f32_16x16x32_bf16 v[88:91], v[150:153], v[190:193], v[88:91]
	s_waitcnt lgkmcnt(1)
	v_mfma_f32_16x16x32_bf16 v[80:83], v[142:145], v[198:201], v[80:83]
	v_mfma_f32_16x16x32_bf16 v[72:75], v[150:153], v[198:201], v[72:75]
	v_mfma_f32_16x16x32_bf16 v[128:131], v[146:149], v[178:181], v[128:131]
	v_mfma_f32_16x16x32_bf16 v[120:123], v[154:157], v[178:181], v[120:123]
	v_mfma_f32_16x16x32_bf16 v[112:115], v[146:149], v[186:189], v[112:115]
	v_mfma_f32_16x16x32_bf16 v[104:107], v[154:157], v[186:189], v[104:107]
	v_mfma_f32_16x16x32_bf16 v[96:99], v[146:149], v[194:197], v[96:99]
	v_mfma_f32_16x16x32_bf16 v[88:91], v[154:157], v[194:197], v[88:91]
	s_waitcnt lgkmcnt(0)
	v_mfma_f32_16x16x32_bf16 v[80:83], v[146:149], v[202:205], v[80:83]
	v_mfma_f32_16x16x32_bf16 v[72:75], v[154:157], v[202:205], v[72:75]
	v_mfma_f32_16x16x32_bf16 v[124:127], v[158:161], v[174:177], v[124:127]
	v_mfma_f32_16x16x32_bf16 v[116:119], v[166:169], v[174:177], v[116:119]
	v_mfma_f32_16x16x32_bf16 v[108:111], v[158:161], v[182:185], v[108:111]
	v_mfma_f32_16x16x32_bf16 v[100:103], v[166:169], v[182:185], v[100:103]
	v_mfma_f32_16x16x32_bf16 v[92:95], v[158:161], v[190:193], v[92:95]
	v_mfma_f32_16x16x32_bf16 v[84:87], v[166:169], v[190:193], v[84:87]
	v_mfma_f32_16x16x32_bf16 v[76:79], v[158:161], v[198:201], v[76:79]
	v_mfma_f32_16x16x32_bf16 v[68:71], v[166:169], v[198:201], v[68:71]
	v_mfma_f32_16x16x32_bf16 v[124:127], v[162:165], v[178:181], v[124:127]
	v_mfma_f32_16x16x32_bf16 v[116:119], v[170:173], v[178:181], v[116:119]
	v_mfma_f32_16x16x32_bf16 v[108:111], v[162:165], v[186:189], v[108:111]
	v_mfma_f32_16x16x32_bf16 v[100:103], v[170:173], v[186:189], v[100:103]
	v_mfma_f32_16x16x32_bf16 v[92:95], v[162:165], v[194:197], v[92:95]
	v_mfma_f32_16x16x32_bf16 v[84:87], v[170:173], v[194:197], v[84:87]
	v_mfma_f32_16x16x32_bf16 v[76:79], v[162:165], v[202:205], v[76:79]
	v_mfma_f32_16x16x32_bf16 v[68:71], v[170:173], v[202:205], v[68:71]
	s_barrier
	ds_read_b128 v[174:177], v141 offset:16384
	ds_read_b128 v[178:181], v141 offset:17408
	ds_read_b128 v[182:185], v141 offset:18432
	ds_read_b128 v[186:189], v141 offset:19456
	ds_read_b128 v[190:193], v141 offset:20480
	ds_read_b128 v[194:197], v141 offset:21504
	ds_read_b128 v[198:201], v141 offset:22528
	ds_read_b128 v[202:205], v141 offset:23552
	s_mov_b32 s23, m0
	s_mov_b32 m0, s90
	s_nop 0
	global_load_lds_dwordx4 v134, s[8:9]
	s_mov_b32 m0, s23
	s_nop 0
	s_mov_b32 s23, m0
	s_mov_b32 m0, s91
	s_nop 0
	global_load_lds_dwordx4 v136, s[8:9]
	s_mov_b32 m0, s23
	s_add_u32 s8, s8, 0x80000
	s_addc_u32 s9, s9, 0
	s_mov_b32 s23, m0
	s_mov_b32 m0, s92
	s_nop 0
	global_load_lds_dwordx4 v134, s[8:9]
	s_mov_b32 m0, s23
	s_nop 0
	s_mov_b32 s23, m0
	s_mov_b32 m0, s20
	s_nop 0
	global_load_lds_dwordx4 v136, s[8:9]
	s_mov_b32 m0, s23
	s_mov_b32 s8, m0
	s_mov_b32 m0, s47
	s_nop 0
	global_load_lds_dwordx4 v2, s[6:7]
	s_mov_b32 m0, s8
	s_nop 0
	s_mov_b32 s8, m0
	s_mov_b32 m0, s21
	s_nop 0
	global_load_lds_dwordx4 v135, s[6:7]
	s_mov_b32 m0, s8
	s_waitcnt vmcnt(9)
	s_waitcnt lgkmcnt(0)
	s_barrier
; #define PG8_STAGE(bufoff, gbase, voff) do { _Pragma("unroll") for (int _i = 0; _i < 2; ++_i) glds16_s((voff)[_i], (const void*)(gbase), ldsbase + (unsigned)((bufoff) + _i * 8192) + ldsw); } while (0)
; #define PG8_LDA(dst, b, h) do { _Pragma("unroll") for (int m = 0; m < 4; ++m) _Pragma("unroll") for (int k = 0; k < 2; ++k) dst[m][k] = *(const PG8_LAS bf16x8*)(lds + PG8_SA(b, h) + aoff + m * 2048 + k * 1024); } while (0)
; #define PG8_LDB(dst, b, h) do { _Pragma("unroll") for (int n = 0; n < 2; ++n) _Pragma("unroll") for (int k = 0; k < 2; ++k) dst[n][k] = *(const PG8_LAS bf16x8*)(lds + PG8_SB(b, h) + boff + n * 2048 + k * 1024); } while (0)
; #define PG8_LDX(pb, tp) do { _Pragma("unroll") for (int k = 0; k < 2; ++k) Ax[k] = *(const PG8_LAS bf16x8*)(lds + xoff + (pb) * 4096 + (tp) * 128 + k * 64); } while (0)
; #define PG8_MMA(ai, bj, At, Bt) do { __builtin_amdgcn_s_setprio(1); _Pragma("unroll") for (int m = 0; m < 4; ++m) _Pragma("unroll") for (int n = 0; n < 2; ++n) _Pragma("unroll") for (int k = 0; k < 2; ++k) \
;         acc[ai][bj][m][n] = __builtin_amdgcn_mfma_f32_16x16x32_bf16(Bt[n][k], At[m][k], acc[ai][bj][m][n], 0, 0, 0); __builtin_amdgcn_s_setprio(0); } while (0)
; #define PG8_WAIT_V(n) asm volatile("s_waitcnt vmcnt(" #n ")" ::: "memory")
; #define PG8_WAIT_L(n) asm volatile("s_waitcnt lgkmcnt(" #n ")" ::: "memory")
; #define PG8_BAR __builtin_amdgcn_s_barrier()
; #define PG8_SCHED __builtin_amdgcn_sched_barrier(0)
; template <class Epi, class Sched, bool HM = false>
; __device__ __forceinline__ void gemm_phase(PG8_LAS unsigned char* lds, const Gemm g, const Sched& S, const Epi& E) {
;     ...
;             PG8_WAIT_V(9); PG8_WAIT_L(0); PG8_BAR; if (!HM) { PG8_MMA(1, 0, At, B0); PG8_MMA(1, 1, At, B1); } PG8_BAR; PG8_SCHED;
;             PG8_LDB(B0, 1, 0); PG8_LDB(B1, 1, 1); PG8_SCHED; PG8_LDA(At, 1, 0); if (hasx) PG8_LDX(pb, 1); PG8_STAGE(PG8_SA(0, 1), a2 + hstepA, voffA);
;             PG8_WAIT_V(9); PG8_WAIT_L(0); PG8_BAR; PG8_MMA(0, 0, At, B0); PG8_MMA(0, 1, At, B1); if (hasx) PG8_MMAX(); PG8_BAR; PG8_SCHED;
	s_waitcnt lgkmcnt(7)
	v_mfma_f32_16x16x32_bf16 v[64:67], v[142:145], v[174:177], v[64:67]
	v_mfma_f32_16x16x32_bf16 v[56:59], v[150:153], v[174:177], v[56:59]
	s_waitcnt lgkmcnt(5)
	v_mfma_f32_16x16x32_bf16 v[48:51], v[142:145], v[182:185], v[48:51]
	v_mfma_f32_16x16x32_bf16 v[40:43], v[150:153], v[182:185], v[40:43]
	s_waitcnt lgkmcnt(3)
	v_mfma_f32_16x16x32_bf16 v[32:35], v[142:145], v[190:193], v[32:35]
	v_mfma_f32_16x16x32_bf16 v[24:27], v[150:153], v[190:193], v[24:27]
	s_waitcnt lgkmcnt(1)
	v_mfma_f32_16x16x32_bf16 v[16:19], v[142:145], v[198:201], v[16:19]
	v_mfma_f32_16x16x32_bf16 v[8:11], v[150:153], v[198:201], v[8:11]
	v_mfma_f32_16x16x32_bf16 v[64:67], v[146:149], v[178:181], v[64:67]
	v_mfma_f32_16x16x32_bf16 v[56:59], v[154:157], v[178:181], v[56:59]
	v_mfma_f32_16x16x32_bf16 v[48:51], v[146:149], v[186:189], v[48:51]
	v_mfma_f32_16x16x32_bf16 v[40:43], v[154:157], v[186:189], v[40:43]
	v_mfma_f32_16x16x32_bf16 v[32:35], v[146:149], v[194:197], v[32:35]
	v_mfma_f32_16x16x32_bf16 v[24:27], v[154:157], v[194:197], v[24:27]
	s_waitcnt lgkmcnt(0)
	v_mfma_f32_16x16x32_bf16 v[16:19], v[146:149], v[202:205], v[16:19]
	v_mfma_f32_16x16x32_bf16 v[8:11], v[154:157], v[202:205], v[8:11]
	v_mfma_f32_16x16x32_bf16 v[60:63], v[158:161], v[174:177], v[60:63]
	v_mfma_f32_16x16x32_bf16 v[52:55], v[166:169], v[174:177], v[52:55]
	v_mfma_f32_16x16x32_bf16 v[44:47], v[158:161], v[182:185], v[44:47]
	v_mfma_f32_16x16x32_bf16 v[36:39], v[166:169], v[182:185], v[36:39]
	v_mfma_f32_16x16x32_bf16 v[28:31], v[158:161], v[190:193], v[28:31]
	v_mfma_f32_16x16x32_bf16 v[20:23], v[166:169], v[190:193], v[20:23]
	v_mfma_f32_16x16x32_bf16 v[12:15], v[158:161], v[198:201], v[12:15]
	v_mfma_f32_16x16x32_bf16 v[4:7], v[166:169], v[198:201], v[4:7]
	v_mfma_f32_16x16x32_bf16 v[60:63], v[162:165], v[178:181], v[60:63]
	v_mfma_f32_16x16x32_bf16 v[52:55], v[170:173], v[178:181], v[52:55]
	v_mfma_f32_16x16x32_bf16 v[44:47], v[162:165], v[186:189], v[44:47]
	v_mfma_f32_16x16x32_bf16 v[36:39], v[170:173], v[186:189], v[36:39]
	v_mfma_f32_16x16x32_bf16 v[28:31], v[162:165], v[194:197], v[28:31]
	v_mfma_f32_16x16x32_bf16 v[20:23], v[170:173], v[194:197], v[20:23]
	v_mfma_f32_16x16x32_bf16 v[12:15], v[162:165], v[202:205], v[12:15]
	v_mfma_f32_16x16x32_bf16 v[4:7], v[170:173], v[202:205], v[4:7]
	s_barrier
	v_add_u32_e32 v132, 0x18000, v140
	ds_read_b128 v[142:145], v132
	ds_read_b128 v[146:149], v132 offset:1024
	ds_read_b128 v[150:153], v132 offset:2048
	ds_read_b128 v[154:157], v132 offset:3072
	v_add_u32_e32 v132, 0x1c000, v140
	ds_read_b128 v[158:161], v132
	ds_read_b128 v[162:165], v132 offset:1024
	ds_read_b128 v[166:169], v132 offset:2048
	ds_read_b128 v[170:173], v132 offset:3072
	ds_read_b128 v[174:177], v141 offset:32768
	ds_read_b128 v[178:181], v141 offset:33792
	ds_read_b128 v[182:185], v141 offset:34816
	ds_read_b128 v[186:189], v141 offset:35840
	ds_read_b128 v[190:193], v141 offset:36864
	ds_read_b128 v[194:197], v141 offset:37888
	ds_read_b128 v[198:201], v141 offset:38912
	ds_read_b128 v[202:205], v141 offset:39936
	s_add_u32 s6, s6, 0x80000
	s_addc_u32 s7, s7, 0
	s_mov_b32 s8, m0
	s_mov_b32 m0, s42
	s_nop 0
	global_load_lds_dwordx4 v2, s[6:7]
	s_mov_b32 m0, s8
	s_nop 0
	s_mov_b32 s8, m0
	s_mov_b32 m0, s40
	s_nop 0
	global_load_lds_dwordx4 v135, s[6:7]
	s_mov_b32 m0, s8
	s_waitcnt vmcnt(9)
	s_waitcnt lgkmcnt(0)
	s_barrier
	s_waitcnt lgkmcnt(7)
	v_mfma_f32_16x16x32_bf16 v[128:131], v[142:145], v[174:177], v[128:131]
	v_mfma_f32_16x16x32_bf16 v[120:123], v[150:153], v[174:177], v[120:123]
	s_waitcnt lgkmcnt(5)
	v_mfma_f32_16x16x32_bf16 v[112:115], v[142:145], v[182:185], v[112:115]
	v_mfma_f32_16x16x32_bf16 v[104:107], v[150:153], v[182:185], v[104:107]
	s_waitcnt lgkmcnt(3)
	v_mfma_f32_16x16x32_bf16 v[96:99], v[142:145], v[190:193], v[96:99]
	v_mfma_f32_16x16x32_bf16 v[88:91], v[150:153], v[190:193], v[88:91]
	s_waitcnt lgkmcnt(1)
	v_mfma_f32_16x16x32_bf16 v[80:83], v[142:145], v[198:201], v[80:83]
	v_mfma_f32_16x16x32_bf16 v[72:75], v[150:153], v[198:201], v[72:75]
	v_mfma_f32_16x16x32_bf16 v[128:131], v[146:149], v[178:181], v[128:131]
	v_mfma_f32_16x16x32_bf16 v[120:123], v[154:157], v[178:181], v[120:123]
	v_mfma_f32_16x16x32_bf16 v[112:115], v[146:149], v[186:189], v[112:115]
	v_mfma_f32_16x16x32_bf16 v[104:107], v[154:157], v[186:189], v[104:107]
	v_mfma_f32_16x16x32_bf16 v[96:99], v[146:149], v[194:197], v[96:99]
	v_mfma_f32_16x16x32_bf16 v[88:91], v[154:157], v[194:197], v[88:91]
	s_waitcnt lgkmcnt(0)
	v_mfma_f32_16x16x32_bf16 v[80:83], v[146:149], v[202:205], v[80:83]
	v_mfma_f32_16x16x32_bf16 v[72:75], v[154:157], v[202:205], v[72:75]
	v_mfma_f32_16x16x32_bf16 v[124:127], v[158:161], v[174:177], v[124:127]
	v_mfma_f32_16x16x32_bf16 v[116:119], v[166:169], v[174:177], v[116:119]
	v_mfma_f32_16x16x32_bf16 v[108:111], v[158:161], v[182:185], v[108:111]
	v_mfma_f32_16x16x32_bf16 v[100:103], v[166:169], v[182:185], v[100:103]
	v_mfma_f32_16x16x32_bf16 v[92:95], v[158:161], v[190:193], v[92:95]
	v_mfma_f32_16x16x32_bf16 v[84:87], v[166:169], v[190:193], v[84:87]
	v_mfma_f32_16x16x32_bf16 v[76:79], v[158:161], v[198:201], v[76:79]
	v_mfma_f32_16x16x32_bf16 v[68:71], v[166:169], v[198:201], v[68:71]
	v_mfma_f32_16x16x32_bf16 v[124:127], v[162:165], v[178:181], v[124:127]
	v_mfma_f32_16x16x32_bf16 v[116:119], v[170:173], v[178:181], v[116:119]
	v_mfma_f32_16x16x32_bf16 v[108:111], v[162:165], v[186:189], v[108:111]
	v_mfma_f32_16x16x32_bf16 v[100:103], v[170:173], v[186:189], v[100:103]
	v_mfma_f32_16x16x32_bf16 v[92:95], v[162:165], v[194:197], v[92:95]
	v_mfma_f32_16x16x32_bf16 v[84:87], v[170:173], v[194:197], v[84:87]
	v_mfma_f32_16x16x32_bf16 v[76:79], v[162:165], v[202:205], v[76:79]
	v_mfma_f32_16x16x32_bf16 v[68:71], v[170:173], v[202:205], v[68:71]
	s_barrier
; #define PG8_STAGE(bufoff, gbase, voff) do { _Pragma("unroll") for (int _i = 0; _i < 2; ++_i) glds16_s((voff)[_i], (const void*)(gbase), ldsbase + (unsigned)((bufoff) + _i * 8192) + ldsw); } while (0)
; #define PG8_LDA(dst, b, h) do { _Pragma("unroll") for (int m = 0; m < 4; ++m) _Pragma("unroll") for (int k = 0; k < 2; ++k) dst[m][k] = *(const PG8_LAS bf16x8*)(lds + PG8_SA(b, h) + aoff + m * 2048 + k * 1024); } while (0)
; #define PG8_MMA(ai, bj, At, Bt) do { __builtin_amdgcn_s_setprio(1); _Pragma("unroll") for (int m = 0; m < 4; ++m) _Pragma("unroll") for (int n = 0; n < 2; ++n) _Pragma("unroll") for (int k = 0; k < 2; ++k) \
;         acc[ai][bj][m][n] = __builtin_amdgcn_mfma_f32_16x16x32_bf16(Bt[n][k], At[m][k], acc[ai][bj][m][n], 0, 0, 0); __builtin_amdgcn_s_setprio(0); } while (0)
; #define PG8_WAIT_V(n) asm volatile("s_waitcnt vmcnt(" #n ")" ::: "memory")
; #define PG8_WAIT_L(n) asm volatile("s_waitcnt lgkmcnt(" #n ")" ::: "memory")
; #define PG8_BAR __builtin_amdgcn_s_barrier()
; #define PG8_SCHED __builtin_amdgcn_sched_barrier(0)
; template <class Epi, class Sched, bool HM = false>
; __device__ __forceinline__ void gemm_phase(PG8_LAS unsigned char* lds, const Gemm g, const Sched& S, const Epi& E) {
;     ...
;             if (!HM) PG8_LDA(At, 1, 1); PG8_STAGE(PG8_SB(1, 0), b3, voffB); PG8_STAGE(PG8_SB(1, 1), b3 + hstepB, voffB); PG8_STAGE(PG8_SA(1, 0), a3, voffA);
;             PG8_WAIT_V(8); PG8_WAIT_L(0); PG8_BAR; if (!HM) { PG8_MMA(1, 0, At, B0); PG8_MMA(1, 1, At, B1); } PG8_BAR; PG8_SCHED;
;         }
;         if (wr == 0) PG8_BAR;
	ds_read_b128 v[174:177], v141 offset:49152
	ds_read_b128 v[178:181], v141 offset:50176
	ds_read_b128 v[182:185], v141 offset:51200
	ds_read_b128 v[186:189], v141 offset:52224
	ds_read_b128 v[190:193], v141 offset:53248
	ds_read_b128 v[194:197], v141 offset:54272
	ds_read_b128 v[198:201], v141 offset:55296
	ds_read_b128 v[202:205], v141 offset:56320
	s_mov_b32 s6, m0
	s_mov_b32 m0, s41
	s_nop 0
	global_load_lds_dwordx4 v134, s[4:5]
	s_mov_b32 m0, s6
	s_nop 0
	s_mov_b32 s6, m0
	s_mov_b32 m0, s44
	s_nop 0
	global_load_lds_dwordx4 v136, s[4:5]
	s_mov_b32 m0, s6
	s_add_u32 s4, s4, 0x80000
	s_addc_u32 s5, s5, 0
	s_mov_b32 s6, m0
	s_mov_b32 m0, s59
	s_nop 0
	global_load_lds_dwordx4 v134, s[4:5]
	s_mov_b32 m0, s6
	s_nop 0
	s_mov_b32 s6, m0
	s_mov_b32 m0, s60
	s_nop 0
	global_load_lds_dwordx4 v136, s[4:5]
	s_mov_b32 m0, s6
	s_mov_b32 s4, m0
	s_mov_b32 m0, s45
	s_nop 0
	global_load_lds_dwordx4 v2, s[0:1]
	s_mov_b32 m0, s4
	s_nop 0
	s_mov_b32 s4, m0
	s_mov_b32 m0, s58
	s_nop 0
	global_load_lds_dwordx4 v135, s[0:1]
	s_mov_b32 m0, s4
	s_waitcnt vmcnt(8)
	s_waitcnt lgkmcnt(0)
	s_barrier
	s_waitcnt lgkmcnt(7)
	v_mfma_f32_16x16x32_bf16 v[64:67], v[142:145], v[174:177], v[64:67]
	v_mfma_f32_16x16x32_bf16 v[56:59], v[150:153], v[174:177], v[56:59]
	s_waitcnt lgkmcnt(5)
	v_mfma_f32_16x16x32_bf16 v[48:51], v[142:145], v[182:185], v[48:51]
	v_mfma_f32_16x16x32_bf16 v[40:43], v[150:153], v[182:185], v[40:43]
	s_waitcnt lgkmcnt(3)
	v_mfma_f32_16x16x32_bf16 v[32:35], v[142:145], v[190:193], v[32:35]
	v_mfma_f32_16x16x32_bf16 v[24:27], v[150:153], v[190:193], v[24:27]
	s_waitcnt lgkmcnt(1)
	v_mfma_f32_16x16x32_bf16 v[16:19], v[142:145], v[198:201], v[16:19]
	v_mfma_f32_16x16x32_bf16 v[8:11], v[150:153], v[198:201], v[8:11]
	v_mfma_f32_16x16x32_bf16 v[64:67], v[146:149], v[178:181], v[64:67]
	v_mfma_f32_16x16x32_bf16 v[56:59], v[154:157], v[178:181], v[56:59]
	v_mfma_f32_16x16x32_bf16 v[48:51], v[146:149], v[186:189], v[48:51]
	v_mfma_f32_16x16x32_bf16 v[40:43], v[154:157], v[186:189], v[40:43]
	v_mfma_f32_16x16x32_bf16 v[32:35], v[146:149], v[194:197], v[32:35]
	v_mfma_f32_16x16x32_bf16 v[24:27], v[154:157], v[194:197], v[24:27]
	s_waitcnt lgkmcnt(0)
	v_mfma_f32_16x16x32_bf16 v[16:19], v[146:149], v[202:205], v[16:19]
	v_mfma_f32_16x16x32_bf16 v[8:11], v[154:157], v[202:205], v[8:11]
	v_mfma_f32_16x16x32_bf16 v[60:63], v[158:161], v[174:177], v[60:63]
	v_mfma_f32_16x16x32_bf16 v[52:55], v[166:169], v[174:177], v[52:55]
	v_mfma_f32_16x16x32_bf16 v[44:47], v[158:161], v[182:185], v[44:47]
	v_mfma_f32_16x16x32_bf16 v[36:39], v[166:169], v[182:185], v[36:39]
	v_mfma_f32_16x16x32_bf16 v[28:31], v[158:161], v[190:193], v[28:31]
	v_mfma_f32_16x16x32_bf16 v[20:23], v[166:169], v[190:193], v[20:23]
	v_mfma_f32_16x16x32_bf16 v[12:15], v[158:161], v[198:201], v[12:15]
	v_mfma_f32_16x16x32_bf16 v[4:7], v[166:169], v[198:201], v[4:7]
	v_mfma_f32_16x16x32_bf16 v[60:63], v[162:165], v[178:181], v[60:63]
	v_mfma_f32_16x16x32_bf16 v[52:55], v[170:173], v[178:181], v[52:55]
	v_mfma_f32_16x16x32_bf16 v[44:47], v[162:165], v[186:189], v[44:47]
	v_mfma_f32_16x16x32_bf16 v[36:39], v[170:173], v[186:189], v[36:39]
	v_mfma_f32_16x16x32_bf16 v[28:31], v[162:165], v[194:197], v[28:31]
	v_mfma_f32_16x16x32_bf16 v[20:23], v[170:173], v[194:197], v[20:23]
	v_mfma_f32_16x16x32_bf16 v[12:15], v[162:165], v[202:205], v[12:15]
	v_mfma_f32_16x16x32_bf16 v[4:7], v[170:173], v[202:205], v[4:7]
	s_barrier
	s_add_i32 s19, s19, 2
	s_addk_i32 s22, 0x1000
	s_add_u32 s15, s15, 0x100
	s_addc_u32 s16, s16, 0
	s_add_u32 s17, s17, 0x100
	s_addc_u32 s18, s18, 0
	s_cmp_gt_u32 s19, 29
	s_cbranch_scc0 .LBB0_1162
	s_and_b64 vcc, exec, s[76:77]
	s_cbranch_vccz .LBB0_1165
	s_barrier

; #define PG8_STAGEX(pb, gbase) glds16_s(voffX, (const void*)(gbase), ldsbase + (unsigned)(XOFF + (pb) * 4096) + ldsx)
; #define PG8_BAR __builtin_amdgcn_s_barrier()
; template <class Epi, class Sched, bool HM = false>
; __device__ __forceinline__ void gemm_phase(PG8_LAS unsigned char* lds, const Gemm g, const Sched& S, const Epi& E) {
;     ...
;     const int tid = tid_, wid = __builtin_amdgcn_readfirstlane(tid >> 6), lane = tid & 63, wr = wid >> 2, wc = wid & 3, fr = lane & 15, fq = lane >> 4;
;     const int K = g.K, nt = K / BK;
;     unsigned voffA[2], voffB[2];
; #pragma unroll
;     for (int i = 0; i < 2; ++i) { int R, C; stage_rc(tid * 16 + i * 8192, R, C); const int Rb = Epi::PERM ? ((R & ~31) + perm32(R & 31)) : R;
;         voffA[i] = (unsigned)(R * g.lda + C) * 2u; voffB[i] = (unsigned)(Rb * g.ldb + C) * 2u; }
;     const unsigned voffX = (unsigned)((4 * (wid & 3) + (lane >> 4)) * g.lda + 8 * (lane & 15)) * 2u;
;     const size_t kstep = (size_t)(BK * 2);
;     const size_t hstepA = (size_t)HALF * g.lda * 2, hstepB = (size_t)HALF * g.ldb * 2;
;     const size_t tstepA = (size_t)(HM ? HALF : g.pms) * g.lda * 2, tstepB = 2 * hstepB, xstep = 2 * hstepA; const bool hasx = g.pms != BM;
;     const unsigned ldsw = (unsigned)wid * 1024u, ldsx = (unsigned)(wid & 3) * 1024u;
;     const unsigned ldsbase = (unsigned)__builtin_amdgcn_readfirstlane((int)(unsigned)(__UINTPTR_TYPE__)lds);
;     const int aoff = lds_byte(wr * 64 + fr, fq * 8), boff = lds_byte(wc * 32 + fr, fq * 8);
;     const int xoff = XOFF + fr * 256 + fq * 16;
;     ...
;     Unit cur, nxt; int ui = 0;
;     if (!S.next(0, cur)) return;
;     f32x4 acc[2][2][4][2]; f32x4 accx[2];
; #pragma unroll
;     for (int a = 0; a < 2; ++a)
; #pragma unroll
;         for (int b = 0; b < 2; ++b)
; #pragma unroll
;             for (int m = 0; m < 4; ++m)
; #pragma unroll
;                 for (int n = 0; n < 2; ++n) acc[a][b][m][n] = (f32x4){0.f, 0.f, 0.f, 0.f};
;     accx[0] = (f32x4){0.f, 0.f, 0.f, 0.f}; accx[1] = accx[0];
;     bf16x8 At[4][2], B0[2][2], B1[2][2], Ax[2];
;     const char* cA = PG8_APTR(cur); const char* cB = PG8_BPTR(cur);
;     S.a_ready(cur);
;     PG8_STAGE(PG8_SB(0, 0), cB, voffB); PG8_STAGE(PG8_SB(0, 1), cB + hstepB, voffB); PG8_STAGE(PG8_SA(0, 0), cA, voffA); PG8_STAGEX(0, cA + xstep); PG8_STAGE(PG8_SA(0, 1), cA + hstepA, voffA);
;     if (wr == 1) PG8_BAR;
;     ...
;     PG8_WAIT_V(0);
;     PG8_BAR;
.LBB0_1168:
	s_waitcnt vmcnt(0)
	s_setprio 0
	v_readlane_b32 s83, v255, 7
	s_barrier
.LBB0_1169:
	v_readlane_b32 s0, v255, 18
	v_readlane_b32 s1, v255, 19
	s_andn2_b64 vcc, exec, s[0:1]
	s_cbranch_vccnz .LBB0_1148
	v_readlane_b32 s6, v255, 5
	s_mov_b64 s[0:1], s[30:31]
	s_mov_b64 s[4:5], s[30:31]
	s_mov_b64 s[8:9], s[30:31]
	v_mov_b32_e32 v5, v0
	v_readlane_b32 s7, v255, 6
	s_andn2_b64 vcc, exec, s[6:7]
	v_readfirstlane_b32 s22, v5
	s_cbranch_vccnz .LBB0_1148
	v_bfe_i32 v6, v5, 27, 1
	v_lshlrev_b32_e32 v4, 4, v5
	v_lshrrev_b32_e32 v6, 22, v6
	v_add_u32_e32 v6, v4, v6
	v_and_b32_e32 v6, 0xfffffc00, v6
	v_sub_u32_e32 v6, v4, v6
	v_ashrrev_i32_e32 v2, 31, v5
	v_lshrrev_b32_e32 v7, 4, v6
	v_lshrrev_b32_e32 v2, 26, v2
	v_bitop3_b32 v6, v7, v6, 32 bitop3:0x6c
	s_add_u32 s12, s0, 0x1a1e4000
	v_add_u32_e32 v2, v5, v2
	v_ashrrev_i32_e32 v8, 31, v6
	s_addc_u32 s13, s1, 0
	v_readlane_b32 s0, v255, 25
	v_ashrrev_i32_e32 v2, 6, v2
	v_lshrrev_b32_e32 v8, 26, v8
	s_add_u32 s0, s4, s0
	v_lshlrev_b32_e32 v7, 3, v2
	v_add_u32_e32 v8, v6, v8
	s_addc_u32 s1, s5, s89
	v_and_b32_e32 v7, -16, v7
	v_ashrrev_i32_e32 v9, 6, v8
	v_and_b32_e32 v8, 0xc0, v8
	s_add_u32 s14, s0, 0x7aa0000
	v_add_u32_e32 v7, v9, v7
	v_sub_u32_e32 v6, v6, v8
	s_addc_u32 s15, s1, 0
	v_lshlrev_b32_e32 v2, 5, v2
	v_ashrrev_i16_sdwa v6, v1, sext(v6) dst_sel:DWORD dst_unused:UNUSED_PAD src0_sel:DWORD src1_sel:BYTE_0
	v_lshlrev_b32_e32 v8, 1, v7
	v_lshrrev_b32_e32 v10, 2, v7
	v_and_b32_e32 v9, 3, v9
	s_mov_b32 s1, 0xfffe0
	v_and_b32_e32 v2, 32, v2
	v_bfe_i32 v6, v6, 0, 16
	v_and_b32_e32 v8, 24, v8
	v_and_b32_e32 v10, 4, v10
	v_and_or_b32 v9, v7, s1, v9
	v_or3_b32 v8, v9, v10, v8
	v_add_lshl_u32 v6, v2, v6, 1
	v_add_u32_e32 v4, 0x2000, v4
	v_lshl_add_u32 v2, v7, 12, v6
	v_lshl_add_u32 v70, v8, 12, v6
	v_ashrrev_i32_e32 v6, 31, v4
	v_lshrrev_b32_e32 v6, 22, v6
	v_add_u32_e32 v6, v4, v6
	v_ashrrev_i32_e32 v6, 10, v6
	v_mul_i32_i24_e32 v7, 0x400, v6
	v_sub_u32_e32 v4, v4, v7
	v_lshrrev_b32_e32 v7, 4, v4
	v_bitop3_b32 v4, v7, v4, 32 bitop3:0x6c
	v_ashrrev_i32_e32 v8, 31, v4
	v_lshrrev_b32_e32 v8, 26, v8
	v_lshlrev_b32_e32 v7, 3, v6
	v_add_u32_e32 v8, v4, v8
	s_ashr_i32 s0, s22, 6
	v_and_b32_e32 v7, -16, v7
	v_ashrrev_i32_e32 v9, 6, v8
	v_and_b32_e32 v8, 0xc0, v8
	s_and_b32 s23, s0, 3
	v_add_u32_e32 v7, v9, v7
	v_sub_u32_e32 v4, v4, v8
	v_and_b32_e32 v9, 3, v9
	v_lshlrev_b32_e32 v6, 5, v6
	v_ashrrev_i16_sdwa v4, v1, sext(v4) dst_sel:DWORD dst_unused:UNUSED_PAD src0_sel:DWORD src1_sel:BYTE_0
	v_lshlrev_b32_e32 v8, 1, v7
	v_lshrrev_b32_e32 v10, 2, v7
	v_and_or_b32 v9, v7, s1, v9
	s_ashr_i32 s27, s22, 8
	s_lshl_b32 s1, s23, 14
	s_lshl_b32 s0, s0, 10
	s_lshl_b32 s24, s23, 10
	v_readlane_b32 s4, v254, 30
	v_and_b32_e32 v6, 32, v6
	v_bfe_i32 v4, v4, 0, 16
	v_and_b32_e32 v8, 24, v8
	v_and_b32_e32 v10, 4, v10
	v_readlane_b32 s5, v254, 31
	s_add_u32 s4, s14, s4
	v_or3_b32 v8, v9, v10, v8
	v_add_lshl_u32 v4, v6, v4, 1
	s_addc_u32 s5, s15, s5
	s_add_i32 s16, s0, 0
	v_lshl_add_u32 v71, v7, 12, v4
	v_lshl_add_u32 v72, v8, 12, v4
	v_and_b32_e32 v4, 15, v5
	v_bfe_u32 v5, v5, 4, 2
	s_add_i32 s17, s16, 0x10000
	s_mov_b32 s0, m0
	s_mov_b32 m0, s17
	s_nop 0
	global_load_lds_dwordx4 v70, s[4:5]
	s_mov_b32 m0, s0
	v_lshlrev_b32_e32 v6, 12, v5
	v_lshlrev_b32_e32 v7, 4, v4
	s_add_i32 s18, s16, 0x12000
	s_mov_b32 s0, m0
	s_mov_b32 m0, s18
	s_nop 0
	global_load_lds_dwordx4 v72, s[4:5]
	s_mov_b32 m0, s0
	v_or3_b32 v73, s1, v6, v7
	v_readlane_b32 s0, v254, 54
	v_readlane_b32 s1, v254, 55
	s_add_u32 s6, s12, s0
	s_addc_u32 s7, s13, s1
	s_add_u32 s0, s4, 0x80000
	s_addc_u32 s1, s5, 0
	s_add_i32 s19, s16, 0x14000
	s_mov_b32 s20, m0
	s_mov_b32 m0, s19
	s_nop 0
	global_load_lds_dwordx4 v70, s[0:1]
	s_mov_b32 m0, s20
	s_add_i32 s20, s16, 0x16000
	s_mov_b32 s21, m0
	s_mov_b32 m0, s20
	s_nop 0
	global_load_lds_dwordx4 v72, s[0:1]
	s_mov_b32 m0, s21
	s_mov_b32 s0, m0
	s_mov_b32 m0, s16
	s_nop 0
	global_load_lds_dwordx4 v2, s[6:7]
	s_mov_b32 m0, s0
	s_add_i32 s21, s16, 0x2000
	s_mov_b32 s0, m0
	s_mov_b32 m0, s21
	s_nop 0
	global_load_lds_dwordx4 v71, s[6:7]
	s_mov_b32 m0, s0
	s_add_u32 s0, s6, 0x100000
	s_addc_u32 s1, s7, 0
	s_add_i32 s24, s24, 0
	s_add_i32 s25, s24, 0x20400
	s_mov_b32 s28, m0
	s_mov_b32 m0, s25
	s_nop 0
	global_load_lds_dwordx4 v73, s[0:1]
	s_mov_b32 m0, s28
	s_add_u32 s0, s6, 0x80000
	s_addc_u32 s1, s7, 0
	s_add_i32 s25, s16, 0x4000
	s_mov_b32 s28, m0
	s_mov_b32 m0, s25
	s_nop 0
	global_load_lds_dwordx4 v2, s[0:1]
	s_mov_b32 m0, s28
	s_add_i32 s28, s16, 0x6000
	s_mov_b32 s29, m0
	s_mov_b32 m0, s28
	s_nop 0
	global_load_lds_dwordx4 v71, s[0:1]
	s_mov_b32 m0, s29
	s_cmp_eq_u32 s27, 1
	s_cselect_b64 s[0:1], -1, 0
	s_cmp_lg_u32 s27, 1
	s_cbranch_scc1 .LBB0_1173
	s_setprio 1
	s_barrier

; #define PG8_STAGE(bufoff, gbase, voff) do { _Pragma("unroll") for (int _i = 0; _i < 2; ++_i) glds16_s((voff)[_i], (const void*)(gbase), ldsbase + (unsigned)((bufoff) + _i * 8192) + ldsw); } while (0)
; #define PG8_STAGEX(pb, gbase) glds16_s(voffX, (const void*)(gbase), ldsbase + (unsigned)(XOFF + (pb) * 4096) + ldsx)
; #define PG8_LDA(dst, b, h) do { _Pragma("unroll") for (int m = 0; m < 4; ++m) _Pragma("unroll") for (int k = 0; k < 2; ++k) dst[m][k] = *(const PG8_LAS bf16x8*)(lds + PG8_SA(b, h) + aoff + m * 2048 + k * 1024); } while (0)
; #define PG8_LDB(dst, b, h) do { _Pragma("unroll") for (int n = 0; n < 2; ++n) _Pragma("unroll") for (int k = 0; k < 2; ++k) dst[n][k] = *(const PG8_LAS bf16x8*)(lds + PG8_SB(b, h) + boff + n * 2048 + k * 1024); } while (0)
; #define PG8_LDX(pb, tp) do { _Pragma("unroll") for (int k = 0; k < 2; ++k) Ax[k] = *(const PG8_LAS bf16x8*)(lds + xoff + (pb) * 4096 + (tp) * 128 + k * 64); } while (0)
; #define PG8_WAIT_V(n) asm volatile("s_waitcnt vmcnt(" #n ")" ::: "memory")
; #define PG8_WAIT_L(n) asm volatile("s_waitcnt lgkmcnt(" #n ")" ::: "memory")
; #define PG8_BAR __builtin_amdgcn_s_barrier()
; #define PG8_SCHED __builtin_amdgcn_sched_barrier(0)
; template <class Epi, class Sched, bool HM = false>
; __device__ __forceinline__ void gemm_phase(PG8_LAS unsigned char* lds, const Gemm g, const Sched& S, const Epi& E) {
;     ...
;             const bool last = (t == nt - 2);
;             const char* a1 = cA + (size_t)(t + 1) * kstep;
;             const char* a2 = last ? nA : cA + (size_t)(t + 2) * kstep; const char* b2 = last ? nB : cB + (size_t)(t + 2) * kstep;
;             const char* a3 = a2 + kstep; const char* b3 = b2 + kstep;
;             asm volatile("; uniform bases" : "+s"(a1), "+s"(a2), "+s"(a3), "+s"(b2), "+s"(b3));
;             if (last && has_next) S.a_ready(nxt);
;             const int pb = (t >> 1) & 1;
;             PG8_LDB(B0, 0, 0); PG8_LDB(B1, 0, 1); PG8_SCHED; PG8_LDA(At, 0, 0); if (hasx) PG8_LDX(pb, 0); PG8_STAGE(PG8_SA(1, 1), a1 + hstepA, voffA); PG8_STAGEX(pb ^ 1, a2 + xstep);
;             PG8_WAIT_V(9); PG8_WAIT_L(0); PG8_BAR; PG8_MMA(0, 0, At, B0); PG8_MMA(0, 1, At, B1); if (hasx) PG8_MMAX(); PG8_BAR; PG8_SCHED;
;             if (!HM) PG8_LDA(At, 0, 1); PG8_STAGE(PG8_SB(0, 0), b2, voffB); PG8_STAGE(PG8_SB(0, 1), b2 + hstepB, voffB); PG8_STAGE(PG8_SA(0, 0), a2, voffA);
.LBB0_1187:
	s_add_u32 s78, s58, 0xffffff80
	s_addc_u32 s79, s59, -1
	s_cmp_eq_u32 s60, 28
	s_cselect_b32 s8, s38, s58
	s_cselect_b32 s9, s39, s59
	s_cselect_b32 s35, s77, s52
	s_cselect_b32 s34, s76, s27
	s_add_u32 s4, s8, 0x80
	s_addc_u32 s5, s9, 0
	s_add_u32 s6, s34, 0x80
	s_addc_u32 s7, s35, 0
	v_add_u32_e32 v68, 0x10000, v76
	ds_read_b128 v[78:81], v68
	ds_read_b128 v[82:85], v68 offset:1024
	ds_read_b128 v[86:89], v68 offset:2048
	ds_read_b128 v[90:93], v68 offset:3072
	v_add_u32_e32 v68, 0x14000, v76
	ds_read_b128 v[94:97], v68
	ds_read_b128 v[98:101], v68 offset:1024
	ds_read_b128 v[102:105], v68 offset:2048
	ds_read_b128 v[106:109], v68 offset:3072
	ds_read_b128 v[110:113], v77
	ds_read_b128 v[114:117], v77 offset:1024
	ds_read_b128 v[118:121], v77 offset:2048
	ds_read_b128 v[122:125], v77 offset:3072
	ds_read_b128 v[126:129], v77 offset:4096
	ds_read_b128 v[130:133], v77 offset:5120
	ds_read_b128 v[134:137], v77 offset:6144
	ds_read_b128 v[138:141], v77 offset:7168
	s_add_u32 s78, s78, 0x80000
	s_addc_u32 s79, s79, 0
	s_mov_b32 s75, m0
	s_mov_b32 m0, s43
	s_nop 0
	global_load_lds_dwordx4 v2, s[78:79]
	s_mov_b32 m0, s75
	s_nop 0
	s_mov_b32 s75, m0
	s_mov_b32 m0, s44
	s_nop 0
	global_load_lds_dwordx4 v71, s[78:79]
	s_mov_b32 m0, s75
	s_add_u32 s78, s8, 0x100000
	s_addc_u32 s79, s9, 0
	s_and_b32 s75, s61, 0x1000
	s_xor_b32 s75, s75, 0x21400
	s_add_i32 s75, s24, s75
	s_mov_b32 s82, m0
	s_mov_b32 m0, s75
	s_nop 0
	global_load_lds_dwordx4 v73, s[78:79]
	s_mov_b32 m0, s82
	s_waitcnt vmcnt(9)
	s_waitcnt lgkmcnt(0)
	s_barrier
	s_waitcnt lgkmcnt(7)
	v_mfma_f32_16x16x32_bf16 v[64:67], v[78:81], v[110:113], v[64:67]
	v_mfma_f32_16x16x32_bf16 v[56:59], v[86:89], v[110:113], v[56:59]
	s_waitcnt lgkmcnt(5)
	v_mfma_f32_16x16x32_bf16 v[48:51], v[78:81], v[118:121], v[48:51]
	v_mfma_f32_16x16x32_bf16 v[40:43], v[86:89], v[118:121], v[40:43]
	s_waitcnt lgkmcnt(3)
	v_mfma_f32_16x16x32_bf16 v[32:35], v[78:81], v[126:129], v[32:35]
	v_mfma_f32_16x16x32_bf16 v[24:27], v[86:89], v[126:129], v[24:27]
	s_waitcnt lgkmcnt(1)
	v_mfma_f32_16x16x32_bf16 v[16:19], v[78:81], v[134:137], v[16:19]
	v_mfma_f32_16x16x32_bf16 v[8:11], v[86:89], v[134:137], v[8:11]
	v_mfma_f32_16x16x32_bf16 v[64:67], v[82:85], v[114:117], v[64:67]
	v_mfma_f32_16x16x32_bf16 v[56:59], v[90:93], v[114:117], v[56:59]
	v_mfma_f32_16x16x32_bf16 v[48:51], v[82:85], v[122:125], v[48:51]
	v_mfma_f32_16x16x32_bf16 v[40:43], v[90:93], v[122:125], v[40:43]
	v_mfma_f32_16x16x32_bf16 v[32:35], v[82:85], v[130:133], v[32:35]
	v_mfma_f32_16x16x32_bf16 v[24:27], v[90:93], v[130:133], v[24:27]
	s_waitcnt lgkmcnt(0)
	v_mfma_f32_16x16x32_bf16 v[16:19], v[82:85], v[138:141], v[16:19]
	v_mfma_f32_16x16x32_bf16 v[8:11], v[90:93], v[138:141], v[8:11]
	v_mfma_f32_16x16x32_bf16 v[60:63], v[94:97], v[110:113], v[60:63]
	v_mfma_f32_16x16x32_bf16 v[52:55], v[102:105], v[110:113], v[52:55]
	v_mfma_f32_16x16x32_bf16 v[44:47], v[94:97], v[118:121], v[44:47]
	v_mfma_f32_16x16x32_bf16 v[36:39], v[102:105], v[118:121], v[36:39]
	v_mfma_f32_16x16x32_bf16 v[28:31], v[94:97], v[126:129], v[28:31]
	v_mfma_f32_16x16x32_bf16 v[20:23], v[102:105], v[126:129], v[20:23]
	v_mfma_f32_16x16x32_bf16 v[12:15], v[94:97], v[134:137], v[12:15]
	v_mfma_f32_16x16x32_bf16 v[4:7], v[102:105], v[134:137], v[4:7]
	v_mfma_f32_16x16x32_bf16 v[60:63], v[98:101], v[114:117], v[60:63]
	v_mfma_f32_16x16x32_bf16 v[52:55], v[106:109], v[114:117], v[52:55]
	v_mfma_f32_16x16x32_bf16 v[44:47], v[98:101], v[122:125], v[44:47]
	v_mfma_f32_16x16x32_bf16 v[36:39], v[106:109], v[122:125], v[36:39]
	v_mfma_f32_16x16x32_bf16 v[28:31], v[98:101], v[130:133], v[28:31]
	v_mfma_f32_16x16x32_bf16 v[20:23], v[106:109], v[130:133], v[20:23]
	v_mfma_f32_16x16x32_bf16 v[12:15], v[98:101], v[138:141], v[12:15]
	v_mfma_f32_16x16x32_bf16 v[4:7], v[106:109], v[138:141], v[4:7]
	s_barrier
	s_mov_b32 s75, m0
	s_mov_b32 m0, s17
	s_nop 0
	global_load_lds_dwordx4 v70, s[34:35]
	s_mov_b32 m0, s75
	s_nop 0
	s_mov_b32 s75, m0
	s_mov_b32 m0, s18
	s_nop 0
	global_load_lds_dwordx4 v72, s[34:35]
	s_mov_b32 m0, s75
	s_add_u32 s34, s34, 0x80000
	s_addc_u32 s35, s35, 0
	s_mov_b32 s75, m0
	s_mov_b32 m0, s19
	s_nop 0
	global_load_lds_dwordx4 v70, s[34:35]
	s_mov_b32 m0, s75
	s_nop 0
	s_mov_b32 s75, m0
	s_mov_b32 m0, s20
	s_nop 0
	global_load_lds_dwordx4 v72, s[34:35]
	s_mov_b32 m0, s75
	s_mov_b32 s34, m0
	s_mov_b32 m0, s16
	s_nop 0
	global_load_lds_dwordx4 v2, s[8:9]
	s_mov_b32 m0, s34
	s_nop 0
	s_mov_b32 s34, m0
	s_mov_b32 m0, s21
	s_nop 0
	global_load_lds_dwordx4 v71, s[8:9]
	s_mov_b32 m0, s34
	s_waitcnt vmcnt(9)
	s_waitcnt lgkmcnt(0)
	s_barrier
; #define PG8_STAGE(bufoff, gbase, voff) do { _Pragma("unroll") for (int _i = 0; _i < 2; ++_i) glds16_s((voff)[_i], (const void*)(gbase), ldsbase + (unsigned)((bufoff) + _i * 8192) + ldsw); } while (0)
; #define PG8_LDA(dst, b, h) do { _Pragma("unroll") for (int m = 0; m < 4; ++m) _Pragma("unroll") for (int k = 0; k < 2; ++k) dst[m][k] = *(const PG8_LAS bf16x8*)(lds + PG8_SA(b, h) + aoff + m * 2048 + k * 1024); } while (0)
; #define PG8_LDB(dst, b, h) do { _Pragma("unroll") for (int n = 0; n < 2; ++n) _Pragma("unroll") for (int k = 0; k < 2; ++k) dst[n][k] = *(const PG8_LAS bf16x8*)(lds + PG8_SB(b, h) + boff + n * 2048 + k * 1024); } while (0)
; #define PG8_LDX(pb, tp) do { _Pragma("unroll") for (int k = 0; k < 2; ++k) Ax[k] = *(const PG8_LAS bf16x8*)(lds + xoff + (pb) * 4096 + (tp) * 128 + k * 64); } while (0)
; #define PG8_MMA(ai, bj, At, Bt) do { __builtin_amdgcn_s_setprio(1); _Pragma("unroll") for (int m = 0; m < 4; ++m) _Pragma("unroll") for (int n = 0; n < 2; ++n) _Pragma("unroll") for (int k = 0; k < 2; ++k) \
;         acc[ai][bj][m][n] = __builtin_amdgcn_mfma_f32_16x16x32_bf16(Bt[n][k], At[m][k], acc[ai][bj][m][n], 0, 0, 0); __builtin_amdgcn_s_setprio(0); } while (0)
; #define PG8_WAIT_V(n) asm volatile("s_waitcnt vmcnt(" #n ")" ::: "memory")
; #define PG8_BAR __builtin_amdgcn_s_barrier()
; template <class Epi, class Sched, bool HM = false>
; __device__ __forceinline__ void gemm_phase(PG8_LAS unsigned char* lds, const Gemm g, const Sched& S, const Epi& E) {
;     ...
;             if (!HM) PG8_LDA(At, 0, 1); PG8_STAGE(PG8_SB(0, 0), b2, voffB); PG8_STAGE(PG8_SB(0, 1), b2 + hstepB, voffB); PG8_STAGE(PG8_SA(0, 0), a2, voffA);
;             PG8_WAIT_V(9); PG8_WAIT_L(0); PG8_BAR; if (!HM) { PG8_MMA(1, 0, At, B0); PG8_MMA(1, 1, At, B1); } PG8_BAR; PG8_SCHED;
;             PG8_LDB(B0, 1, 0); PG8_LDB(B1, 1, 1); PG8_SCHED; PG8_LDA(At, 1, 0); if (hasx) PG8_LDX(pb, 1); PG8_STAGE(PG8_SA(0, 1), a2 + hstepA, voffA);
;             PG8_WAIT_V(9); PG8_WAIT_L(0); PG8_BAR; PG8_MMA(0, 0, At, B0); PG8_MMA(0, 1, At, B1); if (hasx) PG8_MMAX(); PG8_BAR; PG8_SCHED;
;             if (!HM) PG8_LDA(At, 1, 1); PG8_STAGE(PG8_SB(1, 0), b3, voffB); PG8_STAGE(PG8_SB(1, 1), b3 + hstepB, voffB); PG8_STAGE(PG8_SA(1, 0), a3, voffA);
;             PG8_WAIT_V(8); PG8_WAIT_L(0); PG8_BAR; if (!HM) { PG8_MMA(1, 0, At, B0); PG8_MMA(1, 1, At, B1); } PG8_BAR; PG8_SCHED;
;         }
	s_barrier
	v_add_u32_e32 v68, 0x18000, v76
	ds_read_b128 v[78:81], v68
	ds_read_b128 v[82:85], v68 offset:1024
	ds_read_b128 v[86:89], v68 offset:2048
	ds_read_b128 v[90:93], v68 offset:3072
	v_add_u32_e32 v68, 0x1c000, v76
	ds_read_b128 v[94:97], v68
	ds_read_b128 v[98:101], v68 offset:1024
	ds_read_b128 v[102:105], v68 offset:2048
	ds_read_b128 v[106:109], v68 offset:3072
	ds_read_b128 v[110:113], v77 offset:32768
	ds_read_b128 v[114:117], v77 offset:33792
	ds_read_b128 v[118:121], v77 offset:34816
	ds_read_b128 v[122:125], v77 offset:35840
	ds_read_b128 v[126:129], v77 offset:36864
	ds_read_b128 v[130:133], v77 offset:37888
	ds_read_b128 v[134:137], v77 offset:38912
	ds_read_b128 v[138:141], v77 offset:39936
	s_add_u32 s8, s8, 0x80000
	s_addc_u32 s9, s9, 0
	s_mov_b32 s34, m0
	s_mov_b32 m0, s25
	s_nop 0
	global_load_lds_dwordx4 v2, s[8:9]
	s_mov_b32 m0, s34
	s_nop 0
	s_mov_b32 s34, m0
	s_mov_b32 m0, s28
	s_nop 0
	global_load_lds_dwordx4 v71, s[8:9]
	s_mov_b32 m0, s34
	s_waitcnt vmcnt(9)
	s_waitcnt lgkmcnt(0)
	s_barrier
	s_waitcnt lgkmcnt(7)
	v_mfma_f32_16x16x32_bf16 v[64:67], v[78:81], v[110:113], v[64:67]
	v_mfma_f32_16x16x32_bf16 v[56:59], v[86:89], v[110:113], v[56:59]
	s_waitcnt lgkmcnt(5)
	v_mfma_f32_16x16x32_bf16 v[48:51], v[78:81], v[118:121], v[48:51]
	v_mfma_f32_16x16x32_bf16 v[40:43], v[86:89], v[118:121], v[40:43]
	s_waitcnt lgkmcnt(3)
	v_mfma_f32_16x16x32_bf16 v[32:35], v[78:81], v[126:129], v[32:35]
	v_mfma_f32_16x16x32_bf16 v[24:27], v[86:89], v[126:129], v[24:27]
	s_waitcnt lgkmcnt(1)
	v_mfma_f32_16x16x32_bf16 v[16:19], v[78:81], v[134:137], v[16:19]
	v_mfma_f32_16x16x32_bf16 v[8:11], v[86:89], v[134:137], v[8:11]
	v_mfma_f32_16x16x32_bf16 v[64:67], v[82:85], v[114:117], v[64:67]
	v_mfma_f32_16x16x32_bf16 v[56:59], v[90:93], v[114:117], v[56:59]
	v_mfma_f32_16x16x32_bf16 v[48:51], v[82:85], v[122:125], v[48:51]
	v_mfma_f32_16x16x32_bf16 v[40:43], v[90:93], v[122:125], v[40:43]
	v_mfma_f32_16x16x32_bf16 v[32:35], v[82:85], v[130:133], v[32:35]
	v_mfma_f32_16x16x32_bf16 v[24:27], v[90:93], v[130:133], v[24:27]
	s_waitcnt lgkmcnt(0)
	v_mfma_f32_16x16x32_bf16 v[16:19], v[82:85], v[138:141], v[16:19]
	v_mfma_f32_16x16x32_bf16 v[8:11], v[90:93], v[138:141], v[8:11]
	v_mfma_f32_16x16x32_bf16 v[60:63], v[94:97], v[110:113], v[60:63]
	v_mfma_f32_16x16x32_bf16 v[52:55], v[102:105], v[110:113], v[52:55]
	v_mfma_f32_16x16x32_bf16 v[44:47], v[94:97], v[118:121], v[44:47]
	v_mfma_f32_16x16x32_bf16 v[36:39], v[102:105], v[118:121], v[36:39]
	v_mfma_f32_16x16x32_bf16 v[28:31], v[94:97], v[126:129], v[28:31]
	v_mfma_f32_16x16x32_bf16 v[20:23], v[102:105], v[126:129], v[20:23]
	v_mfma_f32_16x16x32_bf16 v[12:15], v[94:97], v[134:137], v[12:15]
	v_mfma_f32_16x16x32_bf16 v[4:7], v[102:105], v[134:137], v[4:7]
	v_mfma_f32_16x16x32_bf16 v[60:63], v[98:101], v[114:117], v[60:63]
	v_mfma_f32_16x16x32_bf16 v[52:55], v[106:109], v[114:117], v[52:55]
	v_mfma_f32_16x16x32_bf16 v[44:47], v[98:101], v[122:125], v[44:47]
	v_mfma_f32_16x16x32_bf16 v[36:39], v[106:109], v[122:125], v[36:39]
	v_mfma_f32_16x16x32_bf16 v[28:31], v[98:101], v[130:133], v[28:31]
	v_mfma_f32_16x16x32_bf16 v[20:23], v[106:109], v[130:133], v[20:23]
	v_mfma_f32_16x16x32_bf16 v[12:15], v[98:101], v[138:141], v[12:15]
	v_mfma_f32_16x16x32_bf16 v[4:7], v[106:109], v[138:141], v[4:7]
	s_barrier
	s_mov_b32 s8, m0
	s_mov_b32 m0, s29
	s_nop 0
	global_load_lds_dwordx4 v70, s[6:7]
	s_mov_b32 m0, s8
	s_nop 0
	s_mov_b32 s8, m0
	s_mov_b32 m0, s30
	s_nop 0
	global_load_lds_dwordx4 v72, s[6:7]
	s_mov_b32 m0, s8
	s_add_u32 s6, s6, 0x80000
	s_addc_u32 s7, s7, 0
	s_mov_b32 s8, m0
	s_mov_b32 m0, s41
	s_nop 0
	global_load_lds_dwordx4 v70, s[6:7]
	s_mov_b32 m0, s8
	s_nop 0
	s_mov_b32 s8, m0
	s_mov_b32 m0, s42
	s_nop 0
	global_load_lds_dwordx4 v72, s[6:7]
	s_mov_b32 m0, s8
	s_mov_b32 s6, m0
	s_mov_b32 m0, s31
	s_nop 0
	global_load_lds_dwordx4 v2, s[4:5]
	s_mov_b32 m0, s6
	s_nop 0
	s_mov_b32 s6, m0
	s_mov_b32 m0, s40
	s_nop 0
	global_load_lds_dwordx4 v71, s[4:5]
	s_mov_b32 m0, s6
	s_waitcnt vmcnt(8)
	s_waitcnt lgkmcnt(0)
	s_barrier
	s_barrier
	s_add_i32 s60, s60, 2
	s_addk_i32 s61, 0x1000
	s_add_u32 s27, s27, 0x100
	s_addc_u32 s52, s52, 0
	s_add_u32 s58, s58, 0x100
	s_addc_u32 s59, s59, 0
	s_cmp_gt_u32 s60, 29
	s_cbranch_scc0 .LBB0_1187
	s_and_b64 vcc, exec, s[62:63]
	s_cbranch_vccz .LBB0_1190
	s_barrier

; #define PG8_WAIT_V(n) asm volatile("s_waitcnt vmcnt(" #n ")" ::: "memory")
; #define PG8_BAR __builtin_amdgcn_s_barrier()
; template <class Epi, class Sched, bool HM = false>
; __device__ __forceinline__ void gemm_phase(PG8_LAS unsigned char* lds, const Gemm g, const Sched& S, const Epi& E) {
;     ...
;     PG8_WAIT_V(0);
;     PG8_BAR;
.LBB0_1248:
	s_waitcnt vmcnt(0)
	s_setprio 0
	v_readlane_b32 s30, v252, 46
	v_readlane_b32 s28, v252, 50
	v_readlane_b32 s31, v252, 47
	v_readlane_b32 s51, v252, 48
	v_readlane_b32 s52, v252, 49
	v_readlane_b32 s57, v255, 8
	v_readlane_b32 s29, v252, 51
	v_readlane_b32 s83, v255, 7
	s_barrier

; #define PG8_STAGE(bufoff, gbase, voff) do { _Pragma("unroll") for (int _i = 0; _i < 2; ++_i) glds16_s((voff)[_i], (const void*)(gbase), ldsbase + (unsigned)((bufoff) + _i * 8192) + ldsw); } while (0)
; template <class Epi, class Sched, bool HM = false>
; __device__ __forceinline__ void gemm_phase(PG8_LAS unsigned char* lds, const Gemm g, const Sched& S, const Epi& E) {
;     ...
;     const int tid = tid_, wid = __builtin_amdgcn_readfirstlane(tid >> 6), lane = tid & 63, wr = wid >> 2, wc = wid & 3, fr = lane & 15, fq = lane >> 4;
;     const int K = g.K, nt = K / BK;
;     unsigned voffA[2], voffB[2];
; #pragma unroll
;     for (int i = 0; i < 2; ++i) { int R, C; stage_rc(tid * 16 + i * 8192, R, C); const int Rb = Epi::PERM ? ((R & ~31) + perm32(R & 31)) : R;
;         voffA[i] = (unsigned)(R * g.lda + C) * 2u; voffB[i] = (unsigned)(Rb * g.ldb + C) * 2u; }
;     const unsigned voffX = (unsigned)((4 * (wid & 3) + (lane >> 4)) * g.lda + 8 * (lane & 15)) * 2u;
;     const size_t kstep = (size_t)(BK * 2);
;     const size_t hstepA = (size_t)HALF * g.lda * 2, hstepB = (size_t)HALF * g.ldb * 2;
;     const size_t tstepA = (size_t)(HM ? HALF : g.pms) * g.lda * 2, tstepB = 2 * hstepB, xstep = 2 * hstepA; const bool hasx = g.pms != BM;
;     const unsigned ldsw = (unsigned)wid * 1024u, ldsx = (unsigned)(wid & 3) * 1024u;
;     const unsigned ldsbase = (unsigned)__builtin_amdgcn_readfirstlane((int)(unsigned)(__UINTPTR_TYPE__)lds);
;     const int aoff = lds_byte(wr * 64 + fr, fq * 8), boff = lds_byte(wc * 32 + fr, fq * 8);
;     const int xoff = XOFF + fr * 256 + fq * 16;
;     ...
;     Unit cur, nxt; int ui = 0;
;     if (!S.next(0, cur)) return;
;     f32x4 acc[2][2][4][2]; f32x4 accx[2];
; #pragma unroll
;     for (int a = 0; a < 2; ++a)
; #pragma unroll
;         for (int b = 0; b < 2; ++b)
; #pragma unroll
;             for (int m = 0; m < 4; ++m)
; #pragma unroll
;                 for (int n = 0; n < 2; ++n) acc[a][b][m][n] = (f32x4){0.f, 0.f, 0.f, 0.f};
;     accx[0] = (f32x4){0.f, 0.f, 0.f, 0.f}; accx[1] = accx[0];
;     bf16x8 At[4][2], B0[2][2], B1[2][2], Ax[2];
;     const char* cA = PG8_APTR(cur); const char* cB = PG8_BPTR(cur);
;     S.a_ready(cur);
;     PG8_STAGE(PG8_SB(0, 0), cB, voffB); PG8_STAGE(PG8_SB(0, 1), cB + hstepB, voffB); PG8_STAGE(PG8_SA(0, 0), cA, voffA); PG8_STAGEX(0, cA + xstep); PG8_STAGE(PG8_SA(0, 1), cA + hstepA, voffA);
;     if (wr == 1) PG8_BAR;
.LBB0_1250:
	s_mov_b64 s[4:5], s[30:31]
	s_mov_b64 s[0:1], s[30:31]
	s_mov_b64 s[8:9], s[30:31]
	v_mov_b32_e32 v4, v0
	s_andn2_b64 vcc, exec, s[96:97]
	v_readfirstlane_b32 s20, v4
	s_cbranch_vccnz .LBB0_1249
	v_bfe_i32 v7, v4, 27, 1
	v_lshlrev_b32_e32 v5, 4, v4
	v_lshrrev_b32_e32 v7, 22, v7
	v_add_u32_e32 v7, v5, v7
	v_and_b32_e32 v7, 0xfffffc00, v7
	v_sub_u32_e32 v7, v5, v7
	v_lshrrev_b32_e32 v8, 4, v7
	v_ashrrev_i32_e32 v6, 31, v4
	v_bitop3_b32 v7, v8, v7, 32 bitop3:0x6c
	s_add_u32 s13, s4, 0x30084000
	v_lshrrev_b32_e32 v6, 26, v6
	v_ashrrev_i32_e32 v9, 31, v7
	s_addc_u32 s14, s5, 0
	v_readlane_b32 s5, v255, 17
	v_add_u32_e32 v6, v4, v6
	v_lshrrev_b32_e32 v9, 26, v9
	s_mul_i32 s4, s5, 0x1600000
	v_ashrrev_i32_e32 v6, 6, v6
	v_add_u32_e32 v9, v7, v9
	s_add_u32 s0, s0, s4
	s_mul_hi_u32 s4, s5, 0x1600000
	v_lshlrev_b32_e32 v8, 3, v6
	v_ashrrev_i32_e32 v10, 6, v9
	v_and_b32_e32 v9, 0xc0, v9
	s_addc_u32 s1, s1, s4
	v_and_b32_e32 v8, -16, v8
	v_lshlrev_b32_e32 v6, 5, v6
	v_sub_u32_e32 v7, v7, v9
	s_add_u32 s15, s0, 0x102a0000
	v_add_u32_e32 v8, v10, v8
	v_and_b32_e32 v6, 32, v6
	v_ashrrev_i16_sdwa v7, v1, sext(v7) dst_sel:DWORD dst_unused:UNUSED_PAD src0_sel:DWORD src1_sel:BYTE_0
	s_addc_u32 s16, s1, 0
	v_add_u32_sdwa v6, v6, sext(v7) dst_sel:DWORD dst_unused:UNUSED_PAD src0_sel:DWORD src1_sel:WORD_0
	v_lshlrev_b32_e32 v7, 1, v8
	v_lshrrev_b32_e32 v9, 2, v8
	v_and_b32_e32 v10, 3, v10
	s_mov_b32 s1, 0x7fffe0
	v_and_b32_e32 v7, 24, v7
	v_and_b32_e32 v9, 4, v9
	v_and_or_b32 v10, v8, s1, v10
	v_or3_b32 v7, v10, v9, v7
	s_movk_i32 s4, 0x1600
	v_mul_lo_u32 v8, v8, s4
	v_mul_u32_u24_e32 v7, 0x1600, v7
	v_add_u32_e32 v5, 0x2000, v5
	v_add_lshl_u32 v225, v6, v8, 1
	v_add_lshl_u32 v226, v7, v6, 1
	v_ashrrev_i32_e32 v6, 31, v5
	v_lshrrev_b32_e32 v6, 22, v6
	v_add_u32_e32 v6, v5, v6
	v_ashrrev_i32_e32 v6, 10, v6
	v_mul_i32_i24_e32 v7, 0x400, v6
	v_sub_u32_e32 v5, v5, v7
	v_lshrrev_b32_e32 v7, 4, v5
	v_bitop3_b32 v5, v7, v5, 32 bitop3:0x6c
	v_ashrrev_i32_e32 v8, 31, v5
	v_lshrrev_b32_e32 v8, 26, v8
	v_add_u32_e32 v8, v5, v8
	v_lshlrev_b32_e32 v7, 3, v6
	v_ashrrev_i32_e32 v9, 6, v8
	v_and_b32_e32 v8, 0xc0, v8
	s_ashr_i32 s0, s20, 6
	v_and_b32_e32 v7, -16, v7
	v_lshlrev_b32_e32 v6, 5, v6
	v_sub_u32_e32 v5, v5, v8
	s_and_b32 s21, s0, 3
	v_add_u32_e32 v7, v9, v7
	v_and_b32_e32 v6, 32, v6
	v_ashrrev_i16_sdwa v5, v1, sext(v5) dst_sel:DWORD dst_unused:UNUSED_PAD src0_sel:DWORD src1_sel:BYTE_0
	v_and_b32_e32 v9, 3, v9
	v_add_u32_sdwa v5, v6, sext(v5) dst_sel:DWORD dst_unused:UNUSED_PAD src0_sel:DWORD src1_sel:WORD_0
	v_lshlrev_b32_e32 v6, 1, v7
	v_lshrrev_b32_e32 v8, 2, v7
	v_and_or_b32 v9, v7, s1, v9
	s_ashr_i32 s22, s20, 8
	s_lshl_b32 s0, s0, 10
	s_lshl_b32 s23, s21, 10
	v_readlane_b32 s1, v254, 50
	v_and_b32_e32 v6, 24, v6
	v_and_b32_e32 v8, 4, v8
	v_mul_lo_u32 v7, v7, s4
	s_add_u32 s4, s15, s1
	v_readlane_b32 s1, v254, 51
	v_or3_b32 v6, v9, v8, v6
	s_addc_u32 s5, s16, s1
	s_add_i32 s17, s0, 0
	v_mul_u32_u24_e32 v6, 0x1600, v6
	s_add_i32 s18, s17, 0x10000
	s_mov_b32 s0, m0
	s_mov_b32 m0, s18
	s_nop 0
	global_load_lds_dwordx4 v226, s[4:5]
	s_mov_b32 m0, s0
	v_add_lshl_u32 v228, v6, v5, 1
	s_add_i32 s19, s17, 0x12000
	s_mov_b32 s0, m0
	s_mov_b32 m0, s19
	s_nop 0
	global_load_lds_dwordx4 v228, s[4:5]
	s_mov_b32 m0, s0
	v_readlane_b32 s1, v254, 23
	s_mul_i32 s0, s1, s10
	s_add_u32 s6, s13, s0
	s_mul_hi_i32 s0, s1, s10
	s_addc_u32 s7, s14, s0
	s_add_u32 s0, s4, 0x160000
	s_addc_u32 s1, s5, 0
	s_add_i32 s24, s17, 0x14000
	s_mov_b32 s25, m0
	s_mov_b32 m0, s24
	s_nop 0
	global_load_lds_dwordx4 v226, s[0:1]
	s_mov_b32 m0, s25
	s_add_i32 s25, s17, 0x16000
	s_mov_b32 s27, m0
	s_mov_b32 m0, s25
	s_nop 0
	global_load_lds_dwordx4 v228, s[0:1]
	s_mov_b32 m0, s27
	v_readlane_b32 s0, v254, 37
	s_add_u32 s6, s6, s0
	v_readlane_b32 s0, v254, 36
	s_addc_u32 s7, s7, s0
	s_mov_b32 s0, m0
	s_mov_b32 m0, s17
	s_nop 0
	global_load_lds_dwordx4 v225, s[6:7]
	s_mov_b32 m0, s0
	v_add_lshl_u32 v227, v5, v7, 1
	s_add_i32 s28, s17, 0x2000
	s_mov_b32 s0, m0
	s_mov_b32 m0, s28
	s_nop 0
	global_load_lds_dwordx4 v227, s[6:7]
	s_mov_b32 m0, s0
	v_bfe_u32 v2, v4, 4, 2
	s_add_u32 s0, s6, 0x2c0000
	v_lshl_or_b32 v5, s21, 2, v2
	v_lshlrev_b32_e32 v232, 4, v5
	s_addc_u32 s1, s7, 0
	s_add_i32 s29, s23, 0
	v_and_b32_e32 v4, 15, v4
	v_mul_u32_u24_e32 v5, 0x2c00, v5
	s_add_i32 s23, s29, 0x20400
	v_lshl_or_b32 v229, v4, 4, v5
	v_xor_b32_e32 v229, v229, v232
	s_mov_b32 s27, m0
	s_mov_b32 m0, s23
	s_nop 0
	global_load_lds_dwordx4 v229, s[0:1]
	s_mov_b32 m0, s27
	s_add_u32 s0, s6, 0x160000
	s_addc_u32 s1, s7, 0
	s_add_i32 s30, s17, 0x4000
	s_mov_b32 s23, m0
	s_mov_b32 m0, s30
	s_nop 0
	global_load_lds_dwordx4 v225, s[0:1]
	s_mov_b32 m0, s23
	s_add_i32 s31, s17, 0x6000
	s_mov_b32 s23, m0
	s_mov_b32 m0, s31
	s_nop 0
	global_load_lds_dwordx4 v227, s[0:1]
	s_mov_b32 m0, s23
	s_cmp_eq_u32 s22, 1
	s_cselect_b64 s[0:1], -1, 0
	s_cmp_lg_u32 s22, 1
	s_cbranch_scc1 .LBB0_1253
	s_setprio 1
	s_barrier

; #define PG8_STAGE(bufoff, gbase, voff) do { _Pragma("unroll") for (int _i = 0; _i < 2; ++_i) glds16_s((voff)[_i], (const void*)(gbase), ldsbase + (unsigned)((bufoff) + _i * 8192) + ldsw); } while (0)
; #define PG8_LDA(dst, b, h) do { _Pragma("unroll") for (int m = 0; m < 4; ++m) _Pragma("unroll") for (int k = 0; k < 2; ++k) dst[m][k] = *(const PG8_LAS bf16x8*)(lds + PG8_SA(b, h) + aoff + m * 2048 + k * 1024); } while (0)
; #define PG8_LDB(dst, b, h) do { _Pragma("unroll") for (int n = 0; n < 2; ++n) _Pragma("unroll") for (int k = 0; k < 2; ++k) dst[n][k] = *(const PG8_LAS bf16x8*)(lds + PG8_SB(b, h) + boff + n * 2048 + k * 1024); } while (0)
; #define PG8_LDX(pb, tp) do { _Pragma("unroll") for (int k = 0; k < 2; ++k) Ax[k] = *(const PG8_LAS bf16x8*)(lds + xoff + (pb) * 4096 + (tp) * 128 + k * 64); } while (0)
; #define PG8_MMA(ai, bj, At, Bt) do { __builtin_amdgcn_s_setprio(1); _Pragma("unroll") for (int m = 0; m < 4; ++m) _Pragma("unroll") for (int n = 0; n < 2; ++n) _Pragma("unroll") for (int k = 0; k < 2; ++k) \
;         acc[ai][bj][m][n] = __builtin_amdgcn_mfma_f32_16x16x32_bf16(Bt[n][k], At[m][k], acc[ai][bj][m][n], 0, 0, 0); __builtin_amdgcn_s_setprio(0); } while (0)
; template <class Epi, class Sched, bool HM = false>
; __device__ __forceinline__ void gemm_phase(PG8_LAS unsigned char* lds, const Gemm g, const Sched& S, const Epi& E) {
;     ...
;             PG8_WAIT_V(9); PG8_WAIT_L(0); PG8_BAR; PG8_MMA(0, 0, At, B0); PG8_MMA(0, 1, At, B1); if (hasx) PG8_MMAX(); PG8_BAR; PG8_SCHED;
;             if (!HM) PG8_LDA(At, 0, 1); PG8_STAGE(PG8_SB(0, 0), b2, voffB); PG8_STAGE(PG8_SB(0, 1), b2 + hstepB, voffB); PG8_STAGE(PG8_SA(0, 0), a2, voffA);
;             PG8_WAIT_V(9); PG8_WAIT_L(0); PG8_BAR; if (!HM) { PG8_MMA(1, 0, At, B0); PG8_MMA(1, 1, At, B1); } PG8_BAR; PG8_SCHED;
;             PG8_LDB(B0, 1, 0); PG8_LDB(B1, 1, 1); PG8_SCHED; PG8_LDA(At, 1, 0); if (hasx) PG8_LDX(pb, 1); PG8_STAGE(PG8_SA(0, 1), a2 + hstepA, voffA);
;             PG8_WAIT_V(9); PG8_WAIT_L(0); PG8_BAR; PG8_MMA(0, 0, At, B0); PG8_MMA(0, 1, At, B1); if (hasx) PG8_MMAX(); PG8_BAR; PG8_SCHED;
;             if (!HM) PG8_LDA(At, 1, 1); PG8_STAGE(PG8_SB(1, 0), b3, voffB); PG8_STAGE(PG8_SB(1, 1), b3 + hstepB, voffB); PG8_STAGE(PG8_SA(1, 0), a3, voffA);
;             PG8_WAIT_V(8); PG8_WAIT_L(0); PG8_BAR; if (!HM) { PG8_MMA(1, 0, At, B0); PG8_MMA(1, 1, At, B1); } PG8_BAR; PG8_SCHED;
.LBB0_1267:
.LBB0_1268:
	s_barrier
	ds_read_b128 v[182:185], v235 offset:49152
	ds_read_b128 v[186:189], v235 offset:50176
	ds_read_b128 v[190:193], v235 offset:51200
	ds_read_b128 v[194:197], v235 offset:52224
	ds_read_b128 v[198:201], v235 offset:53248
	ds_read_b128 v[202:205], v235 offset:54272
	ds_read_b128 v[206:209], v235 offset:55296
	ds_read_b128 v[210:213], v235 offset:56320
	s_mov_b32 s8, m0
	s_mov_b32 m0, s51
	s_nop 0
	global_load_lds_dwordx4 v226, s[6:7]
	s_mov_b32 m0, s8
	s_nop 0
	s_mov_b32 s8, m0
	s_mov_b32 m0, s52
	s_nop 0
	global_load_lds_dwordx4 v228, s[6:7]
	s_mov_b32 m0, s8
	s_add_u32 s6, s6, 0x160000
	s_addc_u32 s7, s7, 0
	s_mov_b32 s8, m0
	s_mov_b32 m0, s74
	s_nop 0
	global_load_lds_dwordx4 v226, s[6:7]
	s_mov_b32 m0, s8
	s_nop 0
	s_mov_b32 s8, m0
	s_mov_b32 m0, s75
	s_nop 0
	global_load_lds_dwordx4 v228, s[6:7]
	s_mov_b32 m0, s8
	s_mov_b32 s6, m0
	s_mov_b32 m0, s62
	s_nop 0
	global_load_lds_dwordx4 v225, s[4:5]
	s_mov_b32 m0, s6
	s_nop 0
	s_mov_b32 s6, m0
	s_mov_b32 m0, s63
	s_nop 0
	global_load_lds_dwordx4 v227, s[4:5]
	s_mov_b32 m0, s6
	s_waitcnt vmcnt(8)
	s_waitcnt lgkmcnt(0)
	s_barrier
	s_waitcnt lgkmcnt(7)
	v_mfma_f32_16x16x32_bf16 v[82:85], v[166:169], v[182:185], v[82:85]
	v_mfma_f32_16x16x32_bf16 v[78:81], v[174:177], v[182:185], v[78:81]
	s_waitcnt lgkmcnt(5)
	v_mfma_f32_16x16x32_bf16 v[74:77], v[166:169], v[190:193], v[74:77]
	v_mfma_f32_16x16x32_bf16 v[66:69], v[174:177], v[190:193], v[66:69]
	s_waitcnt lgkmcnt(3)
	v_mfma_f32_16x16x32_bf16 v[58:61], v[166:169], v[198:201], v[58:61]
	v_mfma_f32_16x16x32_bf16 v[50:53], v[174:177], v[198:201], v[50:53]
	s_waitcnt lgkmcnt(1)
	v_mfma_f32_16x16x32_bf16 v[42:45], v[166:169], v[206:209], v[42:45]
	v_mfma_f32_16x16x32_bf16 v[34:37], v[174:177], v[206:209], v[34:37]
	v_mfma_f32_16x16x32_bf16 v[82:85], v[170:173], v[186:189], v[82:85]
	v_mfma_f32_16x16x32_bf16 v[78:81], v[178:181], v[186:189], v[78:81]
	v_mfma_f32_16x16x32_bf16 v[74:77], v[170:173], v[194:197], v[74:77]
	v_mfma_f32_16x16x32_bf16 v[66:69], v[178:181], v[194:197], v[66:69]
	v_mfma_f32_16x16x32_bf16 v[58:61], v[170:173], v[202:205], v[58:61]
	v_mfma_f32_16x16x32_bf16 v[50:53], v[178:181], v[202:205], v[50:53]
	s_waitcnt lgkmcnt(0)
	v_mfma_f32_16x16x32_bf16 v[42:45], v[170:173], v[210:213], v[42:45]
	v_mfma_f32_16x16x32_bf16 v[34:37], v[178:181], v[210:213], v[34:37]
	v_mfma_f32_16x16x32_bf16 v[70:73], v[150:153], v[182:185], v[70:73]
	v_mfma_f32_16x16x32_bf16 v[62:65], v[158:161], v[182:185], v[62:65]
	v_mfma_f32_16x16x32_bf16 v[54:57], v[150:153], v[190:193], v[54:57]
	v_mfma_f32_16x16x32_bf16 v[46:49], v[158:161], v[190:193], v[46:49]
	v_mfma_f32_16x16x32_bf16 v[38:41], v[150:153], v[198:201], v[38:41]
	v_mfma_f32_16x16x32_bf16 v[30:33], v[158:161], v[198:201], v[30:33]
	v_mfma_f32_16x16x32_bf16 v[26:29], v[150:153], v[206:209], v[26:29]
	v_mfma_f32_16x16x32_bf16 v[22:25], v[158:161], v[206:209], v[22:25]
	v_mfma_f32_16x16x32_bf16 v[70:73], v[154:157], v[186:189], v[70:73]
	v_mfma_f32_16x16x32_bf16 v[62:65], v[162:165], v[186:189], v[62:65]
	v_mfma_f32_16x16x32_bf16 v[54:57], v[154:157], v[194:197], v[54:57]
	v_mfma_f32_16x16x32_bf16 v[46:49], v[162:165], v[194:197], v[46:49]
	v_mfma_f32_16x16x32_bf16 v[38:41], v[154:157], v[202:205], v[38:41]
	v_mfma_f32_16x16x32_bf16 v[30:33], v[162:165], v[202:205], v[30:33]
	v_mfma_f32_16x16x32_bf16 v[26:29], v[154:157], v[210:213], v[26:29]
	v_mfma_f32_16x16x32_bf16 v[22:25], v[162:165], v[210:213], v[22:25]
	s_barrier
	s_add_i32 s23, s23, 2
	s_addk_i32 s22, 0x1000
	s_add_u32 s88, s88, 0x100
	s_addc_u32 s89, s89, 0
	s_add_u32 s27, s27, 0x100
	s_addc_u32 s82, s82, 0
	s_cmpk_gt_u32 s23, 0x55
	s_cbranch_scc1 .LBB0_1284

; #define PG8_STAGE(bufoff, gbase, voff) do { _Pragma("unroll") for (int _i = 0; _i < 2; ++_i) glds16_s((voff)[_i], (const void*)(gbase), ldsbase + (unsigned)((bufoff) + _i * 8192) + ldsw); } while (0)
; #define PG8_STAGEX(pb, gbase) glds16_s(voffX, (const void*)(gbase), ldsbase + (unsigned)(XOFF + (pb) * 4096) + ldsx)
; #define PG8_LDA(dst, b, h) do { _Pragma("unroll") for (int m = 0; m < 4; ++m) _Pragma("unroll") for (int k = 0; k < 2; ++k) dst[m][k] = *(const PG8_LAS bf16x8*)(lds + PG8_SA(b, h) + aoff + m * 2048 + k * 1024); } while (0)
; #define PG8_LDB(dst, b, h) do { _Pragma("unroll") for (int n = 0; n < 2; ++n) _Pragma("unroll") for (int k = 0; k < 2; ++k) dst[n][k] = *(const PG8_LAS bf16x8*)(lds + PG8_SB(b, h) + boff + n * 2048 + k * 1024); } while (0)
; #define PG8_LDX(pb, tp) do { _Pragma("unroll") for (int k = 0; k < 2; ++k) Ax[k] = *(const PG8_LAS bf16x8*)(lds + xoff + (pb) * 4096 + (tp) * 128 + k * 64); } while (0)
; #define PG8_MMA(ai, bj, At, Bt) do { __builtin_amdgcn_s_setprio(1); _Pragma("unroll") for (int m = 0; m < 4; ++m) _Pragma("unroll") for (int n = 0; n < 2; ++n) _Pragma("unroll") for (int k = 0; k < 2; ++k) \
;         acc[ai][bj][m][n] = __builtin_amdgcn_mfma_f32_16x16x32_bf16(Bt[n][k], At[m][k], acc[ai][bj][m][n], 0, 0, 0); __builtin_amdgcn_s_setprio(0); } while (0)
; #define PG8_WAIT_V(n) asm volatile("s_waitcnt vmcnt(" #n ")" ::: "memory")
; #define PG8_WAIT_L(n) asm volatile("s_waitcnt lgkmcnt(" #n ")" ::: "memory")
; #define PG8_BAR __builtin_amdgcn_s_barrier()
; #define PG8_SCHED __builtin_amdgcn_sched_barrier(0)
; template <class Epi, class Sched, bool HM = false>
; __device__ __forceinline__ void gemm_phase(PG8_LAS unsigned char* lds, const Gemm g, const Sched& S, const Epi& E) {
;     ...
;             PG8_LDB(B0, 0, 0); PG8_LDB(B1, 0, 1); PG8_SCHED; PG8_LDA(At, 0, 0); if (hasx) PG8_LDX(pb, 0); PG8_STAGE(PG8_SA(1, 1), a1 + hstepA, voffA); PG8_STAGEX(pb ^ 1, a2 + xstep);
;             PG8_WAIT_V(9); PG8_WAIT_L(0); PG8_BAR; PG8_MMA(0, 0, At, B0); PG8_MMA(0, 1, At, B1); if (hasx) PG8_MMAX(); PG8_BAR; PG8_SCHED;
.LBB0_1271:
	s_add_u32 s40, s40, 0x160000
	s_addc_u32 s41, s41, 0
	s_mov_b32 s21, m0
	s_mov_b32 m0, s76
	s_nop 0
	global_load_lds_dwordx4 v225, s[40:41]
	s_mov_b32 m0, s21
	s_nop 0
	s_mov_b32 s21, m0
	s_mov_b32 m0, s77
	s_nop 0
	global_load_lds_dwordx4 v227, s[40:41]
	s_mov_b32 m0, s21
	s_add_u32 s40, s8, 0x2c0000
	s_addc_u32 s41, s9, 0
	s_xor_b32 s20, s20, 0x21400
	s_add_i32 s20, s29, s20
	s_mov_b32 s21, m0
	s_mov_b32 m0, s20
	s_nop 0
	global_load_lds_dwordx4 v229, s[40:41]
	s_mov_b32 m0, s21
	s_waitcnt vmcnt(9)
	s_waitcnt lgkmcnt(0)
	s_barrier
	s_waitcnt lgkmcnt(7)
	v_mfma_f32_16x16x32_bf16 v[146:149], v[166:169], v[206:209], v[146:149]
	v_mfma_f32_16x16x32_bf16 v[142:145], v[174:177], v[206:209], v[142:145]
	s_waitcnt lgkmcnt(5)
	v_mfma_f32_16x16x32_bf16 v[138:141], v[166:169], v[198:201], v[138:141]
	v_mfma_f32_16x16x32_bf16 v[130:133], v[174:177], v[198:201], v[130:133]
	s_waitcnt lgkmcnt(3)
	v_mfma_f32_16x16x32_bf16 v[122:125], v[166:169], v[190:193], v[122:125]
	v_mfma_f32_16x16x32_bf16 v[114:117], v[174:177], v[190:193], v[114:117]
	s_waitcnt lgkmcnt(1)
	v_mfma_f32_16x16x32_bf16 v[106:109], v[166:169], v[182:185], v[106:109]
	v_mfma_f32_16x16x32_bf16 v[98:101], v[174:177], v[182:185], v[98:101]
	v_mfma_f32_16x16x32_bf16 v[146:149], v[170:173], v[210:213], v[146:149]
	v_mfma_f32_16x16x32_bf16 v[142:145], v[178:181], v[210:213], v[142:145]
	v_mfma_f32_16x16x32_bf16 v[138:141], v[170:173], v[202:205], v[138:141]
	v_mfma_f32_16x16x32_bf16 v[130:133], v[178:181], v[202:205], v[130:133]
	v_mfma_f32_16x16x32_bf16 v[122:125], v[170:173], v[194:197], v[122:125]
	v_mfma_f32_16x16x32_bf16 v[114:117], v[178:181], v[194:197], v[114:117]
	s_waitcnt lgkmcnt(0)
	v_mfma_f32_16x16x32_bf16 v[106:109], v[170:173], v[186:189], v[106:109]
	v_mfma_f32_16x16x32_bf16 v[98:101], v[178:181], v[186:189], v[98:101]
	v_mfma_f32_16x16x32_bf16 v[134:137], v[150:153], v[206:209], v[134:137]
	v_mfma_f32_16x16x32_bf16 v[126:129], v[158:161], v[206:209], v[126:129]
	v_mfma_f32_16x16x32_bf16 v[118:121], v[150:153], v[198:201], v[118:121]
	v_mfma_f32_16x16x32_bf16 v[110:113], v[158:161], v[198:201], v[110:113]
	v_mfma_f32_16x16x32_bf16 v[102:105], v[150:153], v[190:193], v[102:105]
	v_mfma_f32_16x16x32_bf16 v[94:97], v[158:161], v[190:193], v[94:97]
	v_mfma_f32_16x16x32_bf16 v[90:93], v[150:153], v[182:185], v[90:93]
	v_mfma_f32_16x16x32_bf16 v[86:89], v[158:161], v[182:185], v[86:89]
	v_mfma_f32_16x16x32_bf16 v[134:137], v[154:157], v[210:213], v[134:137]
	v_mfma_f32_16x16x32_bf16 v[126:129], v[162:165], v[210:213], v[126:129]
	v_mfma_f32_16x16x32_bf16 v[118:121], v[154:157], v[202:205], v[118:121]
	v_mfma_f32_16x16x32_bf16 v[110:113], v[162:165], v[202:205], v[110:113]
	v_mfma_f32_16x16x32_bf16 v[102:105], v[154:157], v[194:197], v[102:105]
	v_mfma_f32_16x16x32_bf16 v[94:97], v[162:165], v[194:197], v[94:97]
	v_mfma_f32_16x16x32_bf16 v[90:93], v[154:157], v[186:189], v[90:93]
	v_mfma_f32_16x16x32_bf16 v[86:89], v[162:165], v[186:189], v[86:89]
	s_andn2_b64 s[40:41], exec, s[46:47]
	s_and_b64 vcc, exec, s[38:39]
	s_cbranch_vccnz .LBB0_1277
	s_and_b64 vcc, exec, s[40:41]
	s_cbranch_vccnz .LBB0_1274
	v_mfma_f32_16x16x32_bf16 v[18:21], v[174:177], v[6:9], v[18:21]
	v_mfma_f32_16x16x32_bf16 v[14:17], v[158:161], v[6:9], v[14:17]
	v_mfma_f32_16x16x32_bf16 v[18:21], v[178:181], v[10:13], v[18:21]
	v_mfma_f32_16x16x32_bf16 v[14:17], v[162:165], v[10:13], v[14:17]
	s_branch .LBB0_1277

; #define PG8_STAGE(bufoff, gbase, voff) do { _Pragma("unroll") for (int _i = 0; _i < 2; ++_i) glds16_s((voff)[_i], (const void*)(gbase), ldsbase + (unsigned)((bufoff) + _i * 8192) + ldsw); } while (0)
; #define PG8_LDA(dst, b, h) do { _Pragma("unroll") for (int m = 0; m < 4; ++m) _Pragma("unroll") for (int k = 0; k < 2; ++k) dst[m][k] = *(const PG8_LAS bf16x8*)(lds + PG8_SA(b, h) + aoff + m * 2048 + k * 1024); } while (0)
; #define PG8_LDB(dst, b, h) do { _Pragma("unroll") for (int n = 0; n < 2; ++n) _Pragma("unroll") for (int k = 0; k < 2; ++k) dst[n][k] = *(const PG8_LAS bf16x8*)(lds + PG8_SB(b, h) + boff + n * 2048 + k * 1024); } while (0)
; #define PG8_LDX(pb, tp) do { _Pragma("unroll") for (int k = 0; k < 2; ++k) Ax[k] = *(const PG8_LAS bf16x8*)(lds + xoff + (pb) * 4096 + (tp) * 128 + k * 64); } while (0)
; #define PG8_MMA(ai, bj, At, Bt) do { __builtin_amdgcn_s_setprio(1); _Pragma("unroll") for (int m = 0; m < 4; ++m) _Pragma("unroll") for (int n = 0; n < 2; ++n) _Pragma("unroll") for (int k = 0; k < 2; ++k) \
;         acc[ai][bj][m][n] = __builtin_amdgcn_mfma_f32_16x16x32_bf16(Bt[n][k], At[m][k], acc[ai][bj][m][n], 0, 0, 0); __builtin_amdgcn_s_setprio(0); } while (0)
; #define PG8_WAIT_V(n) asm volatile("s_waitcnt vmcnt(" #n ")" ::: "memory")
; #define PG8_WAIT_L(n) asm volatile("s_waitcnt lgkmcnt(" #n ")" ::: "memory")
; #define PG8_BAR __builtin_amdgcn_s_barrier()
; #define PG8_SCHED __builtin_amdgcn_sched_barrier(0)
; template <class Epi, class Sched, bool HM = false>
; __device__ __forceinline__ void gemm_phase(PG8_LAS unsigned char* lds, const Gemm g, const Sched& S, const Epi& E) {
;     ...
;             if (!HM) PG8_LDA(At, 0, 1); PG8_STAGE(PG8_SB(0, 0), b2, voffB); PG8_STAGE(PG8_SB(0, 1), b2 + hstepB, voffB); PG8_STAGE(PG8_SA(0, 0), a2, voffA);
;             PG8_WAIT_V(9); PG8_WAIT_L(0); PG8_BAR; if (!HM) { PG8_MMA(1, 0, At, B0); PG8_MMA(1, 1, At, B1); } PG8_BAR; PG8_SCHED;
;             PG8_LDB(B0, 1, 0); PG8_LDB(B1, 1, 1); PG8_SCHED; PG8_LDA(At, 1, 0); if (hasx) PG8_LDX(pb, 1); PG8_STAGE(PG8_SA(0, 1), a2 + hstepA, voffA);
.LBB0_1276:
.LBB0_1277:
	s_barrier
	ds_read_b128 v[182:185], v235 offset:16384
	ds_read_b128 v[186:189], v235 offset:17408
	ds_read_b128 v[190:193], v235 offset:18432
	ds_read_b128 v[194:197], v235 offset:19456
	ds_read_b128 v[198:201], v235 offset:20480
	ds_read_b128 v[202:205], v235 offset:21504
	ds_read_b128 v[206:209], v235 offset:22528
	ds_read_b128 v[210:213], v235 offset:23552
	s_mov_b32 s20, m0
	s_mov_b32 m0, s18
	s_nop 0
	global_load_lds_dwordx4 v226, s[34:35]
	s_mov_b32 m0, s20
	s_nop 0
	s_mov_b32 s20, m0
	s_mov_b32 m0, s19
	s_nop 0
	global_load_lds_dwordx4 v228, s[34:35]
	s_mov_b32 m0, s20
	s_add_u32 s20, s34, 0x160000
	s_addc_u32 s21, s35, 0
	s_mov_b32 s34, m0
	s_mov_b32 m0, s24
	s_nop 0
	global_load_lds_dwordx4 v226, s[20:21]
	s_mov_b32 m0, s34
	s_nop 0
	s_mov_b32 s34, m0
	s_mov_b32 m0, s25
	s_nop 0
	global_load_lds_dwordx4 v228, s[20:21]
	s_mov_b32 m0, s34
	s_mov_b32 s20, m0
	s_mov_b32 m0, s17
	s_nop 0
	global_load_lds_dwordx4 v225, s[8:9]
	s_mov_b32 m0, s20
	s_nop 0
	s_mov_b32 s20, m0
	s_mov_b32 m0, s28
	s_nop 0
	global_load_lds_dwordx4 v227, s[8:9]
	s_mov_b32 m0, s20
	s_waitcnt vmcnt(9)
	s_waitcnt lgkmcnt(0)
	s_barrier
	s_waitcnt lgkmcnt(7)
	v_mfma_f32_16x16x32_bf16 v[82:85], v[166:169], v[182:185], v[82:85]
	v_mfma_f32_16x16x32_bf16 v[78:81], v[174:177], v[182:185], v[78:81]
	s_waitcnt lgkmcnt(5)
	v_mfma_f32_16x16x32_bf16 v[74:77], v[166:169], v[190:193], v[74:77]
	v_mfma_f32_16x16x32_bf16 v[66:69], v[174:177], v[190:193], v[66:69]
	s_waitcnt lgkmcnt(3)
	v_mfma_f32_16x16x32_bf16 v[58:61], v[166:169], v[198:201], v[58:61]
	v_mfma_f32_16x16x32_bf16 v[50:53], v[174:177], v[198:201], v[50:53]
	s_waitcnt lgkmcnt(1)
	v_mfma_f32_16x16x32_bf16 v[42:45], v[166:169], v[206:209], v[42:45]
	v_mfma_f32_16x16x32_bf16 v[34:37], v[174:177], v[206:209], v[34:37]
	v_mfma_f32_16x16x32_bf16 v[82:85], v[170:173], v[186:189], v[82:85]
	v_mfma_f32_16x16x32_bf16 v[78:81], v[178:181], v[186:189], v[78:81]
	v_mfma_f32_16x16x32_bf16 v[74:77], v[170:173], v[194:197], v[74:77]
	v_mfma_f32_16x16x32_bf16 v[66:69], v[178:181], v[194:197], v[66:69]
	v_mfma_f32_16x16x32_bf16 v[58:61], v[170:173], v[202:205], v[58:61]
	v_mfma_f32_16x16x32_bf16 v[50:53], v[178:181], v[202:205], v[50:53]
	s_waitcnt lgkmcnt(0)
	v_mfma_f32_16x16x32_bf16 v[42:45], v[170:173], v[210:213], v[42:45]
	v_mfma_f32_16x16x32_bf16 v[34:37], v[178:181], v[210:213], v[34:37]
	v_mfma_f32_16x16x32_bf16 v[70:73], v[150:153], v[182:185], v[70:73]
	v_mfma_f32_16x16x32_bf16 v[62:65], v[158:161], v[182:185], v[62:65]
	v_mfma_f32_16x16x32_bf16 v[54:57], v[150:153], v[190:193], v[54:57]
	v_mfma_f32_16x16x32_bf16 v[46:49], v[158:161], v[190:193], v[46:49]
	v_mfma_f32_16x16x32_bf16 v[38:41], v[150:153], v[198:201], v[38:41]
	v_mfma_f32_16x16x32_bf16 v[30:33], v[158:161], v[198:201], v[30:33]
	v_mfma_f32_16x16x32_bf16 v[26:29], v[150:153], v[206:209], v[26:29]
	v_mfma_f32_16x16x32_bf16 v[22:25], v[158:161], v[206:209], v[22:25]
	v_mfma_f32_16x16x32_bf16 v[70:73], v[154:157], v[186:189], v[70:73]
	v_mfma_f32_16x16x32_bf16 v[62:65], v[162:165], v[186:189], v[62:65]
	v_mfma_f32_16x16x32_bf16 v[54:57], v[154:157], v[194:197], v[54:57]
	v_mfma_f32_16x16x32_bf16 v[46:49], v[162:165], v[194:197], v[46:49]
	v_mfma_f32_16x16x32_bf16 v[38:41], v[154:157], v[202:205], v[38:41]
	v_mfma_f32_16x16x32_bf16 v[30:33], v[162:165], v[202:205], v[30:33]
	v_mfma_f32_16x16x32_bf16 v[26:29], v[154:157], v[210:213], v[26:29]
	v_mfma_f32_16x16x32_bf16 v[22:25], v[162:165], v[210:213], v[22:25]
	s_barrier
	v_add_u32_e32 v4, 0x18000, v234
	ds_read_b128 v[166:169], v4
	ds_read_b128 v[170:173], v4 offset:1024
	ds_read_b128 v[174:177], v4 offset:2048
	ds_read_b128 v[178:181], v4 offset:3072
	v_add_u32_e32 v4, 0x1c000, v234
	ds_read_b128 v[150:153], v4
	ds_read_b128 v[154:157], v4 offset:1024
	ds_read_b128 v[158:161], v4 offset:2048
	ds_read_b128 v[162:165], v4 offset:3072
	ds_read_b128 v[206:209], v235 offset:32768
	ds_read_b128 v[210:213], v235 offset:33792
	ds_read_b128 v[198:201], v235 offset:34816
	ds_read_b128 v[202:205], v235 offset:35840
	ds_read_b128 v[190:193], v235 offset:36864
	ds_read_b128 v[194:197], v235 offset:37888
	ds_read_b128 v[182:185], v235 offset:38912
	ds_read_b128 v[186:189], v235 offset:39936
	s_and_b64 vcc, exec, s[38:39]
	s_cbranch_vccnz .LBB0_1279
	v_xor_b32_e32 v6, 0x80, v2
	ds_read_b128 v[6:9], v6
	v_xor_b32_e32 v10, 0xc0, v2
	ds_read_b128 v[10:13], v10
; #define PG8_STAGE(bufoff, gbase, voff) do { _Pragma("unroll") for (int _i = 0; _i < 2; ++_i) glds16_s((voff)[_i], (const void*)(gbase), ldsbase + (unsigned)((bufoff) + _i * 8192) + ldsw); } while (0)
; #define PG8_LDA(dst, b, h) do { _Pragma("unroll") for (int m = 0; m < 4; ++m) _Pragma("unroll") for (int k = 0; k < 2; ++k) dst[m][k] = *(const PG8_LAS bf16x8*)(lds + PG8_SA(b, h) + aoff + m * 2048 + k * 1024); } while (0)
; #define PG8_LDB(dst, b, h) do { _Pragma("unroll") for (int n = 0; n < 2; ++n) _Pragma("unroll") for (int k = 0; k < 2; ++k) dst[n][k] = *(const PG8_LAS bf16x8*)(lds + PG8_SB(b, h) + boff + n * 2048 + k * 1024); } while (0)
; #define PG8_LDX(pb, tp) do { _Pragma("unroll") for (int k = 0; k < 2; ++k) Ax[k] = *(const PG8_LAS bf16x8*)(lds + xoff + (pb) * 4096 + (tp) * 128 + k * 64); } while (0)
; #define PG8_MMA(ai, bj, At, Bt) do { __builtin_amdgcn_s_setprio(1); _Pragma("unroll") for (int m = 0; m < 4; ++m) _Pragma("unroll") for (int n = 0; n < 2; ++n) _Pragma("unroll") for (int k = 0; k < 2; ++k) \
;         acc[ai][bj][m][n] = __builtin_amdgcn_mfma_f32_16x16x32_bf16(Bt[n][k], At[m][k], acc[ai][bj][m][n], 0, 0, 0); __builtin_amdgcn_s_setprio(0); } while (0)
; #define PG8_WAIT_V(n) asm volatile("s_waitcnt vmcnt(" #n ")" ::: "memory")
; #define PG8_WAIT_L(n) asm volatile("s_waitcnt lgkmcnt(" #n ")" ::: "memory")
; #define PG8_BAR __builtin_amdgcn_s_barrier()
; #define PG8_SCHED __builtin_amdgcn_sched_barrier(0)
; template <class Epi, class Sched, bool HM = false>
; __device__ __forceinline__ void gemm_phase(PG8_LAS unsigned char* lds, const Gemm g, const Sched& S, const Epi& E) {
;     ...
;             PG8_LDB(B0, 1, 0); PG8_LDB(B1, 1, 1); PG8_SCHED; PG8_LDA(At, 1, 0); if (hasx) PG8_LDX(pb, 1); PG8_STAGE(PG8_SA(0, 1), a2 + hstepA, voffA);
;             PG8_WAIT_V(9); PG8_WAIT_L(0); PG8_BAR; PG8_MMA(0, 0, At, B0); PG8_MMA(0, 1, At, B1); if (hasx) PG8_MMAX(); PG8_BAR; PG8_SCHED;
.LBB0_1279:
	s_add_u32 s8, s8, 0x160000
	s_addc_u32 s9, s9, 0
	s_mov_b32 s20, m0
	s_mov_b32 m0, s30
	s_nop 0
	global_load_lds_dwordx4 v225, s[8:9]
	s_mov_b32 m0, s20
	s_nop 0
	s_mov_b32 s20, m0
	s_mov_b32 m0, s31
	s_nop 0
	global_load_lds_dwordx4 v227, s[8:9]
	s_mov_b32 m0, s20
	s_waitcnt vmcnt(9)
	s_waitcnt lgkmcnt(0)
	s_barrier
	s_waitcnt lgkmcnt(7)
	v_mfma_f32_16x16x32_bf16 v[146:149], v[166:169], v[206:209], v[146:149]
	v_mfma_f32_16x16x32_bf16 v[142:145], v[174:177], v[206:209], v[142:145]
	s_waitcnt lgkmcnt(5)
	v_mfma_f32_16x16x32_bf16 v[138:141], v[166:169], v[198:201], v[138:141]
	v_mfma_f32_16x16x32_bf16 v[130:133], v[174:177], v[198:201], v[130:133]
	s_waitcnt lgkmcnt(3)
	v_mfma_f32_16x16x32_bf16 v[122:125], v[166:169], v[190:193], v[122:125]
	v_mfma_f32_16x16x32_bf16 v[114:117], v[174:177], v[190:193], v[114:117]
	s_waitcnt lgkmcnt(1)
	v_mfma_f32_16x16x32_bf16 v[106:109], v[166:169], v[182:185], v[106:109]
	v_mfma_f32_16x16x32_bf16 v[98:101], v[174:177], v[182:185], v[98:101]
	v_mfma_f32_16x16x32_bf16 v[146:149], v[170:173], v[210:213], v[146:149]
	v_mfma_f32_16x16x32_bf16 v[142:145], v[178:181], v[210:213], v[142:145]
	v_mfma_f32_16x16x32_bf16 v[138:141], v[170:173], v[202:205], v[138:141]
	v_mfma_f32_16x16x32_bf16 v[130:133], v[178:181], v[202:205], v[130:133]
	v_mfma_f32_16x16x32_bf16 v[122:125], v[170:173], v[194:197], v[122:125]
	v_mfma_f32_16x16x32_bf16 v[114:117], v[178:181], v[194:197], v[114:117]
	s_waitcnt lgkmcnt(0)
	v_mfma_f32_16x16x32_bf16 v[106:109], v[170:173], v[186:189], v[106:109]
	v_mfma_f32_16x16x32_bf16 v[98:101], v[178:181], v[186:189], v[98:101]
	v_mfma_f32_16x16x32_bf16 v[134:137], v[150:153], v[206:209], v[134:137]
	v_mfma_f32_16x16x32_bf16 v[126:129], v[158:161], v[206:209], v[126:129]
	v_mfma_f32_16x16x32_bf16 v[118:121], v[150:153], v[198:201], v[118:121]
	v_mfma_f32_16x16x32_bf16 v[110:113], v[158:161], v[198:201], v[110:113]
	v_mfma_f32_16x16x32_bf16 v[102:105], v[150:153], v[190:193], v[102:105]
	v_mfma_f32_16x16x32_bf16 v[94:97], v[158:161], v[190:193], v[94:97]
	v_mfma_f32_16x16x32_bf16 v[90:93], v[150:153], v[182:185], v[90:93]
	v_mfma_f32_16x16x32_bf16 v[86:89], v[158:161], v[182:185], v[86:89]
	v_mfma_f32_16x16x32_bf16 v[134:137], v[154:157], v[210:213], v[134:137]
	v_mfma_f32_16x16x32_bf16 v[126:129], v[162:165], v[210:213], v[126:129]
	v_mfma_f32_16x16x32_bf16 v[118:121], v[154:157], v[202:205], v[118:121]
	v_mfma_f32_16x16x32_bf16 v[110:113], v[162:165], v[202:205], v[110:113]
	v_mfma_f32_16x16x32_bf16 v[102:105], v[154:157], v[194:197], v[102:105]
	v_mfma_f32_16x16x32_bf16 v[94:97], v[162:165], v[194:197], v[94:97]
	v_mfma_f32_16x16x32_bf16 v[90:93], v[154:157], v[186:189], v[90:93]
	v_mfma_f32_16x16x32_bf16 v[86:89], v[162:165], v[186:189], v[86:89]
	s_and_b64 vcc, exec, s[38:39]
	s_cbranch_vccnz .LBB0_1268
	s_and_b64 vcc, exec, s[40:41]
	s_cbranch_vccnz .LBB0_1282
	v_mfma_f32_16x16x32_bf16 v[18:21], v[174:177], v[6:9], v[18:21]
	v_mfma_f32_16x16x32_bf16 v[14:17], v[158:161], v[6:9], v[14:17]
	v_mfma_f32_16x16x32_bf16 v[18:21], v[178:181], v[10:13], v[18:21]
	v_mfma_f32_16x16x32_bf16 v[14:17], v[162:165], v[10:13], v[14:17]
	s_branch .LBB0_1267
